# cmp phase top-16 rank: fully unrolled competitor scan with static ge/gt selection (2 VALU per pair instead of 4 VALU + 2 SALU)
# speedup vs baseline: 1.0196x; 1.0128x over previous
; __device__ __forceinline__ void cmp_phase(LAS unsigned char* lds, const bf16_t* __restrict__ P, const bf16_t* __restrict__ Kc, const bf16_t* __restrict__ Vc,
;                                           bf16_t* __restrict__ ocmp, unsigned long long* __restrict__ mask, int G, const int wave0) {
;     ...
;         {
;             float s[32];
; #pragma unroll
;             for (int i = 0; i < 32; ++i) s[i] = sc[2 * i + hi];
;             int rank[32];
; #pragma unroll
;             for (int i = 0; i < 32; ++i) rank[i] = 0;
;             const int kmax = ((tw0 + 31) >> 6) + 1;
; #pragma nounroll
;             for (int k = 0; k < kmax; ++k) {
;                 const float sk = sc[k];
;                 const int kk = k - hi;
; #pragma unroll
;                 for (int i = 0; i < 32; ++i) rank[i] += ((sk > s[i]) || ((sk == s[i]) && (kk < 2 * i))) ? 1 : 0;
;             }
.LBB0_782:
	v_lshl_add_u32 v30, v80, 2, v65
	ds_read2_b32 v[0:1], v30 offset1:2
	ds_read2_b32 v[2:3], v30 offset0:4 offset1:6
	ds_read2_b32 v[4:5], v30 offset0:8 offset1:10
	ds_read2_b32 v[6:7], v30 offset0:12 offset1:14
	ds_read2_b32 v[8:9], v30 offset0:16 offset1:18
	ds_read2_b32 v[10:11], v30 offset0:20 offset1:22
	ds_read2_b32 v[12:13], v30 offset0:24 offset1:26
	ds_read2_b32 v[14:15], v30 offset0:28 offset1:30
	ds_read2_b32 v[16:17], v30 offset0:32 offset1:34
	ds_read2_b32 v[18:19], v30 offset0:36 offset1:38
	ds_read2_b32 v[20:21], v30 offset0:40 offset1:42
	ds_read2_b32 v[22:23], v30 offset0:44 offset1:46
	ds_read2_b32 v[24:25], v30 offset0:48 offset1:50
	ds_read2_b32 v[26:27], v30 offset0:52 offset1:54
	ds_read2_b32 v[28:29], v30 offset0:56 offset1:58
	ds_read2_b32 v[30:31], v30 offset0:60 offset1:62
	v_readlane_b32 s4, v255, 9
	v_readlane_b32 s5, v255, 11
	s_or_b32 s4, s4, s5
	v_readlane_b32 s5, v253, 13
	s_or_b32 s15, s4, s5
	s_cmp_gt_u32 s15, 63
	s_cbranch_scc0 .LBB0_786
	v_readlane_b32 s4, v255, 12
	s_lshr_b32 s4, s4, 6
	s_add_i32 s14, s4, 1
	v_readlane_b32 s4, v253, 7
	v_readlane_b32 s66, v254, 34
	v_readlane_b32 s67, v254, 35
	v_readlane_b32 s88, v254, 39
	v_add_u32_e32 v104, s4, v99
	v_readlane_b32 s72, v254, 22
	v_cmp_ne_u32_e64 s[6:7], 0, v80
	ds_read2_b32 v[100:101], v104 offset1:1
	v_mov_b32_e32 v97, 0
	v_mov_b32_e32 v96, 0
	v_mov_b32_e32 v95, 0
	v_mov_b32_e32 v94, 0
	v_mov_b32_e32 v93, 0
	v_mov_b32_e32 v92, 0
	v_mov_b32_e32 v91, 0
	v_mov_b32_e32 v90, 0
	v_mov_b32_e32 v89, 0
	v_mov_b32_e32 v88, 0
	v_mov_b32_e32 v87, 0
	v_mov_b32_e32 v86, 0
	v_mov_b32_e32 v85, 0
	v_mov_b32_e32 v84, 0
	v_mov_b32_e32 v83, 0
	v_mov_b32_e32 v81, 0
	v_mov_b32_e32 v79, 0
	v_mov_b32_e32 v78, 0
	v_mov_b32_e32 v77, 0
	v_mov_b32_e32 v76, 0
	v_mov_b32_e32 v75, 0
	v_mov_b32_e32 v74, 0
	v_mov_b32_e32 v73, 0
	v_mov_b32_e32 v72, 0
	v_mov_b32_e32 v71, 0
	v_mov_b32_e32 v70, 0
	v_mov_b32_e32 v69, 0
	v_mov_b32_e32 v68, 0
	v_mov_b32_e32 v67, 0
	v_mov_b32_e32 v66, 0
	v_mov_b32_e32 v65, 0
	v_mov_b32_e32 v64, 0
	s_waitcnt lgkmcnt(0)
	s_cmp_le_u32 s14, 0
	s_cbranch_scc1 .Lrk_done
	ds_read2_b32 v[102:103], v104 offset0:2 offset1:3
	s_waitcnt lgkmcnt(1)
	v_cmp_ge_f32_e64 s[8:9], v100, v0
	v_cmp_ge_f32_e64 s[10:11], v100, v1
	v_cmp_ge_f32_e64 s[12:13], v100, v2
	s_and_b64 s[8:9], s[8:9], s[6:7]
	v_addc_co_u32_e64 v97, vcc, 0, v97, s[8:9]
	v_cmp_ge_f32_e64 s[8:9], v100, v3
	v_addc_co_u32_e64 v96, vcc, 0, v96, s[10:11]
	v_cmp_ge_f32_e64 s[10:11], v100, v4
	v_addc_co_u32_e64 v95, vcc, 0, v95, s[12:13]
	v_cmp_ge_f32_e64 s[12:13], v100, v5
	v_addc_co_u32_e64 v94, vcc, 0, v94, s[8:9]
	v_cmp_ge_f32_e64 s[8:9], v100, v6
	v_addc_co_u32_e64 v93, vcc, 0, v93, s[10:11]
	v_cmp_ge_f32_e64 s[10:11], v100, v7
	v_addc_co_u32_e64 v92, vcc, 0, v92, s[12:13]
	v_cmp_ge_f32_e64 s[12:13], v100, v8
	v_addc_co_u32_e64 v91, vcc, 0, v91, s[8:9]
	v_cmp_ge_f32_e64 s[8:9], v100, v9
	v_addc_co_u32_e64 v90, vcc, 0, v90, s[10:11]
	v_cmp_ge_f32_e64 s[10:11], v100, v10
	v_addc_co_u32_e64 v89, vcc, 0, v89, s[12:13]
	v_cmp_ge_f32_e64 s[12:13], v100, v11
	v_addc_co_u32_e64 v88, vcc, 0, v88, s[8:9]
	v_cmp_ge_f32_e64 s[8:9], v100, v12
	v_addc_co_u32_e64 v87, vcc, 0, v87, s[10:11]
	v_cmp_ge_f32_e64 s[10:11], v100, v13
	v_addc_co_u32_e64 v86, vcc, 0, v86, s[12:13]
	v_cmp_ge_f32_e64 s[12:13], v100, v14
	v_addc_co_u32_e64 v85, vcc, 0, v85, s[8:9]
	v_cmp_ge_f32_e64 s[8:9], v100, v15
	v_addc_co_u32_e64 v84, vcc, 0, v84, s[10:11]
	v_cmp_ge_f32_e64 s[10:11], v100, v16
	v_addc_co_u32_e64 v83, vcc, 0, v83, s[12:13]
	v_cmp_ge_f32_e64 s[12:13], v100, v17
	v_addc_co_u32_e64 v81, vcc, 0, v81, s[8:9]
	v_cmp_ge_f32_e64 s[8:9], v100, v18
	v_addc_co_u32_e64 v79, vcc, 0, v79, s[10:11]
	v_cmp_ge_f32_e64 s[10:11], v100, v19
	v_addc_co_u32_e64 v78, vcc, 0, v78, s[12:13]
	v_cmp_ge_f32_e64 s[12:13], v100, v20
	v_addc_co_u32_e64 v77, vcc, 0, v77, s[8:9]
	v_cmp_ge_f32_e64 s[8:9], v100, v21
	v_addc_co_u32_e64 v76, vcc, 0, v76, s[10:11]
	v_cmp_ge_f32_e64 s[10:11], v100, v22
	v_addc_co_u32_e64 v75, vcc, 0, v75, s[12:13]
	v_cmp_ge_f32_e64 s[12:13], v100, v23
	v_addc_co_u32_e64 v74, vcc, 0, v74, s[8:9]
	v_cmp_ge_f32_e64 s[8:9], v100, v24
	v_addc_co_u32_e64 v73, vcc, 0, v73, s[10:11]
	v_cmp_ge_f32_e64 s[10:11], v100, v25
	v_addc_co_u32_e64 v72, vcc, 0, v72, s[12:13]
	v_cmp_ge_f32_e64 s[12:13], v100, v26
	v_addc_co_u32_e64 v71, vcc, 0, v71, s[8:9]
	v_cmp_ge_f32_e64 s[8:9], v100, v27
	v_addc_co_u32_e64 v70, vcc, 0, v70, s[10:11]
	v_cmp_ge_f32_e64 s[10:11], v100, v28
	v_addc_co_u32_e64 v69, vcc, 0, v69, s[12:13]
	v_cmp_ge_f32_e64 s[12:13], v100, v29
	v_addc_co_u32_e64 v68, vcc, 0, v68, s[8:9]
	v_cmp_ge_f32_e64 s[8:9], v100, v30
	v_addc_co_u32_e64 v67, vcc, 0, v67, s[10:11]
	v_cmp_ge_f32_e64 s[10:11], v100, v31
	v_addc_co_u32_e64 v66, vcc, 0, v66, s[12:13]
	s_nop 0
	v_addc_co_u32_e64 v65, vcc, 0, v65, s[8:9]
	v_addc_co_u32_e64 v64, vcc, 0, v64, s[10:11]
	s_cmp_le_u32 s14, 1
	s_cbranch_scc1 .Lrk_done
; __device__ __forceinline__ void cmp_phase(LAS unsigned char* lds, const bf16_t* __restrict__ P, const bf16_t* __restrict__ Kc, const bf16_t* __restrict__ Vc,
;                                           bf16_t* __restrict__ ocmp, unsigned long long* __restrict__ mask, int G, const int wave0) {
;     ...
; #pragma nounroll
;             for (int k = 0; k < kmax; ++k) {
;                 const float sk = sc[k];
;                 const int kk = k - hi;
; #pragma unroll
;                 for (int i = 0; i < 32; ++i) rank[i] += ((sk > s[i]) || ((sk == s[i]) && (kk < 2 * i))) ? 1 : 0;
;             }
	v_cmp_gt_f32_e64 s[8:9], v101, v0
	v_cmp_ge_f32_e64 s[10:11], v101, v1
	v_cmp_ge_f32_e64 s[12:13], v101, v2
	v_addc_co_u32_e64 v97, vcc, 0, v97, s[8:9]
	v_cmp_ge_f32_e64 s[8:9], v101, v3
	v_addc_co_u32_e64 v96, vcc, 0, v96, s[10:11]
	v_cmp_ge_f32_e64 s[10:11], v101, v4
	v_addc_co_u32_e64 v95, vcc, 0, v95, s[12:13]
	v_cmp_ge_f32_e64 s[12:13], v101, v5
	v_addc_co_u32_e64 v94, vcc, 0, v94, s[8:9]
	v_cmp_ge_f32_e64 s[8:9], v101, v6
	v_addc_co_u32_e64 v93, vcc, 0, v93, s[10:11]
	v_cmp_ge_f32_e64 s[10:11], v101, v7
	v_addc_co_u32_e64 v92, vcc, 0, v92, s[12:13]
	v_cmp_ge_f32_e64 s[12:13], v101, v8
	v_addc_co_u32_e64 v91, vcc, 0, v91, s[8:9]
	v_cmp_ge_f32_e64 s[8:9], v101, v9
	v_addc_co_u32_e64 v90, vcc, 0, v90, s[10:11]
	v_cmp_ge_f32_e64 s[10:11], v101, v10
	v_addc_co_u32_e64 v89, vcc, 0, v89, s[12:13]
	v_cmp_ge_f32_e64 s[12:13], v101, v11
	v_addc_co_u32_e64 v88, vcc, 0, v88, s[8:9]
	v_cmp_ge_f32_e64 s[8:9], v101, v12
	v_addc_co_u32_e64 v87, vcc, 0, v87, s[10:11]
	v_cmp_ge_f32_e64 s[10:11], v101, v13
	v_addc_co_u32_e64 v86, vcc, 0, v86, s[12:13]
	v_cmp_ge_f32_e64 s[12:13], v101, v14
	v_addc_co_u32_e64 v85, vcc, 0, v85, s[8:9]
	v_cmp_ge_f32_e64 s[8:9], v101, v15
	v_addc_co_u32_e64 v84, vcc, 0, v84, s[10:11]
	v_cmp_ge_f32_e64 s[10:11], v101, v16
	v_addc_co_u32_e64 v83, vcc, 0, v83, s[12:13]
	v_cmp_ge_f32_e64 s[12:13], v101, v17
	v_addc_co_u32_e64 v81, vcc, 0, v81, s[8:9]
	v_cmp_ge_f32_e64 s[8:9], v101, v18
	v_addc_co_u32_e64 v79, vcc, 0, v79, s[10:11]
	v_cmp_ge_f32_e64 s[10:11], v101, v19
	v_addc_co_u32_e64 v78, vcc, 0, v78, s[12:13]
	v_cmp_ge_f32_e64 s[12:13], v101, v20
	v_addc_co_u32_e64 v77, vcc, 0, v77, s[8:9]
	v_cmp_ge_f32_e64 s[8:9], v101, v21
	v_addc_co_u32_e64 v76, vcc, 0, v76, s[10:11]
	v_cmp_ge_f32_e64 s[10:11], v101, v22
	v_addc_co_u32_e64 v75, vcc, 0, v75, s[12:13]
	v_cmp_ge_f32_e64 s[12:13], v101, v23
	v_addc_co_u32_e64 v74, vcc, 0, v74, s[8:9]
	v_cmp_ge_f32_e64 s[8:9], v101, v24
	v_addc_co_u32_e64 v73, vcc, 0, v73, s[10:11]
	v_cmp_ge_f32_e64 s[10:11], v101, v25
	v_addc_co_u32_e64 v72, vcc, 0, v72, s[12:13]
	v_cmp_ge_f32_e64 s[12:13], v101, v26
	v_addc_co_u32_e64 v71, vcc, 0, v71, s[8:9]
	v_cmp_ge_f32_e64 s[8:9], v101, v27
	v_addc_co_u32_e64 v70, vcc, 0, v70, s[10:11]
	v_cmp_ge_f32_e64 s[10:11], v101, v28
	v_addc_co_u32_e64 v69, vcc, 0, v69, s[12:13]
	v_cmp_ge_f32_e64 s[12:13], v101, v29
	v_addc_co_u32_e64 v68, vcc, 0, v68, s[8:9]
	v_cmp_ge_f32_e64 s[8:9], v101, v30
	v_addc_co_u32_e64 v67, vcc, 0, v67, s[10:11]
	v_cmp_ge_f32_e64 s[10:11], v101, v31
	v_addc_co_u32_e64 v66, vcc, 0, v66, s[12:13]
	s_nop 0
	v_addc_co_u32_e64 v65, vcc, 0, v65, s[8:9]
	v_addc_co_u32_e64 v64, vcc, 0, v64, s[10:11]
	s_cmp_le_u32 s14, 2
	s_cbranch_scc1 .Lrk_done
	ds_read2_b32 v[100:101], v104 offset0:4 offset1:5
	s_waitcnt lgkmcnt(1)
	v_cmp_gt_f32_e64 s[8:9], v102, v0
	v_cmp_ge_f32_e64 s[10:11], v102, v1
	v_cmp_ge_f32_e64 s[12:13], v102, v2
	v_addc_co_u32_e64 v97, vcc, 0, v97, s[8:9]
	v_cmp_ge_f32_e64 s[8:9], v102, v3
	s_and_b64 s[10:11], s[10:11], s[6:7]
	v_addc_co_u32_e64 v96, vcc, 0, v96, s[10:11]
	v_cmp_ge_f32_e64 s[10:11], v102, v4
	v_addc_co_u32_e64 v95, vcc, 0, v95, s[12:13]
	v_cmp_ge_f32_e64 s[12:13], v102, v5
	v_addc_co_u32_e64 v94, vcc, 0, v94, s[8:9]
	v_cmp_ge_f32_e64 s[8:9], v102, v6
	v_addc_co_u32_e64 v93, vcc, 0, v93, s[10:11]
	v_cmp_ge_f32_e64 s[10:11], v102, v7
	v_addc_co_u32_e64 v92, vcc, 0, v92, s[12:13]
	v_cmp_ge_f32_e64 s[12:13], v102, v8
	v_addc_co_u32_e64 v91, vcc, 0, v91, s[8:9]
	v_cmp_ge_f32_e64 s[8:9], v102, v9
	v_addc_co_u32_e64 v90, vcc, 0, v90, s[10:11]
	v_cmp_ge_f32_e64 s[10:11], v102, v10
	v_addc_co_u32_e64 v89, vcc, 0, v89, s[12:13]
	v_cmp_ge_f32_e64 s[12:13], v102, v11
	v_addc_co_u32_e64 v88, vcc, 0, v88, s[8:9]
	v_cmp_ge_f32_e64 s[8:9], v102, v12
	v_addc_co_u32_e64 v87, vcc, 0, v87, s[10:11]
	v_cmp_ge_f32_e64 s[10:11], v102, v13
	v_addc_co_u32_e64 v86, vcc, 0, v86, s[12:13]
	v_cmp_ge_f32_e64 s[12:13], v102, v14
	v_addc_co_u32_e64 v85, vcc, 0, v85, s[8:9]
	v_cmp_ge_f32_e64 s[8:9], v102, v15
	v_addc_co_u32_e64 v84, vcc, 0, v84, s[10:11]
	v_cmp_ge_f32_e64 s[10:11], v102, v16
	v_addc_co_u32_e64 v83, vcc, 0, v83, s[12:13]
	v_cmp_ge_f32_e64 s[12:13], v102, v17
	v_addc_co_u32_e64 v81, vcc, 0, v81, s[8:9]
	v_cmp_ge_f32_e64 s[8:9], v102, v18
	v_addc_co_u32_e64 v79, vcc, 0, v79, s[10:11]
	v_cmp_ge_f32_e64 s[10:11], v102, v19
	v_addc_co_u32_e64 v78, vcc, 0, v78, s[12:13]
	v_cmp_ge_f32_e64 s[12:13], v102, v20
	v_addc_co_u32_e64 v77, vcc, 0, v77, s[8:9]
	v_cmp_ge_f32_e64 s[8:9], v102, v21
	v_addc_co_u32_e64 v76, vcc, 0, v76, s[10:11]
	v_cmp_ge_f32_e64 s[10:11], v102, v22
	v_addc_co_u32_e64 v75, vcc, 0, v75, s[12:13]
	v_cmp_ge_f32_e64 s[12:13], v102, v23
	v_addc_co_u32_e64 v74, vcc, 0, v74, s[8:9]
	v_cmp_ge_f32_e64 s[8:9], v102, v24
	v_addc_co_u32_e64 v73, vcc, 0, v73, s[10:11]
	v_cmp_ge_f32_e64 s[10:11], v102, v25
	v_addc_co_u32_e64 v72, vcc, 0, v72, s[12:13]
	v_cmp_ge_f32_e64 s[12:13], v102, v26
	v_addc_co_u32_e64 v71, vcc, 0, v71, s[8:9]
	v_cmp_ge_f32_e64 s[8:9], v102, v27
	v_addc_co_u32_e64 v70, vcc, 0, v70, s[10:11]
	v_cmp_ge_f32_e64 s[10:11], v102, v28
	v_addc_co_u32_e64 v69, vcc, 0, v69, s[12:13]
	v_cmp_ge_f32_e64 s[12:13], v102, v29
	v_addc_co_u32_e64 v68, vcc, 0, v68, s[8:9]
	v_cmp_ge_f32_e64 s[8:9], v102, v30
	v_addc_co_u32_e64 v67, vcc, 0, v67, s[10:11]
	v_cmp_ge_f32_e64 s[10:11], v102, v31
	v_addc_co_u32_e64 v66, vcc, 0, v66, s[12:13]
	s_nop 0
	v_addc_co_u32_e64 v65, vcc, 0, v65, s[8:9]
	v_addc_co_u32_e64 v64, vcc, 0, v64, s[10:11]
	s_cmp_le_u32 s14, 3
	s_cbranch_scc1 .Lrk_done
; __device__ __forceinline__ void cmp_phase(LAS unsigned char* lds, const bf16_t* __restrict__ P, const bf16_t* __restrict__ Kc, const bf16_t* __restrict__ Vc,
;                                           bf16_t* __restrict__ ocmp, unsigned long long* __restrict__ mask, int G, const int wave0) {
;     ...
; #pragma nounroll
;             for (int k = 0; k < kmax; ++k) {
;                 const float sk = sc[k];
;                 const int kk = k - hi;
; #pragma unroll
;                 for (int i = 0; i < 32; ++i) rank[i] += ((sk > s[i]) || ((sk == s[i]) && (kk < 2 * i))) ? 1 : 0;
;             }
	v_cmp_gt_f32_e64 s[8:9], v103, v0
	v_cmp_gt_f32_e64 s[10:11], v103, v1
	v_cmp_ge_f32_e64 s[12:13], v103, v2
	v_addc_co_u32_e64 v97, vcc, 0, v97, s[8:9]
	v_cmp_ge_f32_e64 s[8:9], v103, v3
	v_addc_co_u32_e64 v96, vcc, 0, v96, s[10:11]
	v_cmp_ge_f32_e64 s[10:11], v103, v4
	v_addc_co_u32_e64 v95, vcc, 0, v95, s[12:13]
	v_cmp_ge_f32_e64 s[12:13], v103, v5
	v_addc_co_u32_e64 v94, vcc, 0, v94, s[8:9]
	v_cmp_ge_f32_e64 s[8:9], v103, v6
	v_addc_co_u32_e64 v93, vcc, 0, v93, s[10:11]
	v_cmp_ge_f32_e64 s[10:11], v103, v7
	v_addc_co_u32_e64 v92, vcc, 0, v92, s[12:13]
	v_cmp_ge_f32_e64 s[12:13], v103, v8
	v_addc_co_u32_e64 v91, vcc, 0, v91, s[8:9]
	v_cmp_ge_f32_e64 s[8:9], v103, v9
	v_addc_co_u32_e64 v90, vcc, 0, v90, s[10:11]
	v_cmp_ge_f32_e64 s[10:11], v103, v10
	v_addc_co_u32_e64 v89, vcc, 0, v89, s[12:13]
	v_cmp_ge_f32_e64 s[12:13], v103, v11
	v_addc_co_u32_e64 v88, vcc, 0, v88, s[8:9]
	v_cmp_ge_f32_e64 s[8:9], v103, v12
	v_addc_co_u32_e64 v87, vcc, 0, v87, s[10:11]
	v_cmp_ge_f32_e64 s[10:11], v103, v13
	v_addc_co_u32_e64 v86, vcc, 0, v86, s[12:13]
	v_cmp_ge_f32_e64 s[12:13], v103, v14
	v_addc_co_u32_e64 v85, vcc, 0, v85, s[8:9]
	v_cmp_ge_f32_e64 s[8:9], v103, v15
	v_addc_co_u32_e64 v84, vcc, 0, v84, s[10:11]
	v_cmp_ge_f32_e64 s[10:11], v103, v16
	v_addc_co_u32_e64 v83, vcc, 0, v83, s[12:13]
	v_cmp_ge_f32_e64 s[12:13], v103, v17
	v_addc_co_u32_e64 v81, vcc, 0, v81, s[8:9]
	v_cmp_ge_f32_e64 s[8:9], v103, v18
	v_addc_co_u32_e64 v79, vcc, 0, v79, s[10:11]
	v_cmp_ge_f32_e64 s[10:11], v103, v19
	v_addc_co_u32_e64 v78, vcc, 0, v78, s[12:13]
	v_cmp_ge_f32_e64 s[12:13], v103, v20
	v_addc_co_u32_e64 v77, vcc, 0, v77, s[8:9]
	v_cmp_ge_f32_e64 s[8:9], v103, v21
	v_addc_co_u32_e64 v76, vcc, 0, v76, s[10:11]
	v_cmp_ge_f32_e64 s[10:11], v103, v22
	v_addc_co_u32_e64 v75, vcc, 0, v75, s[12:13]
	v_cmp_ge_f32_e64 s[12:13], v103, v23
	v_addc_co_u32_e64 v74, vcc, 0, v74, s[8:9]
	v_cmp_ge_f32_e64 s[8:9], v103, v24
	v_addc_co_u32_e64 v73, vcc, 0, v73, s[10:11]
	v_cmp_ge_f32_e64 s[10:11], v103, v25
	v_addc_co_u32_e64 v72, vcc, 0, v72, s[12:13]
	v_cmp_ge_f32_e64 s[12:13], v103, v26
	v_addc_co_u32_e64 v71, vcc, 0, v71, s[8:9]
	v_cmp_ge_f32_e64 s[8:9], v103, v27
	v_addc_co_u32_e64 v70, vcc, 0, v70, s[10:11]
	v_cmp_ge_f32_e64 s[10:11], v103, v28
	v_addc_co_u32_e64 v69, vcc, 0, v69, s[12:13]
	v_cmp_ge_f32_e64 s[12:13], v103, v29
	v_addc_co_u32_e64 v68, vcc, 0, v68, s[8:9]
	v_cmp_ge_f32_e64 s[8:9], v103, v30
	v_addc_co_u32_e64 v67, vcc, 0, v67, s[10:11]
	v_cmp_ge_f32_e64 s[10:11], v103, v31
	v_addc_co_u32_e64 v66, vcc, 0, v66, s[12:13]
	s_nop 0
	v_addc_co_u32_e64 v65, vcc, 0, v65, s[8:9]
	v_addc_co_u32_e64 v64, vcc, 0, v64, s[10:11]
	s_cmp_le_u32 s14, 4
	s_cbranch_scc1 .Lrk_done
	ds_read2_b32 v[102:103], v104 offset0:6 offset1:7
	s_waitcnt lgkmcnt(1)
	v_cmp_gt_f32_e64 s[8:9], v100, v0
	v_cmp_gt_f32_e64 s[10:11], v100, v1
	v_cmp_ge_f32_e64 s[12:13], v100, v2
	v_addc_co_u32_e64 v97, vcc, 0, v97, s[8:9]
	v_cmp_ge_f32_e64 s[8:9], v100, v3
	v_addc_co_u32_e64 v96, vcc, 0, v96, s[10:11]
	v_cmp_ge_f32_e64 s[10:11], v100, v4
	s_and_b64 s[12:13], s[12:13], s[6:7]
	v_addc_co_u32_e64 v95, vcc, 0, v95, s[12:13]
	v_cmp_ge_f32_e64 s[12:13], v100, v5
	v_addc_co_u32_e64 v94, vcc, 0, v94, s[8:9]
	v_cmp_ge_f32_e64 s[8:9], v100, v6
	v_addc_co_u32_e64 v93, vcc, 0, v93, s[10:11]
	v_cmp_ge_f32_e64 s[10:11], v100, v7
	v_addc_co_u32_e64 v92, vcc, 0, v92, s[12:13]
	v_cmp_ge_f32_e64 s[12:13], v100, v8
	v_addc_co_u32_e64 v91, vcc, 0, v91, s[8:9]
	v_cmp_ge_f32_e64 s[8:9], v100, v9
	v_addc_co_u32_e64 v90, vcc, 0, v90, s[10:11]
	v_cmp_ge_f32_e64 s[10:11], v100, v10
	v_addc_co_u32_e64 v89, vcc, 0, v89, s[12:13]
	v_cmp_ge_f32_e64 s[12:13], v100, v11
	v_addc_co_u32_e64 v88, vcc, 0, v88, s[8:9]
	v_cmp_ge_f32_e64 s[8:9], v100, v12
	v_addc_co_u32_e64 v87, vcc, 0, v87, s[10:11]
	v_cmp_ge_f32_e64 s[10:11], v100, v13
	v_addc_co_u32_e64 v86, vcc, 0, v86, s[12:13]
	v_cmp_ge_f32_e64 s[12:13], v100, v14
	v_addc_co_u32_e64 v85, vcc, 0, v85, s[8:9]
	v_cmp_ge_f32_e64 s[8:9], v100, v15
	v_addc_co_u32_e64 v84, vcc, 0, v84, s[10:11]
	v_cmp_ge_f32_e64 s[10:11], v100, v16
	v_addc_co_u32_e64 v83, vcc, 0, v83, s[12:13]
	v_cmp_ge_f32_e64 s[12:13], v100, v17
	v_addc_co_u32_e64 v81, vcc, 0, v81, s[8:9]
	v_cmp_ge_f32_e64 s[8:9], v100, v18
	v_addc_co_u32_e64 v79, vcc, 0, v79, s[10:11]
	v_cmp_ge_f32_e64 s[10:11], v100, v19
	v_addc_co_u32_e64 v78, vcc, 0, v78, s[12:13]
	v_cmp_ge_f32_e64 s[12:13], v100, v20
	v_addc_co_u32_e64 v77, vcc, 0, v77, s[8:9]
	v_cmp_ge_f32_e64 s[8:9], v100, v21
	v_addc_co_u32_e64 v76, vcc, 0, v76, s[10:11]
	v_cmp_ge_f32_e64 s[10:11], v100, v22
	v_addc_co_u32_e64 v75, vcc, 0, v75, s[12:13]
	v_cmp_ge_f32_e64 s[12:13], v100, v23
	v_addc_co_u32_e64 v74, vcc, 0, v74, s[8:9]
	v_cmp_ge_f32_e64 s[8:9], v100, v24
	v_addc_co_u32_e64 v73, vcc, 0, v73, s[10:11]
	v_cmp_ge_f32_e64 s[10:11], v100, v25
	v_addc_co_u32_e64 v72, vcc, 0, v72, s[12:13]
	v_cmp_ge_f32_e64 s[12:13], v100, v26
	v_addc_co_u32_e64 v71, vcc, 0, v71, s[8:9]
	v_cmp_ge_f32_e64 s[8:9], v100, v27
	v_addc_co_u32_e64 v70, vcc, 0, v70, s[10:11]
	v_cmp_ge_f32_e64 s[10:11], v100, v28
	v_addc_co_u32_e64 v69, vcc, 0, v69, s[12:13]
	v_cmp_ge_f32_e64 s[12:13], v100, v29
	v_addc_co_u32_e64 v68, vcc, 0, v68, s[8:9]
	v_cmp_ge_f32_e64 s[8:9], v100, v30
	v_addc_co_u32_e64 v67, vcc, 0, v67, s[10:11]
	v_cmp_ge_f32_e64 s[10:11], v100, v31
	v_addc_co_u32_e64 v66, vcc, 0, v66, s[12:13]
	s_nop 0
	v_addc_co_u32_e64 v65, vcc, 0, v65, s[8:9]
	v_addc_co_u32_e64 v64, vcc, 0, v64, s[10:11]
	s_cmp_le_u32 s14, 5
	s_cbranch_scc1 .Lrk_done
; __device__ __forceinline__ void cmp_phase(LAS unsigned char* lds, const bf16_t* __restrict__ P, const bf16_t* __restrict__ Kc, const bf16_t* __restrict__ Vc,
;                                           bf16_t* __restrict__ ocmp, unsigned long long* __restrict__ mask, int G, const int wave0) {
;     ...
; #pragma nounroll
;             for (int k = 0; k < kmax; ++k) {
;                 const float sk = sc[k];
;                 const int kk = k - hi;
; #pragma unroll
;                 for (int i = 0; i < 32; ++i) rank[i] += ((sk > s[i]) || ((sk == s[i]) && (kk < 2 * i))) ? 1 : 0;
;             }
	v_cmp_gt_f32_e64 s[8:9], v101, v0
	v_cmp_gt_f32_e64 s[10:11], v101, v1
	v_cmp_gt_f32_e64 s[12:13], v101, v2
	v_addc_co_u32_e64 v97, vcc, 0, v97, s[8:9]
	v_cmp_ge_f32_e64 s[8:9], v101, v3
	v_addc_co_u32_e64 v96, vcc, 0, v96, s[10:11]
	v_cmp_ge_f32_e64 s[10:11], v101, v4
	v_addc_co_u32_e64 v95, vcc, 0, v95, s[12:13]
	v_cmp_ge_f32_e64 s[12:13], v101, v5
	v_addc_co_u32_e64 v94, vcc, 0, v94, s[8:9]
	v_cmp_ge_f32_e64 s[8:9], v101, v6
	v_addc_co_u32_e64 v93, vcc, 0, v93, s[10:11]
	v_cmp_ge_f32_e64 s[10:11], v101, v7
	v_addc_co_u32_e64 v92, vcc, 0, v92, s[12:13]
	v_cmp_ge_f32_e64 s[12:13], v101, v8
	v_addc_co_u32_e64 v91, vcc, 0, v91, s[8:9]
	v_cmp_ge_f32_e64 s[8:9], v101, v9
	v_addc_co_u32_e64 v90, vcc, 0, v90, s[10:11]
	v_cmp_ge_f32_e64 s[10:11], v101, v10
	v_addc_co_u32_e64 v89, vcc, 0, v89, s[12:13]
	v_cmp_ge_f32_e64 s[12:13], v101, v11
	v_addc_co_u32_e64 v88, vcc, 0, v88, s[8:9]
	v_cmp_ge_f32_e64 s[8:9], v101, v12
	v_addc_co_u32_e64 v87, vcc, 0, v87, s[10:11]
	v_cmp_ge_f32_e64 s[10:11], v101, v13
	v_addc_co_u32_e64 v86, vcc, 0, v86, s[12:13]
	v_cmp_ge_f32_e64 s[12:13], v101, v14
	v_addc_co_u32_e64 v85, vcc, 0, v85, s[8:9]
	v_cmp_ge_f32_e64 s[8:9], v101, v15
	v_addc_co_u32_e64 v84, vcc, 0, v84, s[10:11]
	v_cmp_ge_f32_e64 s[10:11], v101, v16
	v_addc_co_u32_e64 v83, vcc, 0, v83, s[12:13]
	v_cmp_ge_f32_e64 s[12:13], v101, v17
	v_addc_co_u32_e64 v81, vcc, 0, v81, s[8:9]
	v_cmp_ge_f32_e64 s[8:9], v101, v18
	v_addc_co_u32_e64 v79, vcc, 0, v79, s[10:11]
	v_cmp_ge_f32_e64 s[10:11], v101, v19
	v_addc_co_u32_e64 v78, vcc, 0, v78, s[12:13]
	v_cmp_ge_f32_e64 s[12:13], v101, v20
	v_addc_co_u32_e64 v77, vcc, 0, v77, s[8:9]
	v_cmp_ge_f32_e64 s[8:9], v101, v21
	v_addc_co_u32_e64 v76, vcc, 0, v76, s[10:11]
	v_cmp_ge_f32_e64 s[10:11], v101, v22
	v_addc_co_u32_e64 v75, vcc, 0, v75, s[12:13]
	v_cmp_ge_f32_e64 s[12:13], v101, v23
	v_addc_co_u32_e64 v74, vcc, 0, v74, s[8:9]
	v_cmp_ge_f32_e64 s[8:9], v101, v24
	v_addc_co_u32_e64 v73, vcc, 0, v73, s[10:11]
	v_cmp_ge_f32_e64 s[10:11], v101, v25
	v_addc_co_u32_e64 v72, vcc, 0, v72, s[12:13]
	v_cmp_ge_f32_e64 s[12:13], v101, v26
	v_addc_co_u32_e64 v71, vcc, 0, v71, s[8:9]
	v_cmp_ge_f32_e64 s[8:9], v101, v27
	v_addc_co_u32_e64 v70, vcc, 0, v70, s[10:11]
	v_cmp_ge_f32_e64 s[10:11], v101, v28
	v_addc_co_u32_e64 v69, vcc, 0, v69, s[12:13]
	v_cmp_ge_f32_e64 s[12:13], v101, v29
	v_addc_co_u32_e64 v68, vcc, 0, v68, s[8:9]
	v_cmp_ge_f32_e64 s[8:9], v101, v30
	v_addc_co_u32_e64 v67, vcc, 0, v67, s[10:11]
	v_cmp_ge_f32_e64 s[10:11], v101, v31
	v_addc_co_u32_e64 v66, vcc, 0, v66, s[12:13]
	s_nop 0
	v_addc_co_u32_e64 v65, vcc, 0, v65, s[8:9]
	v_addc_co_u32_e64 v64, vcc, 0, v64, s[10:11]
	s_cmp_le_u32 s14, 6
	s_cbranch_scc1 .Lrk_done
	ds_read2_b32 v[100:101], v104 offset0:8 offset1:9
	s_waitcnt lgkmcnt(1)
	v_cmp_gt_f32_e64 s[8:9], v102, v0
	v_cmp_gt_f32_e64 s[10:11], v102, v1
	v_cmp_gt_f32_e64 s[12:13], v102, v2
	v_addc_co_u32_e64 v97, vcc, 0, v97, s[8:9]
	v_cmp_ge_f32_e64 s[8:9], v102, v3
	v_addc_co_u32_e64 v96, vcc, 0, v96, s[10:11]
	v_cmp_ge_f32_e64 s[10:11], v102, v4
	v_addc_co_u32_e64 v95, vcc, 0, v95, s[12:13]
	v_cmp_ge_f32_e64 s[12:13], v102, v5
	s_and_b64 s[8:9], s[8:9], s[6:7]
	v_addc_co_u32_e64 v94, vcc, 0, v94, s[8:9]
	v_cmp_ge_f32_e64 s[8:9], v102, v6
	v_addc_co_u32_e64 v93, vcc, 0, v93, s[10:11]
	v_cmp_ge_f32_e64 s[10:11], v102, v7
	v_addc_co_u32_e64 v92, vcc, 0, v92, s[12:13]
	v_cmp_ge_f32_e64 s[12:13], v102, v8
	v_addc_co_u32_e64 v91, vcc, 0, v91, s[8:9]
	v_cmp_ge_f32_e64 s[8:9], v102, v9
	v_addc_co_u32_e64 v90, vcc, 0, v90, s[10:11]
	v_cmp_ge_f32_e64 s[10:11], v102, v10
	v_addc_co_u32_e64 v89, vcc, 0, v89, s[12:13]
	v_cmp_ge_f32_e64 s[12:13], v102, v11
	v_addc_co_u32_e64 v88, vcc, 0, v88, s[8:9]
	v_cmp_ge_f32_e64 s[8:9], v102, v12
	v_addc_co_u32_e64 v87, vcc, 0, v87, s[10:11]
	v_cmp_ge_f32_e64 s[10:11], v102, v13
	v_addc_co_u32_e64 v86, vcc, 0, v86, s[12:13]
	v_cmp_ge_f32_e64 s[12:13], v102, v14
	v_addc_co_u32_e64 v85, vcc, 0, v85, s[8:9]
	v_cmp_ge_f32_e64 s[8:9], v102, v15
	v_addc_co_u32_e64 v84, vcc, 0, v84, s[10:11]
	v_cmp_ge_f32_e64 s[10:11], v102, v16
	v_addc_co_u32_e64 v83, vcc, 0, v83, s[12:13]
	v_cmp_ge_f32_e64 s[12:13], v102, v17
	v_addc_co_u32_e64 v81, vcc, 0, v81, s[8:9]
	v_cmp_ge_f32_e64 s[8:9], v102, v18
	v_addc_co_u32_e64 v79, vcc, 0, v79, s[10:11]
	v_cmp_ge_f32_e64 s[10:11], v102, v19
	v_addc_co_u32_e64 v78, vcc, 0, v78, s[12:13]
	v_cmp_ge_f32_e64 s[12:13], v102, v20
	v_addc_co_u32_e64 v77, vcc, 0, v77, s[8:9]
	v_cmp_ge_f32_e64 s[8:9], v102, v21
	v_addc_co_u32_e64 v76, vcc, 0, v76, s[10:11]
	v_cmp_ge_f32_e64 s[10:11], v102, v22
	v_addc_co_u32_e64 v75, vcc, 0, v75, s[12:13]
	v_cmp_ge_f32_e64 s[12:13], v102, v23
	v_addc_co_u32_e64 v74, vcc, 0, v74, s[8:9]
	v_cmp_ge_f32_e64 s[8:9], v102, v24
	v_addc_co_u32_e64 v73, vcc, 0, v73, s[10:11]
	v_cmp_ge_f32_e64 s[10:11], v102, v25
	v_addc_co_u32_e64 v72, vcc, 0, v72, s[12:13]
	v_cmp_ge_f32_e64 s[12:13], v102, v26
	v_addc_co_u32_e64 v71, vcc, 0, v71, s[8:9]
	v_cmp_ge_f32_e64 s[8:9], v102, v27
	v_addc_co_u32_e64 v70, vcc, 0, v70, s[10:11]
	v_cmp_ge_f32_e64 s[10:11], v102, v28
	v_addc_co_u32_e64 v69, vcc, 0, v69, s[12:13]
	v_cmp_ge_f32_e64 s[12:13], v102, v29
	v_addc_co_u32_e64 v68, vcc, 0, v68, s[8:9]
	v_cmp_ge_f32_e64 s[8:9], v102, v30
	v_addc_co_u32_e64 v67, vcc, 0, v67, s[10:11]
	v_cmp_ge_f32_e64 s[10:11], v102, v31
	v_addc_co_u32_e64 v66, vcc, 0, v66, s[12:13]
	s_nop 0
	v_addc_co_u32_e64 v65, vcc, 0, v65, s[8:9]
	v_addc_co_u32_e64 v64, vcc, 0, v64, s[10:11]
	s_cmp_le_u32 s14, 7
	s_cbranch_scc1 .Lrk_done
; __device__ __forceinline__ void cmp_phase(LAS unsigned char* lds, const bf16_t* __restrict__ P, const bf16_t* __restrict__ Kc, const bf16_t* __restrict__ Vc,
;                                           bf16_t* __restrict__ ocmp, unsigned long long* __restrict__ mask, int G, const int wave0) {
;     ...
; #pragma nounroll
;             for (int k = 0; k < kmax; ++k) {
;                 const float sk = sc[k];
;                 const int kk = k - hi;
; #pragma unroll
;                 for (int i = 0; i < 32; ++i) rank[i] += ((sk > s[i]) || ((sk == s[i]) && (kk < 2 * i))) ? 1 : 0;
;             }
	v_cmp_gt_f32_e64 s[8:9], v103, v0
	v_cmp_gt_f32_e64 s[10:11], v103, v1
	v_cmp_gt_f32_e64 s[12:13], v103, v2
	v_addc_co_u32_e64 v97, vcc, 0, v97, s[8:9]
	v_cmp_gt_f32_e64 s[8:9], v103, v3
	v_addc_co_u32_e64 v96, vcc, 0, v96, s[10:11]
	v_cmp_ge_f32_e64 s[10:11], v103, v4
	v_addc_co_u32_e64 v95, vcc, 0, v95, s[12:13]
	v_cmp_ge_f32_e64 s[12:13], v103, v5
	v_addc_co_u32_e64 v94, vcc, 0, v94, s[8:9]
	v_cmp_ge_f32_e64 s[8:9], v103, v6
	v_addc_co_u32_e64 v93, vcc, 0, v93, s[10:11]
	v_cmp_ge_f32_e64 s[10:11], v103, v7
	v_addc_co_u32_e64 v92, vcc, 0, v92, s[12:13]
	v_cmp_ge_f32_e64 s[12:13], v103, v8
	v_addc_co_u32_e64 v91, vcc, 0, v91, s[8:9]
	v_cmp_ge_f32_e64 s[8:9], v103, v9
	v_addc_co_u32_e64 v90, vcc, 0, v90, s[10:11]
	v_cmp_ge_f32_e64 s[10:11], v103, v10
	v_addc_co_u32_e64 v89, vcc, 0, v89, s[12:13]
	v_cmp_ge_f32_e64 s[12:13], v103, v11
	v_addc_co_u32_e64 v88, vcc, 0, v88, s[8:9]
	v_cmp_ge_f32_e64 s[8:9], v103, v12
	v_addc_co_u32_e64 v87, vcc, 0, v87, s[10:11]
	v_cmp_ge_f32_e64 s[10:11], v103, v13
	v_addc_co_u32_e64 v86, vcc, 0, v86, s[12:13]
	v_cmp_ge_f32_e64 s[12:13], v103, v14
	v_addc_co_u32_e64 v85, vcc, 0, v85, s[8:9]
	v_cmp_ge_f32_e64 s[8:9], v103, v15
	v_addc_co_u32_e64 v84, vcc, 0, v84, s[10:11]
	v_cmp_ge_f32_e64 s[10:11], v103, v16
	v_addc_co_u32_e64 v83, vcc, 0, v83, s[12:13]
	v_cmp_ge_f32_e64 s[12:13], v103, v17
	v_addc_co_u32_e64 v81, vcc, 0, v81, s[8:9]
	v_cmp_ge_f32_e64 s[8:9], v103, v18
	v_addc_co_u32_e64 v79, vcc, 0, v79, s[10:11]
	v_cmp_ge_f32_e64 s[10:11], v103, v19
	v_addc_co_u32_e64 v78, vcc, 0, v78, s[12:13]
	v_cmp_ge_f32_e64 s[12:13], v103, v20
	v_addc_co_u32_e64 v77, vcc, 0, v77, s[8:9]
	v_cmp_ge_f32_e64 s[8:9], v103, v21
	v_addc_co_u32_e64 v76, vcc, 0, v76, s[10:11]
	v_cmp_ge_f32_e64 s[10:11], v103, v22
	v_addc_co_u32_e64 v75, vcc, 0, v75, s[12:13]
	v_cmp_ge_f32_e64 s[12:13], v103, v23
	v_addc_co_u32_e64 v74, vcc, 0, v74, s[8:9]
	v_cmp_ge_f32_e64 s[8:9], v103, v24
	v_addc_co_u32_e64 v73, vcc, 0, v73, s[10:11]
	v_cmp_ge_f32_e64 s[10:11], v103, v25
	v_addc_co_u32_e64 v72, vcc, 0, v72, s[12:13]
	v_cmp_ge_f32_e64 s[12:13], v103, v26
	v_addc_co_u32_e64 v71, vcc, 0, v71, s[8:9]
	v_cmp_ge_f32_e64 s[8:9], v103, v27
	v_addc_co_u32_e64 v70, vcc, 0, v70, s[10:11]
	v_cmp_ge_f32_e64 s[10:11], v103, v28
	v_addc_co_u32_e64 v69, vcc, 0, v69, s[12:13]
	v_cmp_ge_f32_e64 s[12:13], v103, v29
	v_addc_co_u32_e64 v68, vcc, 0, v68, s[8:9]
	v_cmp_ge_f32_e64 s[8:9], v103, v30
	v_addc_co_u32_e64 v67, vcc, 0, v67, s[10:11]
	v_cmp_ge_f32_e64 s[10:11], v103, v31
	v_addc_co_u32_e64 v66, vcc, 0, v66, s[12:13]
	s_nop 0
	v_addc_co_u32_e64 v65, vcc, 0, v65, s[8:9]
	v_addc_co_u32_e64 v64, vcc, 0, v64, s[10:11]
	s_cmp_le_u32 s14, 8
	s_cbranch_scc1 .Lrk_done
	ds_read2_b32 v[102:103], v104 offset0:10 offset1:11
	s_waitcnt lgkmcnt(1)
	v_cmp_gt_f32_e64 s[8:9], v100, v0
	v_cmp_gt_f32_e64 s[10:11], v100, v1
	v_cmp_gt_f32_e64 s[12:13], v100, v2
	v_addc_co_u32_e64 v97, vcc, 0, v97, s[8:9]
	v_cmp_gt_f32_e64 s[8:9], v100, v3
	v_addc_co_u32_e64 v96, vcc, 0, v96, s[10:11]
	v_cmp_ge_f32_e64 s[10:11], v100, v4
	v_addc_co_u32_e64 v95, vcc, 0, v95, s[12:13]
	v_cmp_ge_f32_e64 s[12:13], v100, v5
	v_addc_co_u32_e64 v94, vcc, 0, v94, s[8:9]
	v_cmp_ge_f32_e64 s[8:9], v100, v6
	s_and_b64 s[10:11], s[10:11], s[6:7]
	v_addc_co_u32_e64 v93, vcc, 0, v93, s[10:11]
	v_cmp_ge_f32_e64 s[10:11], v100, v7
	v_addc_co_u32_e64 v92, vcc, 0, v92, s[12:13]
	v_cmp_ge_f32_e64 s[12:13], v100, v8
	v_addc_co_u32_e64 v91, vcc, 0, v91, s[8:9]
	v_cmp_ge_f32_e64 s[8:9], v100, v9
	v_addc_co_u32_e64 v90, vcc, 0, v90, s[10:11]
	v_cmp_ge_f32_e64 s[10:11], v100, v10
	v_addc_co_u32_e64 v89, vcc, 0, v89, s[12:13]
	v_cmp_ge_f32_e64 s[12:13], v100, v11
	v_addc_co_u32_e64 v88, vcc, 0, v88, s[8:9]
	v_cmp_ge_f32_e64 s[8:9], v100, v12
	v_addc_co_u32_e64 v87, vcc, 0, v87, s[10:11]
	v_cmp_ge_f32_e64 s[10:11], v100, v13
	v_addc_co_u32_e64 v86, vcc, 0, v86, s[12:13]
	v_cmp_ge_f32_e64 s[12:13], v100, v14
	v_addc_co_u32_e64 v85, vcc, 0, v85, s[8:9]
	v_cmp_ge_f32_e64 s[8:9], v100, v15
	v_addc_co_u32_e64 v84, vcc, 0, v84, s[10:11]
	v_cmp_ge_f32_e64 s[10:11], v100, v16
	v_addc_co_u32_e64 v83, vcc, 0, v83, s[12:13]
	v_cmp_ge_f32_e64 s[12:13], v100, v17
	v_addc_co_u32_e64 v81, vcc, 0, v81, s[8:9]
	v_cmp_ge_f32_e64 s[8:9], v100, v18
	v_addc_co_u32_e64 v79, vcc, 0, v79, s[10:11]
	v_cmp_ge_f32_e64 s[10:11], v100, v19
	v_addc_co_u32_e64 v78, vcc, 0, v78, s[12:13]
	v_cmp_ge_f32_e64 s[12:13], v100, v20
	v_addc_co_u32_e64 v77, vcc, 0, v77, s[8:9]
	v_cmp_ge_f32_e64 s[8:9], v100, v21
	v_addc_co_u32_e64 v76, vcc, 0, v76, s[10:11]
	v_cmp_ge_f32_e64 s[10:11], v100, v22
	v_addc_co_u32_e64 v75, vcc, 0, v75, s[12:13]
	v_cmp_ge_f32_e64 s[12:13], v100, v23
	v_addc_co_u32_e64 v74, vcc, 0, v74, s[8:9]
	v_cmp_ge_f32_e64 s[8:9], v100, v24
	v_addc_co_u32_e64 v73, vcc, 0, v73, s[10:11]
	v_cmp_ge_f32_e64 s[10:11], v100, v25
	v_addc_co_u32_e64 v72, vcc, 0, v72, s[12:13]
	v_cmp_ge_f32_e64 s[12:13], v100, v26
	v_addc_co_u32_e64 v71, vcc, 0, v71, s[8:9]
	v_cmp_ge_f32_e64 s[8:9], v100, v27
	v_addc_co_u32_e64 v70, vcc, 0, v70, s[10:11]
	v_cmp_ge_f32_e64 s[10:11], v100, v28
	v_addc_co_u32_e64 v69, vcc, 0, v69, s[12:13]
	v_cmp_ge_f32_e64 s[12:13], v100, v29
	v_addc_co_u32_e64 v68, vcc, 0, v68, s[8:9]
	v_cmp_ge_f32_e64 s[8:9], v100, v30
	v_addc_co_u32_e64 v67, vcc, 0, v67, s[10:11]
	v_cmp_ge_f32_e64 s[10:11], v100, v31
	v_addc_co_u32_e64 v66, vcc, 0, v66, s[12:13]
	s_nop 0
	v_addc_co_u32_e64 v65, vcc, 0, v65, s[8:9]
	v_addc_co_u32_e64 v64, vcc, 0, v64, s[10:11]
	s_cmp_le_u32 s14, 9
	s_cbranch_scc1 .Lrk_done
; __device__ __forceinline__ void cmp_phase(LAS unsigned char* lds, const bf16_t* __restrict__ P, const bf16_t* __restrict__ Kc, const bf16_t* __restrict__ Vc,
;                                           bf16_t* __restrict__ ocmp, unsigned long long* __restrict__ mask, int G, const int wave0) {
;     ...
; #pragma nounroll
;             for (int k = 0; k < kmax; ++k) {
;                 const float sk = sc[k];
;                 const int kk = k - hi;
; #pragma unroll
;                 for (int i = 0; i < 32; ++i) rank[i] += ((sk > s[i]) || ((sk == s[i]) && (kk < 2 * i))) ? 1 : 0;
;             }
	v_cmp_gt_f32_e64 s[8:9], v101, v0
	v_cmp_gt_f32_e64 s[10:11], v101, v1
	v_cmp_gt_f32_e64 s[12:13], v101, v2
	v_addc_co_u32_e64 v97, vcc, 0, v97, s[8:9]
	v_cmp_gt_f32_e64 s[8:9], v101, v3
	v_addc_co_u32_e64 v96, vcc, 0, v96, s[10:11]
	v_cmp_gt_f32_e64 s[10:11], v101, v4
	v_addc_co_u32_e64 v95, vcc, 0, v95, s[12:13]
	v_cmp_ge_f32_e64 s[12:13], v101, v5
	v_addc_co_u32_e64 v94, vcc, 0, v94, s[8:9]
	v_cmp_ge_f32_e64 s[8:9], v101, v6
	v_addc_co_u32_e64 v93, vcc, 0, v93, s[10:11]
	v_cmp_ge_f32_e64 s[10:11], v101, v7
	v_addc_co_u32_e64 v92, vcc, 0, v92, s[12:13]
	v_cmp_ge_f32_e64 s[12:13], v101, v8
	v_addc_co_u32_e64 v91, vcc, 0, v91, s[8:9]
	v_cmp_ge_f32_e64 s[8:9], v101, v9
	v_addc_co_u32_e64 v90, vcc, 0, v90, s[10:11]
	v_cmp_ge_f32_e64 s[10:11], v101, v10
	v_addc_co_u32_e64 v89, vcc, 0, v89, s[12:13]
	v_cmp_ge_f32_e64 s[12:13], v101, v11
	v_addc_co_u32_e64 v88, vcc, 0, v88, s[8:9]
	v_cmp_ge_f32_e64 s[8:9], v101, v12
	v_addc_co_u32_e64 v87, vcc, 0, v87, s[10:11]
	v_cmp_ge_f32_e64 s[10:11], v101, v13
	v_addc_co_u32_e64 v86, vcc, 0, v86, s[12:13]
	v_cmp_ge_f32_e64 s[12:13], v101, v14
	v_addc_co_u32_e64 v85, vcc, 0, v85, s[8:9]
	v_cmp_ge_f32_e64 s[8:9], v101, v15
	v_addc_co_u32_e64 v84, vcc, 0, v84, s[10:11]
	v_cmp_ge_f32_e64 s[10:11], v101, v16
	v_addc_co_u32_e64 v83, vcc, 0, v83, s[12:13]
	v_cmp_ge_f32_e64 s[12:13], v101, v17
	v_addc_co_u32_e64 v81, vcc, 0, v81, s[8:9]
	v_cmp_ge_f32_e64 s[8:9], v101, v18
	v_addc_co_u32_e64 v79, vcc, 0, v79, s[10:11]
	v_cmp_ge_f32_e64 s[10:11], v101, v19
	v_addc_co_u32_e64 v78, vcc, 0, v78, s[12:13]
	v_cmp_ge_f32_e64 s[12:13], v101, v20
	v_addc_co_u32_e64 v77, vcc, 0, v77, s[8:9]
	v_cmp_ge_f32_e64 s[8:9], v101, v21
	v_addc_co_u32_e64 v76, vcc, 0, v76, s[10:11]
	v_cmp_ge_f32_e64 s[10:11], v101, v22
	v_addc_co_u32_e64 v75, vcc, 0, v75, s[12:13]
	v_cmp_ge_f32_e64 s[12:13], v101, v23
	v_addc_co_u32_e64 v74, vcc, 0, v74, s[8:9]
	v_cmp_ge_f32_e64 s[8:9], v101, v24
	v_addc_co_u32_e64 v73, vcc, 0, v73, s[10:11]
	v_cmp_ge_f32_e64 s[10:11], v101, v25
	v_addc_co_u32_e64 v72, vcc, 0, v72, s[12:13]
	v_cmp_ge_f32_e64 s[12:13], v101, v26
	v_addc_co_u32_e64 v71, vcc, 0, v71, s[8:9]
	v_cmp_ge_f32_e64 s[8:9], v101, v27
	v_addc_co_u32_e64 v70, vcc, 0, v70, s[10:11]
	v_cmp_ge_f32_e64 s[10:11], v101, v28
	v_addc_co_u32_e64 v69, vcc, 0, v69, s[12:13]
	v_cmp_ge_f32_e64 s[12:13], v101, v29
	v_addc_co_u32_e64 v68, vcc, 0, v68, s[8:9]
	v_cmp_ge_f32_e64 s[8:9], v101, v30
	v_addc_co_u32_e64 v67, vcc, 0, v67, s[10:11]
	v_cmp_ge_f32_e64 s[10:11], v101, v31
	v_addc_co_u32_e64 v66, vcc, 0, v66, s[12:13]
	s_nop 0
	v_addc_co_u32_e64 v65, vcc, 0, v65, s[8:9]
	v_addc_co_u32_e64 v64, vcc, 0, v64, s[10:11]
	s_cmp_le_u32 s14, 10
	s_cbranch_scc1 .Lrk_done
	ds_read2_b32 v[100:101], v104 offset0:12 offset1:13
	s_waitcnt lgkmcnt(1)
	v_cmp_gt_f32_e64 s[8:9], v102, v0
	v_cmp_gt_f32_e64 s[10:11], v102, v1
	v_cmp_gt_f32_e64 s[12:13], v102, v2
	v_addc_co_u32_e64 v97, vcc, 0, v97, s[8:9]
	v_cmp_gt_f32_e64 s[8:9], v102, v3
	v_addc_co_u32_e64 v96, vcc, 0, v96, s[10:11]
	v_cmp_gt_f32_e64 s[10:11], v102, v4
	v_addc_co_u32_e64 v95, vcc, 0, v95, s[12:13]
	v_cmp_ge_f32_e64 s[12:13], v102, v5
	v_addc_co_u32_e64 v94, vcc, 0, v94, s[8:9]
	v_cmp_ge_f32_e64 s[8:9], v102, v6
	v_addc_co_u32_e64 v93, vcc, 0, v93, s[10:11]
	v_cmp_ge_f32_e64 s[10:11], v102, v7
	s_and_b64 s[12:13], s[12:13], s[6:7]
	v_addc_co_u32_e64 v92, vcc, 0, v92, s[12:13]
	v_cmp_ge_f32_e64 s[12:13], v102, v8
	v_addc_co_u32_e64 v91, vcc, 0, v91, s[8:9]
	v_cmp_ge_f32_e64 s[8:9], v102, v9
	v_addc_co_u32_e64 v90, vcc, 0, v90, s[10:11]
	v_cmp_ge_f32_e64 s[10:11], v102, v10
	v_addc_co_u32_e64 v89, vcc, 0, v89, s[12:13]
	v_cmp_ge_f32_e64 s[12:13], v102, v11
	v_addc_co_u32_e64 v88, vcc, 0, v88, s[8:9]
	v_cmp_ge_f32_e64 s[8:9], v102, v12
	v_addc_co_u32_e64 v87, vcc, 0, v87, s[10:11]
	v_cmp_ge_f32_e64 s[10:11], v102, v13
	v_addc_co_u32_e64 v86, vcc, 0, v86, s[12:13]
	v_cmp_ge_f32_e64 s[12:13], v102, v14
	v_addc_co_u32_e64 v85, vcc, 0, v85, s[8:9]
	v_cmp_ge_f32_e64 s[8:9], v102, v15
	v_addc_co_u32_e64 v84, vcc, 0, v84, s[10:11]
	v_cmp_ge_f32_e64 s[10:11], v102, v16
	v_addc_co_u32_e64 v83, vcc, 0, v83, s[12:13]
	v_cmp_ge_f32_e64 s[12:13], v102, v17
	v_addc_co_u32_e64 v81, vcc, 0, v81, s[8:9]
	v_cmp_ge_f32_e64 s[8:9], v102, v18
	v_addc_co_u32_e64 v79, vcc, 0, v79, s[10:11]
	v_cmp_ge_f32_e64 s[10:11], v102, v19
	v_addc_co_u32_e64 v78, vcc, 0, v78, s[12:13]
	v_cmp_ge_f32_e64 s[12:13], v102, v20
	v_addc_co_u32_e64 v77, vcc, 0, v77, s[8:9]
	v_cmp_ge_f32_e64 s[8:9], v102, v21
	v_addc_co_u32_e64 v76, vcc, 0, v76, s[10:11]
	v_cmp_ge_f32_e64 s[10:11], v102, v22
	v_addc_co_u32_e64 v75, vcc, 0, v75, s[12:13]
	v_cmp_ge_f32_e64 s[12:13], v102, v23
	v_addc_co_u32_e64 v74, vcc, 0, v74, s[8:9]
	v_cmp_ge_f32_e64 s[8:9], v102, v24
	v_addc_co_u32_e64 v73, vcc, 0, v73, s[10:11]
	v_cmp_ge_f32_e64 s[10:11], v102, v25
	v_addc_co_u32_e64 v72, vcc, 0, v72, s[12:13]
	v_cmp_ge_f32_e64 s[12:13], v102, v26
	v_addc_co_u32_e64 v71, vcc, 0, v71, s[8:9]
	v_cmp_ge_f32_e64 s[8:9], v102, v27
	v_addc_co_u32_e64 v70, vcc, 0, v70, s[10:11]
	v_cmp_ge_f32_e64 s[10:11], v102, v28
	v_addc_co_u32_e64 v69, vcc, 0, v69, s[12:13]
	v_cmp_ge_f32_e64 s[12:13], v102, v29
	v_addc_co_u32_e64 v68, vcc, 0, v68, s[8:9]
	v_cmp_ge_f32_e64 s[8:9], v102, v30
	v_addc_co_u32_e64 v67, vcc, 0, v67, s[10:11]
	v_cmp_ge_f32_e64 s[10:11], v102, v31
	v_addc_co_u32_e64 v66, vcc, 0, v66, s[12:13]
	s_nop 0
	v_addc_co_u32_e64 v65, vcc, 0, v65, s[8:9]
	v_addc_co_u32_e64 v64, vcc, 0, v64, s[10:11]
	s_cmp_le_u32 s14, 11
	s_cbranch_scc1 .Lrk_done
; __device__ __forceinline__ void cmp_phase(LAS unsigned char* lds, const bf16_t* __restrict__ P, const bf16_t* __restrict__ Kc, const bf16_t* __restrict__ Vc,
;                                           bf16_t* __restrict__ ocmp, unsigned long long* __restrict__ mask, int G, const int wave0) {
;     ...
; #pragma nounroll
;             for (int k = 0; k < kmax; ++k) {
;                 const float sk = sc[k];
;                 const int kk = k - hi;
; #pragma unroll
;                 for (int i = 0; i < 32; ++i) rank[i] += ((sk > s[i]) || ((sk == s[i]) && (kk < 2 * i))) ? 1 : 0;
;             }
	v_cmp_gt_f32_e64 s[8:9], v103, v0
	v_cmp_gt_f32_e64 s[10:11], v103, v1
	v_cmp_gt_f32_e64 s[12:13], v103, v2
	v_addc_co_u32_e64 v97, vcc, 0, v97, s[8:9]
	v_cmp_gt_f32_e64 s[8:9], v103, v3
	v_addc_co_u32_e64 v96, vcc, 0, v96, s[10:11]
	v_cmp_gt_f32_e64 s[10:11], v103, v4
	v_addc_co_u32_e64 v95, vcc, 0, v95, s[12:13]
	v_cmp_gt_f32_e64 s[12:13], v103, v5
	v_addc_co_u32_e64 v94, vcc, 0, v94, s[8:9]
	v_cmp_ge_f32_e64 s[8:9], v103, v6
	v_addc_co_u32_e64 v93, vcc, 0, v93, s[10:11]
	v_cmp_ge_f32_e64 s[10:11], v103, v7
	v_addc_co_u32_e64 v92, vcc, 0, v92, s[12:13]
	v_cmp_ge_f32_e64 s[12:13], v103, v8
	v_addc_co_u32_e64 v91, vcc, 0, v91, s[8:9]
	v_cmp_ge_f32_e64 s[8:9], v103, v9
	v_addc_co_u32_e64 v90, vcc, 0, v90, s[10:11]
	v_cmp_ge_f32_e64 s[10:11], v103, v10
	v_addc_co_u32_e64 v89, vcc, 0, v89, s[12:13]
	v_cmp_ge_f32_e64 s[12:13], v103, v11
	v_addc_co_u32_e64 v88, vcc, 0, v88, s[8:9]
	v_cmp_ge_f32_e64 s[8:9], v103, v12
	v_addc_co_u32_e64 v87, vcc, 0, v87, s[10:11]
	v_cmp_ge_f32_e64 s[10:11], v103, v13
	v_addc_co_u32_e64 v86, vcc, 0, v86, s[12:13]
	v_cmp_ge_f32_e64 s[12:13], v103, v14
	v_addc_co_u32_e64 v85, vcc, 0, v85, s[8:9]
	v_cmp_ge_f32_e64 s[8:9], v103, v15
	v_addc_co_u32_e64 v84, vcc, 0, v84, s[10:11]
	v_cmp_ge_f32_e64 s[10:11], v103, v16
	v_addc_co_u32_e64 v83, vcc, 0, v83, s[12:13]
	v_cmp_ge_f32_e64 s[12:13], v103, v17
	v_addc_co_u32_e64 v81, vcc, 0, v81, s[8:9]
	v_cmp_ge_f32_e64 s[8:9], v103, v18
	v_addc_co_u32_e64 v79, vcc, 0, v79, s[10:11]
	v_cmp_ge_f32_e64 s[10:11], v103, v19
	v_addc_co_u32_e64 v78, vcc, 0, v78, s[12:13]
	v_cmp_ge_f32_e64 s[12:13], v103, v20
	v_addc_co_u32_e64 v77, vcc, 0, v77, s[8:9]
	v_cmp_ge_f32_e64 s[8:9], v103, v21
	v_addc_co_u32_e64 v76, vcc, 0, v76, s[10:11]
	v_cmp_ge_f32_e64 s[10:11], v103, v22
	v_addc_co_u32_e64 v75, vcc, 0, v75, s[12:13]
	v_cmp_ge_f32_e64 s[12:13], v103, v23
	v_addc_co_u32_e64 v74, vcc, 0, v74, s[8:9]
	v_cmp_ge_f32_e64 s[8:9], v103, v24
	v_addc_co_u32_e64 v73, vcc, 0, v73, s[10:11]
	v_cmp_ge_f32_e64 s[10:11], v103, v25
	v_addc_co_u32_e64 v72, vcc, 0, v72, s[12:13]
	v_cmp_ge_f32_e64 s[12:13], v103, v26
	v_addc_co_u32_e64 v71, vcc, 0, v71, s[8:9]
	v_cmp_ge_f32_e64 s[8:9], v103, v27
	v_addc_co_u32_e64 v70, vcc, 0, v70, s[10:11]
	v_cmp_ge_f32_e64 s[10:11], v103, v28
	v_addc_co_u32_e64 v69, vcc, 0, v69, s[12:13]
	v_cmp_ge_f32_e64 s[12:13], v103, v29
	v_addc_co_u32_e64 v68, vcc, 0, v68, s[8:9]
	v_cmp_ge_f32_e64 s[8:9], v103, v30
	v_addc_co_u32_e64 v67, vcc, 0, v67, s[10:11]
	v_cmp_ge_f32_e64 s[10:11], v103, v31
	v_addc_co_u32_e64 v66, vcc, 0, v66, s[12:13]
	s_nop 0
	v_addc_co_u32_e64 v65, vcc, 0, v65, s[8:9]
	v_addc_co_u32_e64 v64, vcc, 0, v64, s[10:11]
	s_cmp_le_u32 s14, 12
	s_cbranch_scc1 .Lrk_done
	ds_read2_b32 v[102:103], v104 offset0:14 offset1:15
	s_waitcnt lgkmcnt(1)
	v_cmp_gt_f32_e64 s[8:9], v100, v0
	v_cmp_gt_f32_e64 s[10:11], v100, v1
	v_cmp_gt_f32_e64 s[12:13], v100, v2
	v_addc_co_u32_e64 v97, vcc, 0, v97, s[8:9]
	v_cmp_gt_f32_e64 s[8:9], v100, v3
	v_addc_co_u32_e64 v96, vcc, 0, v96, s[10:11]
	v_cmp_gt_f32_e64 s[10:11], v100, v4
	v_addc_co_u32_e64 v95, vcc, 0, v95, s[12:13]
	v_cmp_gt_f32_e64 s[12:13], v100, v5
	v_addc_co_u32_e64 v94, vcc, 0, v94, s[8:9]
	v_cmp_ge_f32_e64 s[8:9], v100, v6
	v_addc_co_u32_e64 v93, vcc, 0, v93, s[10:11]
	v_cmp_ge_f32_e64 s[10:11], v100, v7
	v_addc_co_u32_e64 v92, vcc, 0, v92, s[12:13]
	v_cmp_ge_f32_e64 s[12:13], v100, v8
	s_and_b64 s[8:9], s[8:9], s[6:7]
	v_addc_co_u32_e64 v91, vcc, 0, v91, s[8:9]
	v_cmp_ge_f32_e64 s[8:9], v100, v9
	v_addc_co_u32_e64 v90, vcc, 0, v90, s[10:11]
	v_cmp_ge_f32_e64 s[10:11], v100, v10
	v_addc_co_u32_e64 v89, vcc, 0, v89, s[12:13]
	v_cmp_ge_f32_e64 s[12:13], v100, v11
	v_addc_co_u32_e64 v88, vcc, 0, v88, s[8:9]
	v_cmp_ge_f32_e64 s[8:9], v100, v12
	v_addc_co_u32_e64 v87, vcc, 0, v87, s[10:11]
	v_cmp_ge_f32_e64 s[10:11], v100, v13
	v_addc_co_u32_e64 v86, vcc, 0, v86, s[12:13]
	v_cmp_ge_f32_e64 s[12:13], v100, v14
	v_addc_co_u32_e64 v85, vcc, 0, v85, s[8:9]
	v_cmp_ge_f32_e64 s[8:9], v100, v15
	v_addc_co_u32_e64 v84, vcc, 0, v84, s[10:11]
	v_cmp_ge_f32_e64 s[10:11], v100, v16
	v_addc_co_u32_e64 v83, vcc, 0, v83, s[12:13]
	v_cmp_ge_f32_e64 s[12:13], v100, v17
	v_addc_co_u32_e64 v81, vcc, 0, v81, s[8:9]
	v_cmp_ge_f32_e64 s[8:9], v100, v18
	v_addc_co_u32_e64 v79, vcc, 0, v79, s[10:11]
	v_cmp_ge_f32_e64 s[10:11], v100, v19
	v_addc_co_u32_e64 v78, vcc, 0, v78, s[12:13]
	v_cmp_ge_f32_e64 s[12:13], v100, v20
	v_addc_co_u32_e64 v77, vcc, 0, v77, s[8:9]
	v_cmp_ge_f32_e64 s[8:9], v100, v21
	v_addc_co_u32_e64 v76, vcc, 0, v76, s[10:11]
	v_cmp_ge_f32_e64 s[10:11], v100, v22
	v_addc_co_u32_e64 v75, vcc, 0, v75, s[12:13]
	v_cmp_ge_f32_e64 s[12:13], v100, v23
	v_addc_co_u32_e64 v74, vcc, 0, v74, s[8:9]
	v_cmp_ge_f32_e64 s[8:9], v100, v24
	v_addc_co_u32_e64 v73, vcc, 0, v73, s[10:11]
	v_cmp_ge_f32_e64 s[10:11], v100, v25
	v_addc_co_u32_e64 v72, vcc, 0, v72, s[12:13]
	v_cmp_ge_f32_e64 s[12:13], v100, v26
	v_addc_co_u32_e64 v71, vcc, 0, v71, s[8:9]
	v_cmp_ge_f32_e64 s[8:9], v100, v27
	v_addc_co_u32_e64 v70, vcc, 0, v70, s[10:11]
	v_cmp_ge_f32_e64 s[10:11], v100, v28
	v_addc_co_u32_e64 v69, vcc, 0, v69, s[12:13]
	v_cmp_ge_f32_e64 s[12:13], v100, v29
	v_addc_co_u32_e64 v68, vcc, 0, v68, s[8:9]
	v_cmp_ge_f32_e64 s[8:9], v100, v30
	v_addc_co_u32_e64 v67, vcc, 0, v67, s[10:11]
	v_cmp_ge_f32_e64 s[10:11], v100, v31
	v_addc_co_u32_e64 v66, vcc, 0, v66, s[12:13]
	s_nop 0
	v_addc_co_u32_e64 v65, vcc, 0, v65, s[8:9]
	v_addc_co_u32_e64 v64, vcc, 0, v64, s[10:11]
	s_cmp_le_u32 s14, 13
	s_cbranch_scc1 .Lrk_done
; __device__ __forceinline__ void cmp_phase(LAS unsigned char* lds, const bf16_t* __restrict__ P, const bf16_t* __restrict__ Kc, const bf16_t* __restrict__ Vc,
;                                           bf16_t* __restrict__ ocmp, unsigned long long* __restrict__ mask, int G, const int wave0) {
;     ...
; #pragma nounroll
;             for (int k = 0; k < kmax; ++k) {
;                 const float sk = sc[k];
;                 const int kk = k - hi;
; #pragma unroll
;                 for (int i = 0; i < 32; ++i) rank[i] += ((sk > s[i]) || ((sk == s[i]) && (kk < 2 * i))) ? 1 : 0;
;             }
	v_cmp_gt_f32_e64 s[8:9], v101, v0
	v_cmp_gt_f32_e64 s[10:11], v101, v1
	v_cmp_gt_f32_e64 s[12:13], v101, v2
	v_addc_co_u32_e64 v97, vcc, 0, v97, s[8:9]
	v_cmp_gt_f32_e64 s[8:9], v101, v3
	v_addc_co_u32_e64 v96, vcc, 0, v96, s[10:11]
	v_cmp_gt_f32_e64 s[10:11], v101, v4
	v_addc_co_u32_e64 v95, vcc, 0, v95, s[12:13]
	v_cmp_gt_f32_e64 s[12:13], v101, v5
	v_addc_co_u32_e64 v94, vcc, 0, v94, s[8:9]
	v_cmp_gt_f32_e64 s[8:9], v101, v6
	v_addc_co_u32_e64 v93, vcc, 0, v93, s[10:11]
	v_cmp_ge_f32_e64 s[10:11], v101, v7
	v_addc_co_u32_e64 v92, vcc, 0, v92, s[12:13]
	v_cmp_ge_f32_e64 s[12:13], v101, v8
	v_addc_co_u32_e64 v91, vcc, 0, v91, s[8:9]
	v_cmp_ge_f32_e64 s[8:9], v101, v9
	v_addc_co_u32_e64 v90, vcc, 0, v90, s[10:11]
	v_cmp_ge_f32_e64 s[10:11], v101, v10
	v_addc_co_u32_e64 v89, vcc, 0, v89, s[12:13]
	v_cmp_ge_f32_e64 s[12:13], v101, v11
	v_addc_co_u32_e64 v88, vcc, 0, v88, s[8:9]
	v_cmp_ge_f32_e64 s[8:9], v101, v12
	v_addc_co_u32_e64 v87, vcc, 0, v87, s[10:11]
	v_cmp_ge_f32_e64 s[10:11], v101, v13
	v_addc_co_u32_e64 v86, vcc, 0, v86, s[12:13]
	v_cmp_ge_f32_e64 s[12:13], v101, v14
	v_addc_co_u32_e64 v85, vcc, 0, v85, s[8:9]
	v_cmp_ge_f32_e64 s[8:9], v101, v15
	v_addc_co_u32_e64 v84, vcc, 0, v84, s[10:11]
	v_cmp_ge_f32_e64 s[10:11], v101, v16
	v_addc_co_u32_e64 v83, vcc, 0, v83, s[12:13]
	v_cmp_ge_f32_e64 s[12:13], v101, v17
	v_addc_co_u32_e64 v81, vcc, 0, v81, s[8:9]
	v_cmp_ge_f32_e64 s[8:9], v101, v18
	v_addc_co_u32_e64 v79, vcc, 0, v79, s[10:11]
	v_cmp_ge_f32_e64 s[10:11], v101, v19
	v_addc_co_u32_e64 v78, vcc, 0, v78, s[12:13]
	v_cmp_ge_f32_e64 s[12:13], v101, v20
	v_addc_co_u32_e64 v77, vcc, 0, v77, s[8:9]
	v_cmp_ge_f32_e64 s[8:9], v101, v21
	v_addc_co_u32_e64 v76, vcc, 0, v76, s[10:11]
	v_cmp_ge_f32_e64 s[10:11], v101, v22
	v_addc_co_u32_e64 v75, vcc, 0, v75, s[12:13]
	v_cmp_ge_f32_e64 s[12:13], v101, v23
	v_addc_co_u32_e64 v74, vcc, 0, v74, s[8:9]
	v_cmp_ge_f32_e64 s[8:9], v101, v24
	v_addc_co_u32_e64 v73, vcc, 0, v73, s[10:11]
	v_cmp_ge_f32_e64 s[10:11], v101, v25
	v_addc_co_u32_e64 v72, vcc, 0, v72, s[12:13]
	v_cmp_ge_f32_e64 s[12:13], v101, v26
	v_addc_co_u32_e64 v71, vcc, 0, v71, s[8:9]
	v_cmp_ge_f32_e64 s[8:9], v101, v27
	v_addc_co_u32_e64 v70, vcc, 0, v70, s[10:11]
	v_cmp_ge_f32_e64 s[10:11], v101, v28
	v_addc_co_u32_e64 v69, vcc, 0, v69, s[12:13]
	v_cmp_ge_f32_e64 s[12:13], v101, v29
	v_addc_co_u32_e64 v68, vcc, 0, v68, s[8:9]
	v_cmp_ge_f32_e64 s[8:9], v101, v30
	v_addc_co_u32_e64 v67, vcc, 0, v67, s[10:11]
	v_cmp_ge_f32_e64 s[10:11], v101, v31
	v_addc_co_u32_e64 v66, vcc, 0, v66, s[12:13]
	s_nop 0
	v_addc_co_u32_e64 v65, vcc, 0, v65, s[8:9]
	v_addc_co_u32_e64 v64, vcc, 0, v64, s[10:11]
	s_cmp_le_u32 s14, 14
	s_cbranch_scc1 .Lrk_done
	ds_read2_b32 v[100:101], v104 offset0:16 offset1:17
	s_waitcnt lgkmcnt(1)
	v_cmp_gt_f32_e64 s[8:9], v102, v0
	v_cmp_gt_f32_e64 s[10:11], v102, v1
	v_cmp_gt_f32_e64 s[12:13], v102, v2
	v_addc_co_u32_e64 v97, vcc, 0, v97, s[8:9]
	v_cmp_gt_f32_e64 s[8:9], v102, v3
	v_addc_co_u32_e64 v96, vcc, 0, v96, s[10:11]
	v_cmp_gt_f32_e64 s[10:11], v102, v4
	v_addc_co_u32_e64 v95, vcc, 0, v95, s[12:13]
	v_cmp_gt_f32_e64 s[12:13], v102, v5
	v_addc_co_u32_e64 v94, vcc, 0, v94, s[8:9]
	v_cmp_gt_f32_e64 s[8:9], v102, v6
	v_addc_co_u32_e64 v93, vcc, 0, v93, s[10:11]
	v_cmp_ge_f32_e64 s[10:11], v102, v7
	v_addc_co_u32_e64 v92, vcc, 0, v92, s[12:13]
	v_cmp_ge_f32_e64 s[12:13], v102, v8
	v_addc_co_u32_e64 v91, vcc, 0, v91, s[8:9]
	v_cmp_ge_f32_e64 s[8:9], v102, v9
	s_and_b64 s[10:11], s[10:11], s[6:7]
	v_addc_co_u32_e64 v90, vcc, 0, v90, s[10:11]
	v_cmp_ge_f32_e64 s[10:11], v102, v10
	v_addc_co_u32_e64 v89, vcc, 0, v89, s[12:13]
	v_cmp_ge_f32_e64 s[12:13], v102, v11
	v_addc_co_u32_e64 v88, vcc, 0, v88, s[8:9]
	v_cmp_ge_f32_e64 s[8:9], v102, v12
	v_addc_co_u32_e64 v87, vcc, 0, v87, s[10:11]
	v_cmp_ge_f32_e64 s[10:11], v102, v13
	v_addc_co_u32_e64 v86, vcc, 0, v86, s[12:13]
	v_cmp_ge_f32_e64 s[12:13], v102, v14
	v_addc_co_u32_e64 v85, vcc, 0, v85, s[8:9]
	v_cmp_ge_f32_e64 s[8:9], v102, v15
	v_addc_co_u32_e64 v84, vcc, 0, v84, s[10:11]
	v_cmp_ge_f32_e64 s[10:11], v102, v16
	v_addc_co_u32_e64 v83, vcc, 0, v83, s[12:13]
	v_cmp_ge_f32_e64 s[12:13], v102, v17
	v_addc_co_u32_e64 v81, vcc, 0, v81, s[8:9]
	v_cmp_ge_f32_e64 s[8:9], v102, v18
	v_addc_co_u32_e64 v79, vcc, 0, v79, s[10:11]
	v_cmp_ge_f32_e64 s[10:11], v102, v19
	v_addc_co_u32_e64 v78, vcc, 0, v78, s[12:13]
	v_cmp_ge_f32_e64 s[12:13], v102, v20
	v_addc_co_u32_e64 v77, vcc, 0, v77, s[8:9]
	v_cmp_ge_f32_e64 s[8:9], v102, v21
	v_addc_co_u32_e64 v76, vcc, 0, v76, s[10:11]
	v_cmp_ge_f32_e64 s[10:11], v102, v22
	v_addc_co_u32_e64 v75, vcc, 0, v75, s[12:13]
	v_cmp_ge_f32_e64 s[12:13], v102, v23
	v_addc_co_u32_e64 v74, vcc, 0, v74, s[8:9]
	v_cmp_ge_f32_e64 s[8:9], v102, v24
	v_addc_co_u32_e64 v73, vcc, 0, v73, s[10:11]
	v_cmp_ge_f32_e64 s[10:11], v102, v25
	v_addc_co_u32_e64 v72, vcc, 0, v72, s[12:13]
	v_cmp_ge_f32_e64 s[12:13], v102, v26
	v_addc_co_u32_e64 v71, vcc, 0, v71, s[8:9]
	v_cmp_ge_f32_e64 s[8:9], v102, v27
	v_addc_co_u32_e64 v70, vcc, 0, v70, s[10:11]
	v_cmp_ge_f32_e64 s[10:11], v102, v28
	v_addc_co_u32_e64 v69, vcc, 0, v69, s[12:13]
	v_cmp_ge_f32_e64 s[12:13], v102, v29
	v_addc_co_u32_e64 v68, vcc, 0, v68, s[8:9]
	v_cmp_ge_f32_e64 s[8:9], v102, v30
	v_addc_co_u32_e64 v67, vcc, 0, v67, s[10:11]
	v_cmp_ge_f32_e64 s[10:11], v102, v31
	v_addc_co_u32_e64 v66, vcc, 0, v66, s[12:13]
	s_nop 0
	v_addc_co_u32_e64 v65, vcc, 0, v65, s[8:9]
	v_addc_co_u32_e64 v64, vcc, 0, v64, s[10:11]
	s_cmp_le_u32 s14, 15
	s_cbranch_scc1 .Lrk_done
; __device__ __forceinline__ void cmp_phase(LAS unsigned char* lds, const bf16_t* __restrict__ P, const bf16_t* __restrict__ Kc, const bf16_t* __restrict__ Vc,
;                                           bf16_t* __restrict__ ocmp, unsigned long long* __restrict__ mask, int G, const int wave0) {
;     ...
; #pragma nounroll
;             for (int k = 0; k < kmax; ++k) {
;                 const float sk = sc[k];
;                 const int kk = k - hi;
; #pragma unroll
;                 for (int i = 0; i < 32; ++i) rank[i] += ((sk > s[i]) || ((sk == s[i]) && (kk < 2 * i))) ? 1 : 0;
;             }
	v_cmp_gt_f32_e64 s[8:9], v103, v0
	v_cmp_gt_f32_e64 s[10:11], v103, v1
	v_cmp_gt_f32_e64 s[12:13], v103, v2
	v_addc_co_u32_e64 v97, vcc, 0, v97, s[8:9]
	v_cmp_gt_f32_e64 s[8:9], v103, v3
	v_addc_co_u32_e64 v96, vcc, 0, v96, s[10:11]
	v_cmp_gt_f32_e64 s[10:11], v103, v4
	v_addc_co_u32_e64 v95, vcc, 0, v95, s[12:13]
	v_cmp_gt_f32_e64 s[12:13], v103, v5
	v_addc_co_u32_e64 v94, vcc, 0, v94, s[8:9]
	v_cmp_gt_f32_e64 s[8:9], v103, v6
	v_addc_co_u32_e64 v93, vcc, 0, v93, s[10:11]
	v_cmp_gt_f32_e64 s[10:11], v103, v7
	v_addc_co_u32_e64 v92, vcc, 0, v92, s[12:13]
	v_cmp_ge_f32_e64 s[12:13], v103, v8
	v_addc_co_u32_e64 v91, vcc, 0, v91, s[8:9]
	v_cmp_ge_f32_e64 s[8:9], v103, v9
	v_addc_co_u32_e64 v90, vcc, 0, v90, s[10:11]
	v_cmp_ge_f32_e64 s[10:11], v103, v10
	v_addc_co_u32_e64 v89, vcc, 0, v89, s[12:13]
	v_cmp_ge_f32_e64 s[12:13], v103, v11
	v_addc_co_u32_e64 v88, vcc, 0, v88, s[8:9]
	v_cmp_ge_f32_e64 s[8:9], v103, v12
	v_addc_co_u32_e64 v87, vcc, 0, v87, s[10:11]
	v_cmp_ge_f32_e64 s[10:11], v103, v13
	v_addc_co_u32_e64 v86, vcc, 0, v86, s[12:13]
	v_cmp_ge_f32_e64 s[12:13], v103, v14
	v_addc_co_u32_e64 v85, vcc, 0, v85, s[8:9]
	v_cmp_ge_f32_e64 s[8:9], v103, v15
	v_addc_co_u32_e64 v84, vcc, 0, v84, s[10:11]
	v_cmp_ge_f32_e64 s[10:11], v103, v16
	v_addc_co_u32_e64 v83, vcc, 0, v83, s[12:13]
	v_cmp_ge_f32_e64 s[12:13], v103, v17
	v_addc_co_u32_e64 v81, vcc, 0, v81, s[8:9]
	v_cmp_ge_f32_e64 s[8:9], v103, v18
	v_addc_co_u32_e64 v79, vcc, 0, v79, s[10:11]
	v_cmp_ge_f32_e64 s[10:11], v103, v19
	v_addc_co_u32_e64 v78, vcc, 0, v78, s[12:13]
	v_cmp_ge_f32_e64 s[12:13], v103, v20
	v_addc_co_u32_e64 v77, vcc, 0, v77, s[8:9]
	v_cmp_ge_f32_e64 s[8:9], v103, v21
	v_addc_co_u32_e64 v76, vcc, 0, v76, s[10:11]
	v_cmp_ge_f32_e64 s[10:11], v103, v22
	v_addc_co_u32_e64 v75, vcc, 0, v75, s[12:13]
	v_cmp_ge_f32_e64 s[12:13], v103, v23
	v_addc_co_u32_e64 v74, vcc, 0, v74, s[8:9]
	v_cmp_ge_f32_e64 s[8:9], v103, v24
	v_addc_co_u32_e64 v73, vcc, 0, v73, s[10:11]
	v_cmp_ge_f32_e64 s[10:11], v103, v25
	v_addc_co_u32_e64 v72, vcc, 0, v72, s[12:13]
	v_cmp_ge_f32_e64 s[12:13], v103, v26
	v_addc_co_u32_e64 v71, vcc, 0, v71, s[8:9]
	v_cmp_ge_f32_e64 s[8:9], v103, v27
	v_addc_co_u32_e64 v70, vcc, 0, v70, s[10:11]
	v_cmp_ge_f32_e64 s[10:11], v103, v28
	v_addc_co_u32_e64 v69, vcc, 0, v69, s[12:13]
	v_cmp_ge_f32_e64 s[12:13], v103, v29
	v_addc_co_u32_e64 v68, vcc, 0, v68, s[8:9]
	v_cmp_ge_f32_e64 s[8:9], v103, v30
	v_addc_co_u32_e64 v67, vcc, 0, v67, s[10:11]
	v_cmp_ge_f32_e64 s[10:11], v103, v31
	v_addc_co_u32_e64 v66, vcc, 0, v66, s[12:13]
	s_nop 0
	v_addc_co_u32_e64 v65, vcc, 0, v65, s[8:9]
	v_addc_co_u32_e64 v64, vcc, 0, v64, s[10:11]
	s_cmp_le_u32 s14, 16
	s_cbranch_scc1 .Lrk_done
	ds_read2_b32 v[102:103], v104 offset0:18 offset1:19
	s_waitcnt lgkmcnt(1)
	v_cmp_gt_f32_e64 s[8:9], v100, v0
	v_cmp_gt_f32_e64 s[10:11], v100, v1
	v_cmp_gt_f32_e64 s[12:13], v100, v2
	v_addc_co_u32_e64 v97, vcc, 0, v97, s[8:9]
	v_cmp_gt_f32_e64 s[8:9], v100, v3
	v_addc_co_u32_e64 v96, vcc, 0, v96, s[10:11]
	v_cmp_gt_f32_e64 s[10:11], v100, v4
	v_addc_co_u32_e64 v95, vcc, 0, v95, s[12:13]
	v_cmp_gt_f32_e64 s[12:13], v100, v5
	v_addc_co_u32_e64 v94, vcc, 0, v94, s[8:9]
	v_cmp_gt_f32_e64 s[8:9], v100, v6
	v_addc_co_u32_e64 v93, vcc, 0, v93, s[10:11]
	v_cmp_gt_f32_e64 s[10:11], v100, v7
	v_addc_co_u32_e64 v92, vcc, 0, v92, s[12:13]
	v_cmp_ge_f32_e64 s[12:13], v100, v8
	v_addc_co_u32_e64 v91, vcc, 0, v91, s[8:9]
	v_cmp_ge_f32_e64 s[8:9], v100, v9
	v_addc_co_u32_e64 v90, vcc, 0, v90, s[10:11]
	v_cmp_ge_f32_e64 s[10:11], v100, v10
	s_and_b64 s[12:13], s[12:13], s[6:7]
	v_addc_co_u32_e64 v89, vcc, 0, v89, s[12:13]
	v_cmp_ge_f32_e64 s[12:13], v100, v11
	v_addc_co_u32_e64 v88, vcc, 0, v88, s[8:9]
	v_cmp_ge_f32_e64 s[8:9], v100, v12
	v_addc_co_u32_e64 v87, vcc, 0, v87, s[10:11]
	v_cmp_ge_f32_e64 s[10:11], v100, v13
	v_addc_co_u32_e64 v86, vcc, 0, v86, s[12:13]
	v_cmp_ge_f32_e64 s[12:13], v100, v14
	v_addc_co_u32_e64 v85, vcc, 0, v85, s[8:9]
	v_cmp_ge_f32_e64 s[8:9], v100, v15
	v_addc_co_u32_e64 v84, vcc, 0, v84, s[10:11]
	v_cmp_ge_f32_e64 s[10:11], v100, v16
	v_addc_co_u32_e64 v83, vcc, 0, v83, s[12:13]
	v_cmp_ge_f32_e64 s[12:13], v100, v17
	v_addc_co_u32_e64 v81, vcc, 0, v81, s[8:9]
	v_cmp_ge_f32_e64 s[8:9], v100, v18
	v_addc_co_u32_e64 v79, vcc, 0, v79, s[10:11]
	v_cmp_ge_f32_e64 s[10:11], v100, v19
	v_addc_co_u32_e64 v78, vcc, 0, v78, s[12:13]
	v_cmp_ge_f32_e64 s[12:13], v100, v20
	v_addc_co_u32_e64 v77, vcc, 0, v77, s[8:9]
	v_cmp_ge_f32_e64 s[8:9], v100, v21
	v_addc_co_u32_e64 v76, vcc, 0, v76, s[10:11]
	v_cmp_ge_f32_e64 s[10:11], v100, v22
	v_addc_co_u32_e64 v75, vcc, 0, v75, s[12:13]
	v_cmp_ge_f32_e64 s[12:13], v100, v23
	v_addc_co_u32_e64 v74, vcc, 0, v74, s[8:9]
	v_cmp_ge_f32_e64 s[8:9], v100, v24
	v_addc_co_u32_e64 v73, vcc, 0, v73, s[10:11]
	v_cmp_ge_f32_e64 s[10:11], v100, v25
	v_addc_co_u32_e64 v72, vcc, 0, v72, s[12:13]
	v_cmp_ge_f32_e64 s[12:13], v100, v26
	v_addc_co_u32_e64 v71, vcc, 0, v71, s[8:9]
	v_cmp_ge_f32_e64 s[8:9], v100, v27
	v_addc_co_u32_e64 v70, vcc, 0, v70, s[10:11]
	v_cmp_ge_f32_e64 s[10:11], v100, v28
	v_addc_co_u32_e64 v69, vcc, 0, v69, s[12:13]
	v_cmp_ge_f32_e64 s[12:13], v100, v29
	v_addc_co_u32_e64 v68, vcc, 0, v68, s[8:9]
	v_cmp_ge_f32_e64 s[8:9], v100, v30
	v_addc_co_u32_e64 v67, vcc, 0, v67, s[10:11]
	v_cmp_ge_f32_e64 s[10:11], v100, v31
	v_addc_co_u32_e64 v66, vcc, 0, v66, s[12:13]
	s_nop 0
	v_addc_co_u32_e64 v65, vcc, 0, v65, s[8:9]
	v_addc_co_u32_e64 v64, vcc, 0, v64, s[10:11]
	s_cmp_le_u32 s14, 17
	s_cbranch_scc1 .Lrk_done
; __device__ __forceinline__ void cmp_phase(LAS unsigned char* lds, const bf16_t* __restrict__ P, const bf16_t* __restrict__ Kc, const bf16_t* __restrict__ Vc,
;                                           bf16_t* __restrict__ ocmp, unsigned long long* __restrict__ mask, int G, const int wave0) {
;     ...
; #pragma nounroll
;             for (int k = 0; k < kmax; ++k) {
;                 const float sk = sc[k];
;                 const int kk = k - hi;
; #pragma unroll
;                 for (int i = 0; i < 32; ++i) rank[i] += ((sk > s[i]) || ((sk == s[i]) && (kk < 2 * i))) ? 1 : 0;
;             }
	v_cmp_gt_f32_e64 s[8:9], v101, v0
	v_cmp_gt_f32_e64 s[10:11], v101, v1
	v_cmp_gt_f32_e64 s[12:13], v101, v2
	v_addc_co_u32_e64 v97, vcc, 0, v97, s[8:9]
	v_cmp_gt_f32_e64 s[8:9], v101, v3
	v_addc_co_u32_e64 v96, vcc, 0, v96, s[10:11]
	v_cmp_gt_f32_e64 s[10:11], v101, v4
	v_addc_co_u32_e64 v95, vcc, 0, v95, s[12:13]
	v_cmp_gt_f32_e64 s[12:13], v101, v5
	v_addc_co_u32_e64 v94, vcc, 0, v94, s[8:9]
	v_cmp_gt_f32_e64 s[8:9], v101, v6
	v_addc_co_u32_e64 v93, vcc, 0, v93, s[10:11]
	v_cmp_gt_f32_e64 s[10:11], v101, v7
	v_addc_co_u32_e64 v92, vcc, 0, v92, s[12:13]
	v_cmp_gt_f32_e64 s[12:13], v101, v8
	v_addc_co_u32_e64 v91, vcc, 0, v91, s[8:9]
	v_cmp_ge_f32_e64 s[8:9], v101, v9
	v_addc_co_u32_e64 v90, vcc, 0, v90, s[10:11]
	v_cmp_ge_f32_e64 s[10:11], v101, v10
	v_addc_co_u32_e64 v89, vcc, 0, v89, s[12:13]
	v_cmp_ge_f32_e64 s[12:13], v101, v11
	v_addc_co_u32_e64 v88, vcc, 0, v88, s[8:9]
	v_cmp_ge_f32_e64 s[8:9], v101, v12
	v_addc_co_u32_e64 v87, vcc, 0, v87, s[10:11]
	v_cmp_ge_f32_e64 s[10:11], v101, v13
	v_addc_co_u32_e64 v86, vcc, 0, v86, s[12:13]
	v_cmp_ge_f32_e64 s[12:13], v101, v14
	v_addc_co_u32_e64 v85, vcc, 0, v85, s[8:9]
	v_cmp_ge_f32_e64 s[8:9], v101, v15
	v_addc_co_u32_e64 v84, vcc, 0, v84, s[10:11]
	v_cmp_ge_f32_e64 s[10:11], v101, v16
	v_addc_co_u32_e64 v83, vcc, 0, v83, s[12:13]
	v_cmp_ge_f32_e64 s[12:13], v101, v17
	v_addc_co_u32_e64 v81, vcc, 0, v81, s[8:9]
	v_cmp_ge_f32_e64 s[8:9], v101, v18
	v_addc_co_u32_e64 v79, vcc, 0, v79, s[10:11]
	v_cmp_ge_f32_e64 s[10:11], v101, v19
	v_addc_co_u32_e64 v78, vcc, 0, v78, s[12:13]
	v_cmp_ge_f32_e64 s[12:13], v101, v20
	v_addc_co_u32_e64 v77, vcc, 0, v77, s[8:9]
	v_cmp_ge_f32_e64 s[8:9], v101, v21
	v_addc_co_u32_e64 v76, vcc, 0, v76, s[10:11]
	v_cmp_ge_f32_e64 s[10:11], v101, v22
	v_addc_co_u32_e64 v75, vcc, 0, v75, s[12:13]
	v_cmp_ge_f32_e64 s[12:13], v101, v23
	v_addc_co_u32_e64 v74, vcc, 0, v74, s[8:9]
	v_cmp_ge_f32_e64 s[8:9], v101, v24
	v_addc_co_u32_e64 v73, vcc, 0, v73, s[10:11]
	v_cmp_ge_f32_e64 s[10:11], v101, v25
	v_addc_co_u32_e64 v72, vcc, 0, v72, s[12:13]
	v_cmp_ge_f32_e64 s[12:13], v101, v26
	v_addc_co_u32_e64 v71, vcc, 0, v71, s[8:9]
	v_cmp_ge_f32_e64 s[8:9], v101, v27
	v_addc_co_u32_e64 v70, vcc, 0, v70, s[10:11]
	v_cmp_ge_f32_e64 s[10:11], v101, v28
	v_addc_co_u32_e64 v69, vcc, 0, v69, s[12:13]
	v_cmp_ge_f32_e64 s[12:13], v101, v29
	v_addc_co_u32_e64 v68, vcc, 0, v68, s[8:9]
	v_cmp_ge_f32_e64 s[8:9], v101, v30
	v_addc_co_u32_e64 v67, vcc, 0, v67, s[10:11]
	v_cmp_ge_f32_e64 s[10:11], v101, v31
	v_addc_co_u32_e64 v66, vcc, 0, v66, s[12:13]
	s_nop 0
	v_addc_co_u32_e64 v65, vcc, 0, v65, s[8:9]
	v_addc_co_u32_e64 v64, vcc, 0, v64, s[10:11]
	s_cmp_le_u32 s14, 18
	s_cbranch_scc1 .Lrk_done
	ds_read2_b32 v[100:101], v104 offset0:20 offset1:21
	s_waitcnt lgkmcnt(1)
	v_cmp_gt_f32_e64 s[8:9], v102, v0
	v_cmp_gt_f32_e64 s[10:11], v102, v1
	v_cmp_gt_f32_e64 s[12:13], v102, v2
	v_addc_co_u32_e64 v97, vcc, 0, v97, s[8:9]
	v_cmp_gt_f32_e64 s[8:9], v102, v3
	v_addc_co_u32_e64 v96, vcc, 0, v96, s[10:11]
	v_cmp_gt_f32_e64 s[10:11], v102, v4
	v_addc_co_u32_e64 v95, vcc, 0, v95, s[12:13]
	v_cmp_gt_f32_e64 s[12:13], v102, v5
	v_addc_co_u32_e64 v94, vcc, 0, v94, s[8:9]
	v_cmp_gt_f32_e64 s[8:9], v102, v6
	v_addc_co_u32_e64 v93, vcc, 0, v93, s[10:11]
	v_cmp_gt_f32_e64 s[10:11], v102, v7
	v_addc_co_u32_e64 v92, vcc, 0, v92, s[12:13]
	v_cmp_gt_f32_e64 s[12:13], v102, v8
	v_addc_co_u32_e64 v91, vcc, 0, v91, s[8:9]
	v_cmp_ge_f32_e64 s[8:9], v102, v9
	v_addc_co_u32_e64 v90, vcc, 0, v90, s[10:11]
	v_cmp_ge_f32_e64 s[10:11], v102, v10
	v_addc_co_u32_e64 v89, vcc, 0, v89, s[12:13]
	v_cmp_ge_f32_e64 s[12:13], v102, v11
	s_and_b64 s[8:9], s[8:9], s[6:7]
	v_addc_co_u32_e64 v88, vcc, 0, v88, s[8:9]
	v_cmp_ge_f32_e64 s[8:9], v102, v12
	v_addc_co_u32_e64 v87, vcc, 0, v87, s[10:11]
	v_cmp_ge_f32_e64 s[10:11], v102, v13
	v_addc_co_u32_e64 v86, vcc, 0, v86, s[12:13]
	v_cmp_ge_f32_e64 s[12:13], v102, v14
	v_addc_co_u32_e64 v85, vcc, 0, v85, s[8:9]
	v_cmp_ge_f32_e64 s[8:9], v102, v15
	v_addc_co_u32_e64 v84, vcc, 0, v84, s[10:11]
	v_cmp_ge_f32_e64 s[10:11], v102, v16
	v_addc_co_u32_e64 v83, vcc, 0, v83, s[12:13]
	v_cmp_ge_f32_e64 s[12:13], v102, v17
	v_addc_co_u32_e64 v81, vcc, 0, v81, s[8:9]
	v_cmp_ge_f32_e64 s[8:9], v102, v18
	v_addc_co_u32_e64 v79, vcc, 0, v79, s[10:11]
	v_cmp_ge_f32_e64 s[10:11], v102, v19
	v_addc_co_u32_e64 v78, vcc, 0, v78, s[12:13]
	v_cmp_ge_f32_e64 s[12:13], v102, v20
	v_addc_co_u32_e64 v77, vcc, 0, v77, s[8:9]
	v_cmp_ge_f32_e64 s[8:9], v102, v21
	v_addc_co_u32_e64 v76, vcc, 0, v76, s[10:11]
	v_cmp_ge_f32_e64 s[10:11], v102, v22
	v_addc_co_u32_e64 v75, vcc, 0, v75, s[12:13]
	v_cmp_ge_f32_e64 s[12:13], v102, v23
	v_addc_co_u32_e64 v74, vcc, 0, v74, s[8:9]
	v_cmp_ge_f32_e64 s[8:9], v102, v24
	v_addc_co_u32_e64 v73, vcc, 0, v73, s[10:11]
	v_cmp_ge_f32_e64 s[10:11], v102, v25
	v_addc_co_u32_e64 v72, vcc, 0, v72, s[12:13]
	v_cmp_ge_f32_e64 s[12:13], v102, v26
	v_addc_co_u32_e64 v71, vcc, 0, v71, s[8:9]
	v_cmp_ge_f32_e64 s[8:9], v102, v27
	v_addc_co_u32_e64 v70, vcc, 0, v70, s[10:11]
	v_cmp_ge_f32_e64 s[10:11], v102, v28
	v_addc_co_u32_e64 v69, vcc, 0, v69, s[12:13]
	v_cmp_ge_f32_e64 s[12:13], v102, v29
	v_addc_co_u32_e64 v68, vcc, 0, v68, s[8:9]
	v_cmp_ge_f32_e64 s[8:9], v102, v30
	v_addc_co_u32_e64 v67, vcc, 0, v67, s[10:11]
	v_cmp_ge_f32_e64 s[10:11], v102, v31
	v_addc_co_u32_e64 v66, vcc, 0, v66, s[12:13]
	s_nop 0
	v_addc_co_u32_e64 v65, vcc, 0, v65, s[8:9]
	v_addc_co_u32_e64 v64, vcc, 0, v64, s[10:11]
	s_cmp_le_u32 s14, 19
	s_cbranch_scc1 .Lrk_done
; __device__ __forceinline__ void cmp_phase(LAS unsigned char* lds, const bf16_t* __restrict__ P, const bf16_t* __restrict__ Kc, const bf16_t* __restrict__ Vc,
;                                           bf16_t* __restrict__ ocmp, unsigned long long* __restrict__ mask, int G, const int wave0) {
;     ...
; #pragma nounroll
;             for (int k = 0; k < kmax; ++k) {
;                 const float sk = sc[k];
;                 const int kk = k - hi;
; #pragma unroll
;                 for (int i = 0; i < 32; ++i) rank[i] += ((sk > s[i]) || ((sk == s[i]) && (kk < 2 * i))) ? 1 : 0;
;             }
	v_cmp_gt_f32_e64 s[8:9], v103, v0
	v_cmp_gt_f32_e64 s[10:11], v103, v1
	v_cmp_gt_f32_e64 s[12:13], v103, v2
	v_addc_co_u32_e64 v97, vcc, 0, v97, s[8:9]
	v_cmp_gt_f32_e64 s[8:9], v103, v3
	v_addc_co_u32_e64 v96, vcc, 0, v96, s[10:11]
	v_cmp_gt_f32_e64 s[10:11], v103, v4
	v_addc_co_u32_e64 v95, vcc, 0, v95, s[12:13]
	v_cmp_gt_f32_e64 s[12:13], v103, v5
	v_addc_co_u32_e64 v94, vcc, 0, v94, s[8:9]
	v_cmp_gt_f32_e64 s[8:9], v103, v6
	v_addc_co_u32_e64 v93, vcc, 0, v93, s[10:11]
	v_cmp_gt_f32_e64 s[10:11], v103, v7
	v_addc_co_u32_e64 v92, vcc, 0, v92, s[12:13]
	v_cmp_gt_f32_e64 s[12:13], v103, v8
	v_addc_co_u32_e64 v91, vcc, 0, v91, s[8:9]
	v_cmp_gt_f32_e64 s[8:9], v103, v9
	v_addc_co_u32_e64 v90, vcc, 0, v90, s[10:11]
	v_cmp_ge_f32_e64 s[10:11], v103, v10
	v_addc_co_u32_e64 v89, vcc, 0, v89, s[12:13]
	v_cmp_ge_f32_e64 s[12:13], v103, v11
	v_addc_co_u32_e64 v88, vcc, 0, v88, s[8:9]
	v_cmp_ge_f32_e64 s[8:9], v103, v12
	v_addc_co_u32_e64 v87, vcc, 0, v87, s[10:11]
	v_cmp_ge_f32_e64 s[10:11], v103, v13
	v_addc_co_u32_e64 v86, vcc, 0, v86, s[12:13]
	v_cmp_ge_f32_e64 s[12:13], v103, v14
	v_addc_co_u32_e64 v85, vcc, 0, v85, s[8:9]
	v_cmp_ge_f32_e64 s[8:9], v103, v15
	v_addc_co_u32_e64 v84, vcc, 0, v84, s[10:11]
	v_cmp_ge_f32_e64 s[10:11], v103, v16
	v_addc_co_u32_e64 v83, vcc, 0, v83, s[12:13]
	v_cmp_ge_f32_e64 s[12:13], v103, v17
	v_addc_co_u32_e64 v81, vcc, 0, v81, s[8:9]
	v_cmp_ge_f32_e64 s[8:9], v103, v18
	v_addc_co_u32_e64 v79, vcc, 0, v79, s[10:11]
	v_cmp_ge_f32_e64 s[10:11], v103, v19
	v_addc_co_u32_e64 v78, vcc, 0, v78, s[12:13]
	v_cmp_ge_f32_e64 s[12:13], v103, v20
	v_addc_co_u32_e64 v77, vcc, 0, v77, s[8:9]
	v_cmp_ge_f32_e64 s[8:9], v103, v21
	v_addc_co_u32_e64 v76, vcc, 0, v76, s[10:11]
	v_cmp_ge_f32_e64 s[10:11], v103, v22
	v_addc_co_u32_e64 v75, vcc, 0, v75, s[12:13]
	v_cmp_ge_f32_e64 s[12:13], v103, v23
	v_addc_co_u32_e64 v74, vcc, 0, v74, s[8:9]
	v_cmp_ge_f32_e64 s[8:9], v103, v24
	v_addc_co_u32_e64 v73, vcc, 0, v73, s[10:11]
	v_cmp_ge_f32_e64 s[10:11], v103, v25
	v_addc_co_u32_e64 v72, vcc, 0, v72, s[12:13]
	v_cmp_ge_f32_e64 s[12:13], v103, v26
	v_addc_co_u32_e64 v71, vcc, 0, v71, s[8:9]
	v_cmp_ge_f32_e64 s[8:9], v103, v27
	v_addc_co_u32_e64 v70, vcc, 0, v70, s[10:11]
	v_cmp_ge_f32_e64 s[10:11], v103, v28
	v_addc_co_u32_e64 v69, vcc, 0, v69, s[12:13]
	v_cmp_ge_f32_e64 s[12:13], v103, v29
	v_addc_co_u32_e64 v68, vcc, 0, v68, s[8:9]
	v_cmp_ge_f32_e64 s[8:9], v103, v30
	v_addc_co_u32_e64 v67, vcc, 0, v67, s[10:11]
	v_cmp_ge_f32_e64 s[10:11], v103, v31
	v_addc_co_u32_e64 v66, vcc, 0, v66, s[12:13]
	s_nop 0
	v_addc_co_u32_e64 v65, vcc, 0, v65, s[8:9]
	v_addc_co_u32_e64 v64, vcc, 0, v64, s[10:11]
	s_cmp_le_u32 s14, 20
	s_cbranch_scc1 .Lrk_done
	ds_read2_b32 v[102:103], v104 offset0:22 offset1:23
	s_waitcnt lgkmcnt(1)
	v_cmp_gt_f32_e64 s[8:9], v100, v0
	v_cmp_gt_f32_e64 s[10:11], v100, v1
	v_cmp_gt_f32_e64 s[12:13], v100, v2
	v_addc_co_u32_e64 v97, vcc, 0, v97, s[8:9]
	v_cmp_gt_f32_e64 s[8:9], v100, v3
	v_addc_co_u32_e64 v96, vcc, 0, v96, s[10:11]
	v_cmp_gt_f32_e64 s[10:11], v100, v4
	v_addc_co_u32_e64 v95, vcc, 0, v95, s[12:13]
	v_cmp_gt_f32_e64 s[12:13], v100, v5
	v_addc_co_u32_e64 v94, vcc, 0, v94, s[8:9]
	v_cmp_gt_f32_e64 s[8:9], v100, v6
	v_addc_co_u32_e64 v93, vcc, 0, v93, s[10:11]
	v_cmp_gt_f32_e64 s[10:11], v100, v7
	v_addc_co_u32_e64 v92, vcc, 0, v92, s[12:13]
	v_cmp_gt_f32_e64 s[12:13], v100, v8
	v_addc_co_u32_e64 v91, vcc, 0, v91, s[8:9]
	v_cmp_gt_f32_e64 s[8:9], v100, v9
	v_addc_co_u32_e64 v90, vcc, 0, v90, s[10:11]
	v_cmp_ge_f32_e64 s[10:11], v100, v10
	v_addc_co_u32_e64 v89, vcc, 0, v89, s[12:13]
	v_cmp_ge_f32_e64 s[12:13], v100, v11
	v_addc_co_u32_e64 v88, vcc, 0, v88, s[8:9]
	v_cmp_ge_f32_e64 s[8:9], v100, v12
	s_and_b64 s[10:11], s[10:11], s[6:7]
	v_addc_co_u32_e64 v87, vcc, 0, v87, s[10:11]
	v_cmp_ge_f32_e64 s[10:11], v100, v13
	v_addc_co_u32_e64 v86, vcc, 0, v86, s[12:13]
	v_cmp_ge_f32_e64 s[12:13], v100, v14
	v_addc_co_u32_e64 v85, vcc, 0, v85, s[8:9]
	v_cmp_ge_f32_e64 s[8:9], v100, v15
	v_addc_co_u32_e64 v84, vcc, 0, v84, s[10:11]
	v_cmp_ge_f32_e64 s[10:11], v100, v16
	v_addc_co_u32_e64 v83, vcc, 0, v83, s[12:13]
	v_cmp_ge_f32_e64 s[12:13], v100, v17
	v_addc_co_u32_e64 v81, vcc, 0, v81, s[8:9]
	v_cmp_ge_f32_e64 s[8:9], v100, v18
	v_addc_co_u32_e64 v79, vcc, 0, v79, s[10:11]
	v_cmp_ge_f32_e64 s[10:11], v100, v19
	v_addc_co_u32_e64 v78, vcc, 0, v78, s[12:13]
	v_cmp_ge_f32_e64 s[12:13], v100, v20
	v_addc_co_u32_e64 v77, vcc, 0, v77, s[8:9]
	v_cmp_ge_f32_e64 s[8:9], v100, v21
	v_addc_co_u32_e64 v76, vcc, 0, v76, s[10:11]
	v_cmp_ge_f32_e64 s[10:11], v100, v22
	v_addc_co_u32_e64 v75, vcc, 0, v75, s[12:13]
	v_cmp_ge_f32_e64 s[12:13], v100, v23
	v_addc_co_u32_e64 v74, vcc, 0, v74, s[8:9]
	v_cmp_ge_f32_e64 s[8:9], v100, v24
	v_addc_co_u32_e64 v73, vcc, 0, v73, s[10:11]
	v_cmp_ge_f32_e64 s[10:11], v100, v25
	v_addc_co_u32_e64 v72, vcc, 0, v72, s[12:13]
	v_cmp_ge_f32_e64 s[12:13], v100, v26
	v_addc_co_u32_e64 v71, vcc, 0, v71, s[8:9]
	v_cmp_ge_f32_e64 s[8:9], v100, v27
	v_addc_co_u32_e64 v70, vcc, 0, v70, s[10:11]
	v_cmp_ge_f32_e64 s[10:11], v100, v28
	v_addc_co_u32_e64 v69, vcc, 0, v69, s[12:13]
	v_cmp_ge_f32_e64 s[12:13], v100, v29
	v_addc_co_u32_e64 v68, vcc, 0, v68, s[8:9]
	v_cmp_ge_f32_e64 s[8:9], v100, v30
	v_addc_co_u32_e64 v67, vcc, 0, v67, s[10:11]
	v_cmp_ge_f32_e64 s[10:11], v100, v31
	v_addc_co_u32_e64 v66, vcc, 0, v66, s[12:13]
	s_nop 0
	v_addc_co_u32_e64 v65, vcc, 0, v65, s[8:9]
	v_addc_co_u32_e64 v64, vcc, 0, v64, s[10:11]
	s_cmp_le_u32 s14, 21
	s_cbranch_scc1 .Lrk_done
; __device__ __forceinline__ void cmp_phase(LAS unsigned char* lds, const bf16_t* __restrict__ P, const bf16_t* __restrict__ Kc, const bf16_t* __restrict__ Vc,
;                                           bf16_t* __restrict__ ocmp, unsigned long long* __restrict__ mask, int G, const int wave0) {
;     ...
; #pragma nounroll
;             for (int k = 0; k < kmax; ++k) {
;                 const float sk = sc[k];
;                 const int kk = k - hi;
; #pragma unroll
;                 for (int i = 0; i < 32; ++i) rank[i] += ((sk > s[i]) || ((sk == s[i]) && (kk < 2 * i))) ? 1 : 0;
;             }
	v_cmp_gt_f32_e64 s[8:9], v101, v0
	v_cmp_gt_f32_e64 s[10:11], v101, v1
	v_cmp_gt_f32_e64 s[12:13], v101, v2
	v_addc_co_u32_e64 v97, vcc, 0, v97, s[8:9]
	v_cmp_gt_f32_e64 s[8:9], v101, v3
	v_addc_co_u32_e64 v96, vcc, 0, v96, s[10:11]
	v_cmp_gt_f32_e64 s[10:11], v101, v4
	v_addc_co_u32_e64 v95, vcc, 0, v95, s[12:13]
	v_cmp_gt_f32_e64 s[12:13], v101, v5
	v_addc_co_u32_e64 v94, vcc, 0, v94, s[8:9]
	v_cmp_gt_f32_e64 s[8:9], v101, v6
	v_addc_co_u32_e64 v93, vcc, 0, v93, s[10:11]
	v_cmp_gt_f32_e64 s[10:11], v101, v7
	v_addc_co_u32_e64 v92, vcc, 0, v92, s[12:13]
	v_cmp_gt_f32_e64 s[12:13], v101, v8
	v_addc_co_u32_e64 v91, vcc, 0, v91, s[8:9]
	v_cmp_gt_f32_e64 s[8:9], v101, v9
	v_addc_co_u32_e64 v90, vcc, 0, v90, s[10:11]
	v_cmp_gt_f32_e64 s[10:11], v101, v10
	v_addc_co_u32_e64 v89, vcc, 0, v89, s[12:13]
	v_cmp_ge_f32_e64 s[12:13], v101, v11
	v_addc_co_u32_e64 v88, vcc, 0, v88, s[8:9]
	v_cmp_ge_f32_e64 s[8:9], v101, v12
	v_addc_co_u32_e64 v87, vcc, 0, v87, s[10:11]
	v_cmp_ge_f32_e64 s[10:11], v101, v13
	v_addc_co_u32_e64 v86, vcc, 0, v86, s[12:13]
	v_cmp_ge_f32_e64 s[12:13], v101, v14
	v_addc_co_u32_e64 v85, vcc, 0, v85, s[8:9]
	v_cmp_ge_f32_e64 s[8:9], v101, v15
	v_addc_co_u32_e64 v84, vcc, 0, v84, s[10:11]
	v_cmp_ge_f32_e64 s[10:11], v101, v16
	v_addc_co_u32_e64 v83, vcc, 0, v83, s[12:13]
	v_cmp_ge_f32_e64 s[12:13], v101, v17
	v_addc_co_u32_e64 v81, vcc, 0, v81, s[8:9]
	v_cmp_ge_f32_e64 s[8:9], v101, v18
	v_addc_co_u32_e64 v79, vcc, 0, v79, s[10:11]
	v_cmp_ge_f32_e64 s[10:11], v101, v19
	v_addc_co_u32_e64 v78, vcc, 0, v78, s[12:13]
	v_cmp_ge_f32_e64 s[12:13], v101, v20
	v_addc_co_u32_e64 v77, vcc, 0, v77, s[8:9]
	v_cmp_ge_f32_e64 s[8:9], v101, v21
	v_addc_co_u32_e64 v76, vcc, 0, v76, s[10:11]
	v_cmp_ge_f32_e64 s[10:11], v101, v22
	v_addc_co_u32_e64 v75, vcc, 0, v75, s[12:13]
	v_cmp_ge_f32_e64 s[12:13], v101, v23
	v_addc_co_u32_e64 v74, vcc, 0, v74, s[8:9]
	v_cmp_ge_f32_e64 s[8:9], v101, v24
	v_addc_co_u32_e64 v73, vcc, 0, v73, s[10:11]
	v_cmp_ge_f32_e64 s[10:11], v101, v25
	v_addc_co_u32_e64 v72, vcc, 0, v72, s[12:13]
	v_cmp_ge_f32_e64 s[12:13], v101, v26
	v_addc_co_u32_e64 v71, vcc, 0, v71, s[8:9]
	v_cmp_ge_f32_e64 s[8:9], v101, v27
	v_addc_co_u32_e64 v70, vcc, 0, v70, s[10:11]
	v_cmp_ge_f32_e64 s[10:11], v101, v28
	v_addc_co_u32_e64 v69, vcc, 0, v69, s[12:13]
	v_cmp_ge_f32_e64 s[12:13], v101, v29
	v_addc_co_u32_e64 v68, vcc, 0, v68, s[8:9]
	v_cmp_ge_f32_e64 s[8:9], v101, v30
	v_addc_co_u32_e64 v67, vcc, 0, v67, s[10:11]
	v_cmp_ge_f32_e64 s[10:11], v101, v31
	v_addc_co_u32_e64 v66, vcc, 0, v66, s[12:13]
	s_nop 0
	v_addc_co_u32_e64 v65, vcc, 0, v65, s[8:9]
	v_addc_co_u32_e64 v64, vcc, 0, v64, s[10:11]
	s_cmp_le_u32 s14, 22
	s_cbranch_scc1 .Lrk_done
	ds_read2_b32 v[100:101], v104 offset0:24 offset1:25
	s_waitcnt lgkmcnt(1)
	v_cmp_gt_f32_e64 s[8:9], v102, v0
	v_cmp_gt_f32_e64 s[10:11], v102, v1
	v_cmp_gt_f32_e64 s[12:13], v102, v2
	v_addc_co_u32_e64 v97, vcc, 0, v97, s[8:9]
	v_cmp_gt_f32_e64 s[8:9], v102, v3
	v_addc_co_u32_e64 v96, vcc, 0, v96, s[10:11]
	v_cmp_gt_f32_e64 s[10:11], v102, v4
	v_addc_co_u32_e64 v95, vcc, 0, v95, s[12:13]
	v_cmp_gt_f32_e64 s[12:13], v102, v5
	v_addc_co_u32_e64 v94, vcc, 0, v94, s[8:9]
	v_cmp_gt_f32_e64 s[8:9], v102, v6
	v_addc_co_u32_e64 v93, vcc, 0, v93, s[10:11]
	v_cmp_gt_f32_e64 s[10:11], v102, v7
	v_addc_co_u32_e64 v92, vcc, 0, v92, s[12:13]
	v_cmp_gt_f32_e64 s[12:13], v102, v8
	v_addc_co_u32_e64 v91, vcc, 0, v91, s[8:9]
	v_cmp_gt_f32_e64 s[8:9], v102, v9
	v_addc_co_u32_e64 v90, vcc, 0, v90, s[10:11]
	v_cmp_gt_f32_e64 s[10:11], v102, v10
	v_addc_co_u32_e64 v89, vcc, 0, v89, s[12:13]
	v_cmp_ge_f32_e64 s[12:13], v102, v11
	v_addc_co_u32_e64 v88, vcc, 0, v88, s[8:9]
	v_cmp_ge_f32_e64 s[8:9], v102, v12
	v_addc_co_u32_e64 v87, vcc, 0, v87, s[10:11]
	v_cmp_ge_f32_e64 s[10:11], v102, v13
	s_and_b64 s[12:13], s[12:13], s[6:7]
	v_addc_co_u32_e64 v86, vcc, 0, v86, s[12:13]
	v_cmp_ge_f32_e64 s[12:13], v102, v14
	v_addc_co_u32_e64 v85, vcc, 0, v85, s[8:9]
	v_cmp_ge_f32_e64 s[8:9], v102, v15
	v_addc_co_u32_e64 v84, vcc, 0, v84, s[10:11]
	v_cmp_ge_f32_e64 s[10:11], v102, v16
	v_addc_co_u32_e64 v83, vcc, 0, v83, s[12:13]
	v_cmp_ge_f32_e64 s[12:13], v102, v17
	v_addc_co_u32_e64 v81, vcc, 0, v81, s[8:9]
	v_cmp_ge_f32_e64 s[8:9], v102, v18
	v_addc_co_u32_e64 v79, vcc, 0, v79, s[10:11]
	v_cmp_ge_f32_e64 s[10:11], v102, v19
	v_addc_co_u32_e64 v78, vcc, 0, v78, s[12:13]
	v_cmp_ge_f32_e64 s[12:13], v102, v20
	v_addc_co_u32_e64 v77, vcc, 0, v77, s[8:9]
	v_cmp_ge_f32_e64 s[8:9], v102, v21
	v_addc_co_u32_e64 v76, vcc, 0, v76, s[10:11]
	v_cmp_ge_f32_e64 s[10:11], v102, v22
	v_addc_co_u32_e64 v75, vcc, 0, v75, s[12:13]
	v_cmp_ge_f32_e64 s[12:13], v102, v23
	v_addc_co_u32_e64 v74, vcc, 0, v74, s[8:9]
	v_cmp_ge_f32_e64 s[8:9], v102, v24
	v_addc_co_u32_e64 v73, vcc, 0, v73, s[10:11]
	v_cmp_ge_f32_e64 s[10:11], v102, v25
	v_addc_co_u32_e64 v72, vcc, 0, v72, s[12:13]
	v_cmp_ge_f32_e64 s[12:13], v102, v26
	v_addc_co_u32_e64 v71, vcc, 0, v71, s[8:9]
	v_cmp_ge_f32_e64 s[8:9], v102, v27
	v_addc_co_u32_e64 v70, vcc, 0, v70, s[10:11]
	v_cmp_ge_f32_e64 s[10:11], v102, v28
	v_addc_co_u32_e64 v69, vcc, 0, v69, s[12:13]
	v_cmp_ge_f32_e64 s[12:13], v102, v29
	v_addc_co_u32_e64 v68, vcc, 0, v68, s[8:9]
	v_cmp_ge_f32_e64 s[8:9], v102, v30
	v_addc_co_u32_e64 v67, vcc, 0, v67, s[10:11]
	v_cmp_ge_f32_e64 s[10:11], v102, v31
	v_addc_co_u32_e64 v66, vcc, 0, v66, s[12:13]
	s_nop 0
	v_addc_co_u32_e64 v65, vcc, 0, v65, s[8:9]
	v_addc_co_u32_e64 v64, vcc, 0, v64, s[10:11]
	s_cmp_le_u32 s14, 23
	s_cbranch_scc1 .Lrk_done
; __device__ __forceinline__ void cmp_phase(LAS unsigned char* lds, const bf16_t* __restrict__ P, const bf16_t* __restrict__ Kc, const bf16_t* __restrict__ Vc,
;                                           bf16_t* __restrict__ ocmp, unsigned long long* __restrict__ mask, int G, const int wave0) {
;     ...
; #pragma nounroll
;             for (int k = 0; k < kmax; ++k) {
;                 const float sk = sc[k];
;                 const int kk = k - hi;
; #pragma unroll
;                 for (int i = 0; i < 32; ++i) rank[i] += ((sk > s[i]) || ((sk == s[i]) && (kk < 2 * i))) ? 1 : 0;
;             }
	v_cmp_gt_f32_e64 s[8:9], v103, v0
	v_cmp_gt_f32_e64 s[10:11], v103, v1
	v_cmp_gt_f32_e64 s[12:13], v103, v2
	v_addc_co_u32_e64 v97, vcc, 0, v97, s[8:9]
	v_cmp_gt_f32_e64 s[8:9], v103, v3
	v_addc_co_u32_e64 v96, vcc, 0, v96, s[10:11]
	v_cmp_gt_f32_e64 s[10:11], v103, v4
	v_addc_co_u32_e64 v95, vcc, 0, v95, s[12:13]
	v_cmp_gt_f32_e64 s[12:13], v103, v5
	v_addc_co_u32_e64 v94, vcc, 0, v94, s[8:9]
	v_cmp_gt_f32_e64 s[8:9], v103, v6
	v_addc_co_u32_e64 v93, vcc, 0, v93, s[10:11]
	v_cmp_gt_f32_e64 s[10:11], v103, v7
	v_addc_co_u32_e64 v92, vcc, 0, v92, s[12:13]
	v_cmp_gt_f32_e64 s[12:13], v103, v8
	v_addc_co_u32_e64 v91, vcc, 0, v91, s[8:9]
	v_cmp_gt_f32_e64 s[8:9], v103, v9
	v_addc_co_u32_e64 v90, vcc, 0, v90, s[10:11]
	v_cmp_gt_f32_e64 s[10:11], v103, v10
	v_addc_co_u32_e64 v89, vcc, 0, v89, s[12:13]
	v_cmp_gt_f32_e64 s[12:13], v103, v11
	v_addc_co_u32_e64 v88, vcc, 0, v88, s[8:9]
	v_cmp_ge_f32_e64 s[8:9], v103, v12
	v_addc_co_u32_e64 v87, vcc, 0, v87, s[10:11]
	v_cmp_ge_f32_e64 s[10:11], v103, v13
	v_addc_co_u32_e64 v86, vcc, 0, v86, s[12:13]
	v_cmp_ge_f32_e64 s[12:13], v103, v14
	v_addc_co_u32_e64 v85, vcc, 0, v85, s[8:9]
	v_cmp_ge_f32_e64 s[8:9], v103, v15
	v_addc_co_u32_e64 v84, vcc, 0, v84, s[10:11]
	v_cmp_ge_f32_e64 s[10:11], v103, v16
	v_addc_co_u32_e64 v83, vcc, 0, v83, s[12:13]
	v_cmp_ge_f32_e64 s[12:13], v103, v17
	v_addc_co_u32_e64 v81, vcc, 0, v81, s[8:9]
	v_cmp_ge_f32_e64 s[8:9], v103, v18
	v_addc_co_u32_e64 v79, vcc, 0, v79, s[10:11]
	v_cmp_ge_f32_e64 s[10:11], v103, v19
	v_addc_co_u32_e64 v78, vcc, 0, v78, s[12:13]
	v_cmp_ge_f32_e64 s[12:13], v103, v20
	v_addc_co_u32_e64 v77, vcc, 0, v77, s[8:9]
	v_cmp_ge_f32_e64 s[8:9], v103, v21
	v_addc_co_u32_e64 v76, vcc, 0, v76, s[10:11]
	v_cmp_ge_f32_e64 s[10:11], v103, v22
	v_addc_co_u32_e64 v75, vcc, 0, v75, s[12:13]
	v_cmp_ge_f32_e64 s[12:13], v103, v23
	v_addc_co_u32_e64 v74, vcc, 0, v74, s[8:9]
	v_cmp_ge_f32_e64 s[8:9], v103, v24
	v_addc_co_u32_e64 v73, vcc, 0, v73, s[10:11]
	v_cmp_ge_f32_e64 s[10:11], v103, v25
	v_addc_co_u32_e64 v72, vcc, 0, v72, s[12:13]
	v_cmp_ge_f32_e64 s[12:13], v103, v26
	v_addc_co_u32_e64 v71, vcc, 0, v71, s[8:9]
	v_cmp_ge_f32_e64 s[8:9], v103, v27
	v_addc_co_u32_e64 v70, vcc, 0, v70, s[10:11]
	v_cmp_ge_f32_e64 s[10:11], v103, v28
	v_addc_co_u32_e64 v69, vcc, 0, v69, s[12:13]
	v_cmp_ge_f32_e64 s[12:13], v103, v29
	v_addc_co_u32_e64 v68, vcc, 0, v68, s[8:9]
	v_cmp_ge_f32_e64 s[8:9], v103, v30
	v_addc_co_u32_e64 v67, vcc, 0, v67, s[10:11]
	v_cmp_ge_f32_e64 s[10:11], v103, v31
	v_addc_co_u32_e64 v66, vcc, 0, v66, s[12:13]
	s_nop 0
	v_addc_co_u32_e64 v65, vcc, 0, v65, s[8:9]
	v_addc_co_u32_e64 v64, vcc, 0, v64, s[10:11]
	s_cmp_le_u32 s14, 24
	s_cbranch_scc1 .Lrk_done
	ds_read2_b32 v[102:103], v104 offset0:26 offset1:27
	s_waitcnt lgkmcnt(1)
	v_cmp_gt_f32_e64 s[8:9], v100, v0
	v_cmp_gt_f32_e64 s[10:11], v100, v1
	v_cmp_gt_f32_e64 s[12:13], v100, v2
	v_addc_co_u32_e64 v97, vcc, 0, v97, s[8:9]
	v_cmp_gt_f32_e64 s[8:9], v100, v3
	v_addc_co_u32_e64 v96, vcc, 0, v96, s[10:11]
	v_cmp_gt_f32_e64 s[10:11], v100, v4
	v_addc_co_u32_e64 v95, vcc, 0, v95, s[12:13]
	v_cmp_gt_f32_e64 s[12:13], v100, v5
	v_addc_co_u32_e64 v94, vcc, 0, v94, s[8:9]
	v_cmp_gt_f32_e64 s[8:9], v100, v6
	v_addc_co_u32_e64 v93, vcc, 0, v93, s[10:11]
	v_cmp_gt_f32_e64 s[10:11], v100, v7
	v_addc_co_u32_e64 v92, vcc, 0, v92, s[12:13]
	v_cmp_gt_f32_e64 s[12:13], v100, v8
	v_addc_co_u32_e64 v91, vcc, 0, v91, s[8:9]
	v_cmp_gt_f32_e64 s[8:9], v100, v9
	v_addc_co_u32_e64 v90, vcc, 0, v90, s[10:11]
	v_cmp_gt_f32_e64 s[10:11], v100, v10
	v_addc_co_u32_e64 v89, vcc, 0, v89, s[12:13]
	v_cmp_gt_f32_e64 s[12:13], v100, v11
	v_addc_co_u32_e64 v88, vcc, 0, v88, s[8:9]
	v_cmp_ge_f32_e64 s[8:9], v100, v12
	v_addc_co_u32_e64 v87, vcc, 0, v87, s[10:11]
	v_cmp_ge_f32_e64 s[10:11], v100, v13
	v_addc_co_u32_e64 v86, vcc, 0, v86, s[12:13]
	v_cmp_ge_f32_e64 s[12:13], v100, v14
	s_and_b64 s[8:9], s[8:9], s[6:7]
	v_addc_co_u32_e64 v85, vcc, 0, v85, s[8:9]
	v_cmp_ge_f32_e64 s[8:9], v100, v15
	v_addc_co_u32_e64 v84, vcc, 0, v84, s[10:11]
	v_cmp_ge_f32_e64 s[10:11], v100, v16
	v_addc_co_u32_e64 v83, vcc, 0, v83, s[12:13]
	v_cmp_ge_f32_e64 s[12:13], v100, v17
	v_addc_co_u32_e64 v81, vcc, 0, v81, s[8:9]
	v_cmp_ge_f32_e64 s[8:9], v100, v18
	v_addc_co_u32_e64 v79, vcc, 0, v79, s[10:11]
	v_cmp_ge_f32_e64 s[10:11], v100, v19
	v_addc_co_u32_e64 v78, vcc, 0, v78, s[12:13]
	v_cmp_ge_f32_e64 s[12:13], v100, v20
	v_addc_co_u32_e64 v77, vcc, 0, v77, s[8:9]
	v_cmp_ge_f32_e64 s[8:9], v100, v21
	v_addc_co_u32_e64 v76, vcc, 0, v76, s[10:11]
	v_cmp_ge_f32_e64 s[10:11], v100, v22
	v_addc_co_u32_e64 v75, vcc, 0, v75, s[12:13]
	v_cmp_ge_f32_e64 s[12:13], v100, v23
	v_addc_co_u32_e64 v74, vcc, 0, v74, s[8:9]
	v_cmp_ge_f32_e64 s[8:9], v100, v24
	v_addc_co_u32_e64 v73, vcc, 0, v73, s[10:11]
	v_cmp_ge_f32_e64 s[10:11], v100, v25
	v_addc_co_u32_e64 v72, vcc, 0, v72, s[12:13]
	v_cmp_ge_f32_e64 s[12:13], v100, v26
	v_addc_co_u32_e64 v71, vcc, 0, v71, s[8:9]
	v_cmp_ge_f32_e64 s[8:9], v100, v27
	v_addc_co_u32_e64 v70, vcc, 0, v70, s[10:11]
	v_cmp_ge_f32_e64 s[10:11], v100, v28
	v_addc_co_u32_e64 v69, vcc, 0, v69, s[12:13]
	v_cmp_ge_f32_e64 s[12:13], v100, v29
	v_addc_co_u32_e64 v68, vcc, 0, v68, s[8:9]
	v_cmp_ge_f32_e64 s[8:9], v100, v30
	v_addc_co_u32_e64 v67, vcc, 0, v67, s[10:11]
	v_cmp_ge_f32_e64 s[10:11], v100, v31
	v_addc_co_u32_e64 v66, vcc, 0, v66, s[12:13]
	s_nop 0
	v_addc_co_u32_e64 v65, vcc, 0, v65, s[8:9]
	v_addc_co_u32_e64 v64, vcc, 0, v64, s[10:11]
	s_cmp_le_u32 s14, 25
	s_cbranch_scc1 .Lrk_done
; __device__ __forceinline__ void cmp_phase(LAS unsigned char* lds, const bf16_t* __restrict__ P, const bf16_t* __restrict__ Kc, const bf16_t* __restrict__ Vc,
;                                           bf16_t* __restrict__ ocmp, unsigned long long* __restrict__ mask, int G, const int wave0) {
;     ...
; #pragma nounroll
;             for (int k = 0; k < kmax; ++k) {
;                 const float sk = sc[k];
;                 const int kk = k - hi;
; #pragma unroll
;                 for (int i = 0; i < 32; ++i) rank[i] += ((sk > s[i]) || ((sk == s[i]) && (kk < 2 * i))) ? 1 : 0;
;             }
	v_cmp_gt_f32_e64 s[8:9], v101, v0
	v_cmp_gt_f32_e64 s[10:11], v101, v1
	v_cmp_gt_f32_e64 s[12:13], v101, v2
	v_addc_co_u32_e64 v97, vcc, 0, v97, s[8:9]
	v_cmp_gt_f32_e64 s[8:9], v101, v3
	v_addc_co_u32_e64 v96, vcc, 0, v96, s[10:11]
	v_cmp_gt_f32_e64 s[10:11], v101, v4
	v_addc_co_u32_e64 v95, vcc, 0, v95, s[12:13]
	v_cmp_gt_f32_e64 s[12:13], v101, v5
	v_addc_co_u32_e64 v94, vcc, 0, v94, s[8:9]
	v_cmp_gt_f32_e64 s[8:9], v101, v6
	v_addc_co_u32_e64 v93, vcc, 0, v93, s[10:11]
	v_cmp_gt_f32_e64 s[10:11], v101, v7
	v_addc_co_u32_e64 v92, vcc, 0, v92, s[12:13]
	v_cmp_gt_f32_e64 s[12:13], v101, v8
	v_addc_co_u32_e64 v91, vcc, 0, v91, s[8:9]
	v_cmp_gt_f32_e64 s[8:9], v101, v9
	v_addc_co_u32_e64 v90, vcc, 0, v90, s[10:11]
	v_cmp_gt_f32_e64 s[10:11], v101, v10
	v_addc_co_u32_e64 v89, vcc, 0, v89, s[12:13]
	v_cmp_gt_f32_e64 s[12:13], v101, v11
	v_addc_co_u32_e64 v88, vcc, 0, v88, s[8:9]
	v_cmp_gt_f32_e64 s[8:9], v101, v12
	v_addc_co_u32_e64 v87, vcc, 0, v87, s[10:11]
	v_cmp_ge_f32_e64 s[10:11], v101, v13
	v_addc_co_u32_e64 v86, vcc, 0, v86, s[12:13]
	v_cmp_ge_f32_e64 s[12:13], v101, v14
	v_addc_co_u32_e64 v85, vcc, 0, v85, s[8:9]
	v_cmp_ge_f32_e64 s[8:9], v101, v15
	v_addc_co_u32_e64 v84, vcc, 0, v84, s[10:11]
	v_cmp_ge_f32_e64 s[10:11], v101, v16
	v_addc_co_u32_e64 v83, vcc, 0, v83, s[12:13]
	v_cmp_ge_f32_e64 s[12:13], v101, v17
	v_addc_co_u32_e64 v81, vcc, 0, v81, s[8:9]
	v_cmp_ge_f32_e64 s[8:9], v101, v18
	v_addc_co_u32_e64 v79, vcc, 0, v79, s[10:11]
	v_cmp_ge_f32_e64 s[10:11], v101, v19
	v_addc_co_u32_e64 v78, vcc, 0, v78, s[12:13]
	v_cmp_ge_f32_e64 s[12:13], v101, v20
	v_addc_co_u32_e64 v77, vcc, 0, v77, s[8:9]
	v_cmp_ge_f32_e64 s[8:9], v101, v21
	v_addc_co_u32_e64 v76, vcc, 0, v76, s[10:11]
	v_cmp_ge_f32_e64 s[10:11], v101, v22
	v_addc_co_u32_e64 v75, vcc, 0, v75, s[12:13]
	v_cmp_ge_f32_e64 s[12:13], v101, v23
	v_addc_co_u32_e64 v74, vcc, 0, v74, s[8:9]
	v_cmp_ge_f32_e64 s[8:9], v101, v24
	v_addc_co_u32_e64 v73, vcc, 0, v73, s[10:11]
	v_cmp_ge_f32_e64 s[10:11], v101, v25
	v_addc_co_u32_e64 v72, vcc, 0, v72, s[12:13]
	v_cmp_ge_f32_e64 s[12:13], v101, v26
	v_addc_co_u32_e64 v71, vcc, 0, v71, s[8:9]
	v_cmp_ge_f32_e64 s[8:9], v101, v27
	v_addc_co_u32_e64 v70, vcc, 0, v70, s[10:11]
	v_cmp_ge_f32_e64 s[10:11], v101, v28
	v_addc_co_u32_e64 v69, vcc, 0, v69, s[12:13]
	v_cmp_ge_f32_e64 s[12:13], v101, v29
	v_addc_co_u32_e64 v68, vcc, 0, v68, s[8:9]
	v_cmp_ge_f32_e64 s[8:9], v101, v30
	v_addc_co_u32_e64 v67, vcc, 0, v67, s[10:11]
	v_cmp_ge_f32_e64 s[10:11], v101, v31
	v_addc_co_u32_e64 v66, vcc, 0, v66, s[12:13]
	s_nop 0
	v_addc_co_u32_e64 v65, vcc, 0, v65, s[8:9]
	v_addc_co_u32_e64 v64, vcc, 0, v64, s[10:11]
	s_cmp_le_u32 s14, 26
	s_cbranch_scc1 .Lrk_done
	ds_read2_b32 v[100:101], v104 offset0:28 offset1:29
	s_waitcnt lgkmcnt(1)
	v_cmp_gt_f32_e64 s[8:9], v102, v0
	v_cmp_gt_f32_e64 s[10:11], v102, v1
	v_cmp_gt_f32_e64 s[12:13], v102, v2
	v_addc_co_u32_e64 v97, vcc, 0, v97, s[8:9]
	v_cmp_gt_f32_e64 s[8:9], v102, v3
	v_addc_co_u32_e64 v96, vcc, 0, v96, s[10:11]
	v_cmp_gt_f32_e64 s[10:11], v102, v4
	v_addc_co_u32_e64 v95, vcc, 0, v95, s[12:13]
	v_cmp_gt_f32_e64 s[12:13], v102, v5
	v_addc_co_u32_e64 v94, vcc, 0, v94, s[8:9]
	v_cmp_gt_f32_e64 s[8:9], v102, v6
	v_addc_co_u32_e64 v93, vcc, 0, v93, s[10:11]
	v_cmp_gt_f32_e64 s[10:11], v102, v7
	v_addc_co_u32_e64 v92, vcc, 0, v92, s[12:13]
	v_cmp_gt_f32_e64 s[12:13], v102, v8
	v_addc_co_u32_e64 v91, vcc, 0, v91, s[8:9]
	v_cmp_gt_f32_e64 s[8:9], v102, v9
	v_addc_co_u32_e64 v90, vcc, 0, v90, s[10:11]
	v_cmp_gt_f32_e64 s[10:11], v102, v10
	v_addc_co_u32_e64 v89, vcc, 0, v89, s[12:13]
	v_cmp_gt_f32_e64 s[12:13], v102, v11
	v_addc_co_u32_e64 v88, vcc, 0, v88, s[8:9]
	v_cmp_gt_f32_e64 s[8:9], v102, v12
	v_addc_co_u32_e64 v87, vcc, 0, v87, s[10:11]
	v_cmp_ge_f32_e64 s[10:11], v102, v13
	v_addc_co_u32_e64 v86, vcc, 0, v86, s[12:13]
	v_cmp_ge_f32_e64 s[12:13], v102, v14
	v_addc_co_u32_e64 v85, vcc, 0, v85, s[8:9]
	v_cmp_ge_f32_e64 s[8:9], v102, v15
	s_and_b64 s[10:11], s[10:11], s[6:7]
	v_addc_co_u32_e64 v84, vcc, 0, v84, s[10:11]
	v_cmp_ge_f32_e64 s[10:11], v102, v16
	v_addc_co_u32_e64 v83, vcc, 0, v83, s[12:13]
	v_cmp_ge_f32_e64 s[12:13], v102, v17
	v_addc_co_u32_e64 v81, vcc, 0, v81, s[8:9]
	v_cmp_ge_f32_e64 s[8:9], v102, v18
	v_addc_co_u32_e64 v79, vcc, 0, v79, s[10:11]
	v_cmp_ge_f32_e64 s[10:11], v102, v19
	v_addc_co_u32_e64 v78, vcc, 0, v78, s[12:13]
	v_cmp_ge_f32_e64 s[12:13], v102, v20
	v_addc_co_u32_e64 v77, vcc, 0, v77, s[8:9]
	v_cmp_ge_f32_e64 s[8:9], v102, v21
	v_addc_co_u32_e64 v76, vcc, 0, v76, s[10:11]
	v_cmp_ge_f32_e64 s[10:11], v102, v22
	v_addc_co_u32_e64 v75, vcc, 0, v75, s[12:13]
	v_cmp_ge_f32_e64 s[12:13], v102, v23
	v_addc_co_u32_e64 v74, vcc, 0, v74, s[8:9]
	v_cmp_ge_f32_e64 s[8:9], v102, v24
	v_addc_co_u32_e64 v73, vcc, 0, v73, s[10:11]
	v_cmp_ge_f32_e64 s[10:11], v102, v25
	v_addc_co_u32_e64 v72, vcc, 0, v72, s[12:13]
	v_cmp_ge_f32_e64 s[12:13], v102, v26
	v_addc_co_u32_e64 v71, vcc, 0, v71, s[8:9]
	v_cmp_ge_f32_e64 s[8:9], v102, v27
	v_addc_co_u32_e64 v70, vcc, 0, v70, s[10:11]
	v_cmp_ge_f32_e64 s[10:11], v102, v28
	v_addc_co_u32_e64 v69, vcc, 0, v69, s[12:13]
	v_cmp_ge_f32_e64 s[12:13], v102, v29
	v_addc_co_u32_e64 v68, vcc, 0, v68, s[8:9]
	v_cmp_ge_f32_e64 s[8:9], v102, v30
	v_addc_co_u32_e64 v67, vcc, 0, v67, s[10:11]
	v_cmp_ge_f32_e64 s[10:11], v102, v31
	v_addc_co_u32_e64 v66, vcc, 0, v66, s[12:13]
	s_nop 0
	v_addc_co_u32_e64 v65, vcc, 0, v65, s[8:9]
	v_addc_co_u32_e64 v64, vcc, 0, v64, s[10:11]
	s_cmp_le_u32 s14, 27
	s_cbranch_scc1 .Lrk_done
; __device__ __forceinline__ void cmp_phase(LAS unsigned char* lds, const bf16_t* __restrict__ P, const bf16_t* __restrict__ Kc, const bf16_t* __restrict__ Vc,
;                                           bf16_t* __restrict__ ocmp, unsigned long long* __restrict__ mask, int G, const int wave0) {
;     ...
; #pragma nounroll
;             for (int k = 0; k < kmax; ++k) {
;                 const float sk = sc[k];
;                 const int kk = k - hi;
; #pragma unroll
;                 for (int i = 0; i < 32; ++i) rank[i] += ((sk > s[i]) || ((sk == s[i]) && (kk < 2 * i))) ? 1 : 0;
;             }
	v_cmp_gt_f32_e64 s[8:9], v103, v0
	v_cmp_gt_f32_e64 s[10:11], v103, v1
	v_cmp_gt_f32_e64 s[12:13], v103, v2
	v_addc_co_u32_e64 v97, vcc, 0, v97, s[8:9]
	v_cmp_gt_f32_e64 s[8:9], v103, v3
	v_addc_co_u32_e64 v96, vcc, 0, v96, s[10:11]
	v_cmp_gt_f32_e64 s[10:11], v103, v4
	v_addc_co_u32_e64 v95, vcc, 0, v95, s[12:13]
	v_cmp_gt_f32_e64 s[12:13], v103, v5
	v_addc_co_u32_e64 v94, vcc, 0, v94, s[8:9]
	v_cmp_gt_f32_e64 s[8:9], v103, v6
	v_addc_co_u32_e64 v93, vcc, 0, v93, s[10:11]
	v_cmp_gt_f32_e64 s[10:11], v103, v7
	v_addc_co_u32_e64 v92, vcc, 0, v92, s[12:13]
	v_cmp_gt_f32_e64 s[12:13], v103, v8
	v_addc_co_u32_e64 v91, vcc, 0, v91, s[8:9]
	v_cmp_gt_f32_e64 s[8:9], v103, v9
	v_addc_co_u32_e64 v90, vcc, 0, v90, s[10:11]
	v_cmp_gt_f32_e64 s[10:11], v103, v10
	v_addc_co_u32_e64 v89, vcc, 0, v89, s[12:13]
	v_cmp_gt_f32_e64 s[12:13], v103, v11
	v_addc_co_u32_e64 v88, vcc, 0, v88, s[8:9]
	v_cmp_gt_f32_e64 s[8:9], v103, v12
	v_addc_co_u32_e64 v87, vcc, 0, v87, s[10:11]
	v_cmp_gt_f32_e64 s[10:11], v103, v13
	v_addc_co_u32_e64 v86, vcc, 0, v86, s[12:13]
	v_cmp_ge_f32_e64 s[12:13], v103, v14
	v_addc_co_u32_e64 v85, vcc, 0, v85, s[8:9]
	v_cmp_ge_f32_e64 s[8:9], v103, v15
	v_addc_co_u32_e64 v84, vcc, 0, v84, s[10:11]
	v_cmp_ge_f32_e64 s[10:11], v103, v16
	v_addc_co_u32_e64 v83, vcc, 0, v83, s[12:13]
	v_cmp_ge_f32_e64 s[12:13], v103, v17
	v_addc_co_u32_e64 v81, vcc, 0, v81, s[8:9]
	v_cmp_ge_f32_e64 s[8:9], v103, v18
	v_addc_co_u32_e64 v79, vcc, 0, v79, s[10:11]
	v_cmp_ge_f32_e64 s[10:11], v103, v19
	v_addc_co_u32_e64 v78, vcc, 0, v78, s[12:13]
	v_cmp_ge_f32_e64 s[12:13], v103, v20
	v_addc_co_u32_e64 v77, vcc, 0, v77, s[8:9]
	v_cmp_ge_f32_e64 s[8:9], v103, v21
	v_addc_co_u32_e64 v76, vcc, 0, v76, s[10:11]
	v_cmp_ge_f32_e64 s[10:11], v103, v22
	v_addc_co_u32_e64 v75, vcc, 0, v75, s[12:13]
	v_cmp_ge_f32_e64 s[12:13], v103, v23
	v_addc_co_u32_e64 v74, vcc, 0, v74, s[8:9]
	v_cmp_ge_f32_e64 s[8:9], v103, v24
	v_addc_co_u32_e64 v73, vcc, 0, v73, s[10:11]
	v_cmp_ge_f32_e64 s[10:11], v103, v25
	v_addc_co_u32_e64 v72, vcc, 0, v72, s[12:13]
	v_cmp_ge_f32_e64 s[12:13], v103, v26
	v_addc_co_u32_e64 v71, vcc, 0, v71, s[8:9]
	v_cmp_ge_f32_e64 s[8:9], v103, v27
	v_addc_co_u32_e64 v70, vcc, 0, v70, s[10:11]
	v_cmp_ge_f32_e64 s[10:11], v103, v28
	v_addc_co_u32_e64 v69, vcc, 0, v69, s[12:13]
	v_cmp_ge_f32_e64 s[12:13], v103, v29
	v_addc_co_u32_e64 v68, vcc, 0, v68, s[8:9]
	v_cmp_ge_f32_e64 s[8:9], v103, v30
	v_addc_co_u32_e64 v67, vcc, 0, v67, s[10:11]
	v_cmp_ge_f32_e64 s[10:11], v103, v31
	v_addc_co_u32_e64 v66, vcc, 0, v66, s[12:13]
	s_nop 0
	v_addc_co_u32_e64 v65, vcc, 0, v65, s[8:9]
	v_addc_co_u32_e64 v64, vcc, 0, v64, s[10:11]
	s_cmp_le_u32 s14, 28
	s_cbranch_scc1 .Lrk_done
	ds_read2_b32 v[102:103], v104 offset0:30 offset1:31
	s_waitcnt lgkmcnt(1)
	v_cmp_gt_f32_e64 s[8:9], v100, v0
	v_cmp_gt_f32_e64 s[10:11], v100, v1
	v_cmp_gt_f32_e64 s[12:13], v100, v2
	v_addc_co_u32_e64 v97, vcc, 0, v97, s[8:9]
	v_cmp_gt_f32_e64 s[8:9], v100, v3
	v_addc_co_u32_e64 v96, vcc, 0, v96, s[10:11]
	v_cmp_gt_f32_e64 s[10:11], v100, v4
	v_addc_co_u32_e64 v95, vcc, 0, v95, s[12:13]
	v_cmp_gt_f32_e64 s[12:13], v100, v5
	v_addc_co_u32_e64 v94, vcc, 0, v94, s[8:9]
	v_cmp_gt_f32_e64 s[8:9], v100, v6
	v_addc_co_u32_e64 v93, vcc, 0, v93, s[10:11]
	v_cmp_gt_f32_e64 s[10:11], v100, v7
	v_addc_co_u32_e64 v92, vcc, 0, v92, s[12:13]
	v_cmp_gt_f32_e64 s[12:13], v100, v8
	v_addc_co_u32_e64 v91, vcc, 0, v91, s[8:9]
	v_cmp_gt_f32_e64 s[8:9], v100, v9
	v_addc_co_u32_e64 v90, vcc, 0, v90, s[10:11]
	v_cmp_gt_f32_e64 s[10:11], v100, v10
	v_addc_co_u32_e64 v89, vcc, 0, v89, s[12:13]
	v_cmp_gt_f32_e64 s[12:13], v100, v11
	v_addc_co_u32_e64 v88, vcc, 0, v88, s[8:9]
	v_cmp_gt_f32_e64 s[8:9], v100, v12
	v_addc_co_u32_e64 v87, vcc, 0, v87, s[10:11]
	v_cmp_gt_f32_e64 s[10:11], v100, v13
	v_addc_co_u32_e64 v86, vcc, 0, v86, s[12:13]
	v_cmp_ge_f32_e64 s[12:13], v100, v14
	v_addc_co_u32_e64 v85, vcc, 0, v85, s[8:9]
	v_cmp_ge_f32_e64 s[8:9], v100, v15
	v_addc_co_u32_e64 v84, vcc, 0, v84, s[10:11]
	v_cmp_ge_f32_e64 s[10:11], v100, v16
	s_and_b64 s[12:13], s[12:13], s[6:7]
	v_addc_co_u32_e64 v83, vcc, 0, v83, s[12:13]
	v_cmp_ge_f32_e64 s[12:13], v100, v17
	v_addc_co_u32_e64 v81, vcc, 0, v81, s[8:9]
	v_cmp_ge_f32_e64 s[8:9], v100, v18
	v_addc_co_u32_e64 v79, vcc, 0, v79, s[10:11]
	v_cmp_ge_f32_e64 s[10:11], v100, v19
	v_addc_co_u32_e64 v78, vcc, 0, v78, s[12:13]
	v_cmp_ge_f32_e64 s[12:13], v100, v20
	v_addc_co_u32_e64 v77, vcc, 0, v77, s[8:9]
	v_cmp_ge_f32_e64 s[8:9], v100, v21
	v_addc_co_u32_e64 v76, vcc, 0, v76, s[10:11]
	v_cmp_ge_f32_e64 s[10:11], v100, v22
	v_addc_co_u32_e64 v75, vcc, 0, v75, s[12:13]
	v_cmp_ge_f32_e64 s[12:13], v100, v23
	v_addc_co_u32_e64 v74, vcc, 0, v74, s[8:9]
	v_cmp_ge_f32_e64 s[8:9], v100, v24
	v_addc_co_u32_e64 v73, vcc, 0, v73, s[10:11]
	v_cmp_ge_f32_e64 s[10:11], v100, v25
	v_addc_co_u32_e64 v72, vcc, 0, v72, s[12:13]
	v_cmp_ge_f32_e64 s[12:13], v100, v26
	v_addc_co_u32_e64 v71, vcc, 0, v71, s[8:9]
	v_cmp_ge_f32_e64 s[8:9], v100, v27
	v_addc_co_u32_e64 v70, vcc, 0, v70, s[10:11]
	v_cmp_ge_f32_e64 s[10:11], v100, v28
	v_addc_co_u32_e64 v69, vcc, 0, v69, s[12:13]
	v_cmp_ge_f32_e64 s[12:13], v100, v29
	v_addc_co_u32_e64 v68, vcc, 0, v68, s[8:9]
	v_cmp_ge_f32_e64 s[8:9], v100, v30
	v_addc_co_u32_e64 v67, vcc, 0, v67, s[10:11]
	v_cmp_ge_f32_e64 s[10:11], v100, v31
	v_addc_co_u32_e64 v66, vcc, 0, v66, s[12:13]
	s_nop 0
	v_addc_co_u32_e64 v65, vcc, 0, v65, s[8:9]
	v_addc_co_u32_e64 v64, vcc, 0, v64, s[10:11]
	s_cmp_le_u32 s14, 29
	s_cbranch_scc1 .Lrk_done
; __device__ __forceinline__ void cmp_phase(LAS unsigned char* lds, const bf16_t* __restrict__ P, const bf16_t* __restrict__ Kc, const bf16_t* __restrict__ Vc,
;                                           bf16_t* __restrict__ ocmp, unsigned long long* __restrict__ mask, int G, const int wave0) {
;     ...
; #pragma nounroll
;             for (int k = 0; k < kmax; ++k) {
;                 const float sk = sc[k];
;                 const int kk = k - hi;
; #pragma unroll
;                 for (int i = 0; i < 32; ++i) rank[i] += ((sk > s[i]) || ((sk == s[i]) && (kk < 2 * i))) ? 1 : 0;
;             }
	v_cmp_gt_f32_e64 s[8:9], v101, v0
	v_cmp_gt_f32_e64 s[10:11], v101, v1
	v_cmp_gt_f32_e64 s[12:13], v101, v2
	v_addc_co_u32_e64 v97, vcc, 0, v97, s[8:9]
	v_cmp_gt_f32_e64 s[8:9], v101, v3
	v_addc_co_u32_e64 v96, vcc, 0, v96, s[10:11]
	v_cmp_gt_f32_e64 s[10:11], v101, v4
	v_addc_co_u32_e64 v95, vcc, 0, v95, s[12:13]
	v_cmp_gt_f32_e64 s[12:13], v101, v5
	v_addc_co_u32_e64 v94, vcc, 0, v94, s[8:9]
	v_cmp_gt_f32_e64 s[8:9], v101, v6
	v_addc_co_u32_e64 v93, vcc, 0, v93, s[10:11]
	v_cmp_gt_f32_e64 s[10:11], v101, v7
	v_addc_co_u32_e64 v92, vcc, 0, v92, s[12:13]
	v_cmp_gt_f32_e64 s[12:13], v101, v8
	v_addc_co_u32_e64 v91, vcc, 0, v91, s[8:9]
	v_cmp_gt_f32_e64 s[8:9], v101, v9
	v_addc_co_u32_e64 v90, vcc, 0, v90, s[10:11]
	v_cmp_gt_f32_e64 s[10:11], v101, v10
	v_addc_co_u32_e64 v89, vcc, 0, v89, s[12:13]
	v_cmp_gt_f32_e64 s[12:13], v101, v11
	v_addc_co_u32_e64 v88, vcc, 0, v88, s[8:9]
	v_cmp_gt_f32_e64 s[8:9], v101, v12
	v_addc_co_u32_e64 v87, vcc, 0, v87, s[10:11]
	v_cmp_gt_f32_e64 s[10:11], v101, v13
	v_addc_co_u32_e64 v86, vcc, 0, v86, s[12:13]
	v_cmp_gt_f32_e64 s[12:13], v101, v14
	v_addc_co_u32_e64 v85, vcc, 0, v85, s[8:9]
	v_cmp_ge_f32_e64 s[8:9], v101, v15
	v_addc_co_u32_e64 v84, vcc, 0, v84, s[10:11]
	v_cmp_ge_f32_e64 s[10:11], v101, v16
	v_addc_co_u32_e64 v83, vcc, 0, v83, s[12:13]
	v_cmp_ge_f32_e64 s[12:13], v101, v17
	v_addc_co_u32_e64 v81, vcc, 0, v81, s[8:9]
	v_cmp_ge_f32_e64 s[8:9], v101, v18
	v_addc_co_u32_e64 v79, vcc, 0, v79, s[10:11]
	v_cmp_ge_f32_e64 s[10:11], v101, v19
	v_addc_co_u32_e64 v78, vcc, 0, v78, s[12:13]
	v_cmp_ge_f32_e64 s[12:13], v101, v20
	v_addc_co_u32_e64 v77, vcc, 0, v77, s[8:9]
	v_cmp_ge_f32_e64 s[8:9], v101, v21
	v_addc_co_u32_e64 v76, vcc, 0, v76, s[10:11]
	v_cmp_ge_f32_e64 s[10:11], v101, v22
	v_addc_co_u32_e64 v75, vcc, 0, v75, s[12:13]
	v_cmp_ge_f32_e64 s[12:13], v101, v23
	v_addc_co_u32_e64 v74, vcc, 0, v74, s[8:9]
	v_cmp_ge_f32_e64 s[8:9], v101, v24
	v_addc_co_u32_e64 v73, vcc, 0, v73, s[10:11]
	v_cmp_ge_f32_e64 s[10:11], v101, v25
	v_addc_co_u32_e64 v72, vcc, 0, v72, s[12:13]
	v_cmp_ge_f32_e64 s[12:13], v101, v26
	v_addc_co_u32_e64 v71, vcc, 0, v71, s[8:9]
	v_cmp_ge_f32_e64 s[8:9], v101, v27
	v_addc_co_u32_e64 v70, vcc, 0, v70, s[10:11]
	v_cmp_ge_f32_e64 s[10:11], v101, v28
	v_addc_co_u32_e64 v69, vcc, 0, v69, s[12:13]
	v_cmp_ge_f32_e64 s[12:13], v101, v29
	v_addc_co_u32_e64 v68, vcc, 0, v68, s[8:9]
	v_cmp_ge_f32_e64 s[8:9], v101, v30
	v_addc_co_u32_e64 v67, vcc, 0, v67, s[10:11]
	v_cmp_ge_f32_e64 s[10:11], v101, v31
	v_addc_co_u32_e64 v66, vcc, 0, v66, s[12:13]
	s_nop 0
	v_addc_co_u32_e64 v65, vcc, 0, v65, s[8:9]
	v_addc_co_u32_e64 v64, vcc, 0, v64, s[10:11]
	s_cmp_le_u32 s14, 30
	s_cbranch_scc1 .Lrk_done
	ds_read2_b32 v[100:101], v104 offset0:32 offset1:33
	s_waitcnt lgkmcnt(1)
	v_cmp_gt_f32_e64 s[8:9], v102, v0
	v_cmp_gt_f32_e64 s[10:11], v102, v1
	v_cmp_gt_f32_e64 s[12:13], v102, v2
	v_addc_co_u32_e64 v97, vcc, 0, v97, s[8:9]
	v_cmp_gt_f32_e64 s[8:9], v102, v3
	v_addc_co_u32_e64 v96, vcc, 0, v96, s[10:11]
	v_cmp_gt_f32_e64 s[10:11], v102, v4
	v_addc_co_u32_e64 v95, vcc, 0, v95, s[12:13]
	v_cmp_gt_f32_e64 s[12:13], v102, v5
	v_addc_co_u32_e64 v94, vcc, 0, v94, s[8:9]
	v_cmp_gt_f32_e64 s[8:9], v102, v6
	v_addc_co_u32_e64 v93, vcc, 0, v93, s[10:11]
	v_cmp_gt_f32_e64 s[10:11], v102, v7
	v_addc_co_u32_e64 v92, vcc, 0, v92, s[12:13]
	v_cmp_gt_f32_e64 s[12:13], v102, v8
	v_addc_co_u32_e64 v91, vcc, 0, v91, s[8:9]
	v_cmp_gt_f32_e64 s[8:9], v102, v9
	v_addc_co_u32_e64 v90, vcc, 0, v90, s[10:11]
	v_cmp_gt_f32_e64 s[10:11], v102, v10
	v_addc_co_u32_e64 v89, vcc, 0, v89, s[12:13]
	v_cmp_gt_f32_e64 s[12:13], v102, v11
	v_addc_co_u32_e64 v88, vcc, 0, v88, s[8:9]
	v_cmp_gt_f32_e64 s[8:9], v102, v12
	v_addc_co_u32_e64 v87, vcc, 0, v87, s[10:11]
	v_cmp_gt_f32_e64 s[10:11], v102, v13
	v_addc_co_u32_e64 v86, vcc, 0, v86, s[12:13]
	v_cmp_gt_f32_e64 s[12:13], v102, v14
	v_addc_co_u32_e64 v85, vcc, 0, v85, s[8:9]
	v_cmp_ge_f32_e64 s[8:9], v102, v15
	v_addc_co_u32_e64 v84, vcc, 0, v84, s[10:11]
	v_cmp_ge_f32_e64 s[10:11], v102, v16
	v_addc_co_u32_e64 v83, vcc, 0, v83, s[12:13]
	v_cmp_ge_f32_e64 s[12:13], v102, v17
	s_and_b64 s[8:9], s[8:9], s[6:7]
	v_addc_co_u32_e64 v81, vcc, 0, v81, s[8:9]
	v_cmp_ge_f32_e64 s[8:9], v102, v18
	v_addc_co_u32_e64 v79, vcc, 0, v79, s[10:11]
	v_cmp_ge_f32_e64 s[10:11], v102, v19
	v_addc_co_u32_e64 v78, vcc, 0, v78, s[12:13]
	v_cmp_ge_f32_e64 s[12:13], v102, v20
	v_addc_co_u32_e64 v77, vcc, 0, v77, s[8:9]
	v_cmp_ge_f32_e64 s[8:9], v102, v21
	v_addc_co_u32_e64 v76, vcc, 0, v76, s[10:11]
	v_cmp_ge_f32_e64 s[10:11], v102, v22
	v_addc_co_u32_e64 v75, vcc, 0, v75, s[12:13]
	v_cmp_ge_f32_e64 s[12:13], v102, v23
	v_addc_co_u32_e64 v74, vcc, 0, v74, s[8:9]
	v_cmp_ge_f32_e64 s[8:9], v102, v24
	v_addc_co_u32_e64 v73, vcc, 0, v73, s[10:11]
	v_cmp_ge_f32_e64 s[10:11], v102, v25
	v_addc_co_u32_e64 v72, vcc, 0, v72, s[12:13]
	v_cmp_ge_f32_e64 s[12:13], v102, v26
	v_addc_co_u32_e64 v71, vcc, 0, v71, s[8:9]
	v_cmp_ge_f32_e64 s[8:9], v102, v27
	v_addc_co_u32_e64 v70, vcc, 0, v70, s[10:11]
	v_cmp_ge_f32_e64 s[10:11], v102, v28
	v_addc_co_u32_e64 v69, vcc, 0, v69, s[12:13]
	v_cmp_ge_f32_e64 s[12:13], v102, v29
	v_addc_co_u32_e64 v68, vcc, 0, v68, s[8:9]
	v_cmp_ge_f32_e64 s[8:9], v102, v30
	v_addc_co_u32_e64 v67, vcc, 0, v67, s[10:11]
	v_cmp_ge_f32_e64 s[10:11], v102, v31
	v_addc_co_u32_e64 v66, vcc, 0, v66, s[12:13]
	s_nop 0
	v_addc_co_u32_e64 v65, vcc, 0, v65, s[8:9]
	v_addc_co_u32_e64 v64, vcc, 0, v64, s[10:11]
	s_cmp_le_u32 s14, 31
	s_cbranch_scc1 .Lrk_done
; __device__ __forceinline__ void cmp_phase(LAS unsigned char* lds, const bf16_t* __restrict__ P, const bf16_t* __restrict__ Kc, const bf16_t* __restrict__ Vc,
;                                           bf16_t* __restrict__ ocmp, unsigned long long* __restrict__ mask, int G, const int wave0) {
;     ...
; #pragma nounroll
;             for (int k = 0; k < kmax; ++k) {
;                 const float sk = sc[k];
;                 const int kk = k - hi;
; #pragma unroll
;                 for (int i = 0; i < 32; ++i) rank[i] += ((sk > s[i]) || ((sk == s[i]) && (kk < 2 * i))) ? 1 : 0;
;             }
	v_cmp_gt_f32_e64 s[8:9], v103, v0
	v_cmp_gt_f32_e64 s[10:11], v103, v1
	v_cmp_gt_f32_e64 s[12:13], v103, v2
	v_addc_co_u32_e64 v97, vcc, 0, v97, s[8:9]
	v_cmp_gt_f32_e64 s[8:9], v103, v3
	v_addc_co_u32_e64 v96, vcc, 0, v96, s[10:11]
	v_cmp_gt_f32_e64 s[10:11], v103, v4
	v_addc_co_u32_e64 v95, vcc, 0, v95, s[12:13]
	v_cmp_gt_f32_e64 s[12:13], v103, v5
	v_addc_co_u32_e64 v94, vcc, 0, v94, s[8:9]
	v_cmp_gt_f32_e64 s[8:9], v103, v6
	v_addc_co_u32_e64 v93, vcc, 0, v93, s[10:11]
	v_cmp_gt_f32_e64 s[10:11], v103, v7
	v_addc_co_u32_e64 v92, vcc, 0, v92, s[12:13]
	v_cmp_gt_f32_e64 s[12:13], v103, v8
	v_addc_co_u32_e64 v91, vcc, 0, v91, s[8:9]
	v_cmp_gt_f32_e64 s[8:9], v103, v9
	v_addc_co_u32_e64 v90, vcc, 0, v90, s[10:11]
	v_cmp_gt_f32_e64 s[10:11], v103, v10
	v_addc_co_u32_e64 v89, vcc, 0, v89, s[12:13]
	v_cmp_gt_f32_e64 s[12:13], v103, v11
	v_addc_co_u32_e64 v88, vcc, 0, v88, s[8:9]
	v_cmp_gt_f32_e64 s[8:9], v103, v12
	v_addc_co_u32_e64 v87, vcc, 0, v87, s[10:11]
	v_cmp_gt_f32_e64 s[10:11], v103, v13
	v_addc_co_u32_e64 v86, vcc, 0, v86, s[12:13]
	v_cmp_gt_f32_e64 s[12:13], v103, v14
	v_addc_co_u32_e64 v85, vcc, 0, v85, s[8:9]
	v_cmp_gt_f32_e64 s[8:9], v103, v15
	v_addc_co_u32_e64 v84, vcc, 0, v84, s[10:11]
	v_cmp_ge_f32_e64 s[10:11], v103, v16
	v_addc_co_u32_e64 v83, vcc, 0, v83, s[12:13]
	v_cmp_ge_f32_e64 s[12:13], v103, v17
	v_addc_co_u32_e64 v81, vcc, 0, v81, s[8:9]
	v_cmp_ge_f32_e64 s[8:9], v103, v18
	v_addc_co_u32_e64 v79, vcc, 0, v79, s[10:11]
	v_cmp_ge_f32_e64 s[10:11], v103, v19
	v_addc_co_u32_e64 v78, vcc, 0, v78, s[12:13]
	v_cmp_ge_f32_e64 s[12:13], v103, v20
	v_addc_co_u32_e64 v77, vcc, 0, v77, s[8:9]
	v_cmp_ge_f32_e64 s[8:9], v103, v21
	v_addc_co_u32_e64 v76, vcc, 0, v76, s[10:11]
	v_cmp_ge_f32_e64 s[10:11], v103, v22
	v_addc_co_u32_e64 v75, vcc, 0, v75, s[12:13]
	v_cmp_ge_f32_e64 s[12:13], v103, v23
	v_addc_co_u32_e64 v74, vcc, 0, v74, s[8:9]
	v_cmp_ge_f32_e64 s[8:9], v103, v24
	v_addc_co_u32_e64 v73, vcc, 0, v73, s[10:11]
	v_cmp_ge_f32_e64 s[10:11], v103, v25
	v_addc_co_u32_e64 v72, vcc, 0, v72, s[12:13]
	v_cmp_ge_f32_e64 s[12:13], v103, v26
	v_addc_co_u32_e64 v71, vcc, 0, v71, s[8:9]
	v_cmp_ge_f32_e64 s[8:9], v103, v27
	v_addc_co_u32_e64 v70, vcc, 0, v70, s[10:11]
	v_cmp_ge_f32_e64 s[10:11], v103, v28
	v_addc_co_u32_e64 v69, vcc, 0, v69, s[12:13]
	v_cmp_ge_f32_e64 s[12:13], v103, v29
	v_addc_co_u32_e64 v68, vcc, 0, v68, s[8:9]
	v_cmp_ge_f32_e64 s[8:9], v103, v30
	v_addc_co_u32_e64 v67, vcc, 0, v67, s[10:11]
	v_cmp_ge_f32_e64 s[10:11], v103, v31
	v_addc_co_u32_e64 v66, vcc, 0, v66, s[12:13]
	s_nop 0
	v_addc_co_u32_e64 v65, vcc, 0, v65, s[8:9]
	v_addc_co_u32_e64 v64, vcc, 0, v64, s[10:11]
	s_cmp_le_u32 s14, 32
	s_cbranch_scc1 .Lrk_done
	ds_read2_b32 v[102:103], v104 offset0:34 offset1:35
	s_waitcnt lgkmcnt(1)
	v_cmp_gt_f32_e64 s[8:9], v100, v0
	v_cmp_gt_f32_e64 s[10:11], v100, v1
	v_cmp_gt_f32_e64 s[12:13], v100, v2
	v_addc_co_u32_e64 v97, vcc, 0, v97, s[8:9]
	v_cmp_gt_f32_e64 s[8:9], v100, v3
	v_addc_co_u32_e64 v96, vcc, 0, v96, s[10:11]
	v_cmp_gt_f32_e64 s[10:11], v100, v4
	v_addc_co_u32_e64 v95, vcc, 0, v95, s[12:13]
	v_cmp_gt_f32_e64 s[12:13], v100, v5
	v_addc_co_u32_e64 v94, vcc, 0, v94, s[8:9]
	v_cmp_gt_f32_e64 s[8:9], v100, v6
	v_addc_co_u32_e64 v93, vcc, 0, v93, s[10:11]
	v_cmp_gt_f32_e64 s[10:11], v100, v7
	v_addc_co_u32_e64 v92, vcc, 0, v92, s[12:13]
	v_cmp_gt_f32_e64 s[12:13], v100, v8
	v_addc_co_u32_e64 v91, vcc, 0, v91, s[8:9]
	v_cmp_gt_f32_e64 s[8:9], v100, v9
	v_addc_co_u32_e64 v90, vcc, 0, v90, s[10:11]
	v_cmp_gt_f32_e64 s[10:11], v100, v10
	v_addc_co_u32_e64 v89, vcc, 0, v89, s[12:13]
	v_cmp_gt_f32_e64 s[12:13], v100, v11
	v_addc_co_u32_e64 v88, vcc, 0, v88, s[8:9]
	v_cmp_gt_f32_e64 s[8:9], v100, v12
	v_addc_co_u32_e64 v87, vcc, 0, v87, s[10:11]
	v_cmp_gt_f32_e64 s[10:11], v100, v13
	v_addc_co_u32_e64 v86, vcc, 0, v86, s[12:13]
	v_cmp_gt_f32_e64 s[12:13], v100, v14
	v_addc_co_u32_e64 v85, vcc, 0, v85, s[8:9]
	v_cmp_gt_f32_e64 s[8:9], v100, v15
	v_addc_co_u32_e64 v84, vcc, 0, v84, s[10:11]
	v_cmp_ge_f32_e64 s[10:11], v100, v16
	v_addc_co_u32_e64 v83, vcc, 0, v83, s[12:13]
	v_cmp_ge_f32_e64 s[12:13], v100, v17
	v_addc_co_u32_e64 v81, vcc, 0, v81, s[8:9]
	v_cmp_ge_f32_e64 s[8:9], v100, v18
	s_and_b64 s[10:11], s[10:11], s[6:7]
	v_addc_co_u32_e64 v79, vcc, 0, v79, s[10:11]
	v_cmp_ge_f32_e64 s[10:11], v100, v19
	v_addc_co_u32_e64 v78, vcc, 0, v78, s[12:13]
	v_cmp_ge_f32_e64 s[12:13], v100, v20
	v_addc_co_u32_e64 v77, vcc, 0, v77, s[8:9]
	v_cmp_ge_f32_e64 s[8:9], v100, v21
	v_addc_co_u32_e64 v76, vcc, 0, v76, s[10:11]
	v_cmp_ge_f32_e64 s[10:11], v100, v22
	v_addc_co_u32_e64 v75, vcc, 0, v75, s[12:13]
	v_cmp_ge_f32_e64 s[12:13], v100, v23
	v_addc_co_u32_e64 v74, vcc, 0, v74, s[8:9]
	v_cmp_ge_f32_e64 s[8:9], v100, v24
	v_addc_co_u32_e64 v73, vcc, 0, v73, s[10:11]
	v_cmp_ge_f32_e64 s[10:11], v100, v25
	v_addc_co_u32_e64 v72, vcc, 0, v72, s[12:13]
	v_cmp_ge_f32_e64 s[12:13], v100, v26
	v_addc_co_u32_e64 v71, vcc, 0, v71, s[8:9]
	v_cmp_ge_f32_e64 s[8:9], v100, v27
	v_addc_co_u32_e64 v70, vcc, 0, v70, s[10:11]
	v_cmp_ge_f32_e64 s[10:11], v100, v28
	v_addc_co_u32_e64 v69, vcc, 0, v69, s[12:13]
	v_cmp_ge_f32_e64 s[12:13], v100, v29
	v_addc_co_u32_e64 v68, vcc, 0, v68, s[8:9]
	v_cmp_ge_f32_e64 s[8:9], v100, v30
	v_addc_co_u32_e64 v67, vcc, 0, v67, s[10:11]
	v_cmp_ge_f32_e64 s[10:11], v100, v31
	v_addc_co_u32_e64 v66, vcc, 0, v66, s[12:13]
	s_nop 0
	v_addc_co_u32_e64 v65, vcc, 0, v65, s[8:9]
	v_addc_co_u32_e64 v64, vcc, 0, v64, s[10:11]
	s_cmp_le_u32 s14, 33
	s_cbranch_scc1 .Lrk_done
; __device__ __forceinline__ void cmp_phase(LAS unsigned char* lds, const bf16_t* __restrict__ P, const bf16_t* __restrict__ Kc, const bf16_t* __restrict__ Vc,
;                                           bf16_t* __restrict__ ocmp, unsigned long long* __restrict__ mask, int G, const int wave0) {
;     ...
; #pragma nounroll
;             for (int k = 0; k < kmax; ++k) {
;                 const float sk = sc[k];
;                 const int kk = k - hi;
; #pragma unroll
;                 for (int i = 0; i < 32; ++i) rank[i] += ((sk > s[i]) || ((sk == s[i]) && (kk < 2 * i))) ? 1 : 0;
;             }
	v_cmp_gt_f32_e64 s[8:9], v101, v0
	v_cmp_gt_f32_e64 s[10:11], v101, v1
	v_cmp_gt_f32_e64 s[12:13], v101, v2
	v_addc_co_u32_e64 v97, vcc, 0, v97, s[8:9]
	v_cmp_gt_f32_e64 s[8:9], v101, v3
	v_addc_co_u32_e64 v96, vcc, 0, v96, s[10:11]
	v_cmp_gt_f32_e64 s[10:11], v101, v4
	v_addc_co_u32_e64 v95, vcc, 0, v95, s[12:13]
	v_cmp_gt_f32_e64 s[12:13], v101, v5
	v_addc_co_u32_e64 v94, vcc, 0, v94, s[8:9]
	v_cmp_gt_f32_e64 s[8:9], v101, v6
	v_addc_co_u32_e64 v93, vcc, 0, v93, s[10:11]
	v_cmp_gt_f32_e64 s[10:11], v101, v7
	v_addc_co_u32_e64 v92, vcc, 0, v92, s[12:13]
	v_cmp_gt_f32_e64 s[12:13], v101, v8
	v_addc_co_u32_e64 v91, vcc, 0, v91, s[8:9]
	v_cmp_gt_f32_e64 s[8:9], v101, v9
	v_addc_co_u32_e64 v90, vcc, 0, v90, s[10:11]
	v_cmp_gt_f32_e64 s[10:11], v101, v10
	v_addc_co_u32_e64 v89, vcc, 0, v89, s[12:13]
	v_cmp_gt_f32_e64 s[12:13], v101, v11
	v_addc_co_u32_e64 v88, vcc, 0, v88, s[8:9]
	v_cmp_gt_f32_e64 s[8:9], v101, v12
	v_addc_co_u32_e64 v87, vcc, 0, v87, s[10:11]
	v_cmp_gt_f32_e64 s[10:11], v101, v13
	v_addc_co_u32_e64 v86, vcc, 0, v86, s[12:13]
	v_cmp_gt_f32_e64 s[12:13], v101, v14
	v_addc_co_u32_e64 v85, vcc, 0, v85, s[8:9]
	v_cmp_gt_f32_e64 s[8:9], v101, v15
	v_addc_co_u32_e64 v84, vcc, 0, v84, s[10:11]
	v_cmp_gt_f32_e64 s[10:11], v101, v16
	v_addc_co_u32_e64 v83, vcc, 0, v83, s[12:13]
	v_cmp_ge_f32_e64 s[12:13], v101, v17
	v_addc_co_u32_e64 v81, vcc, 0, v81, s[8:9]
	v_cmp_ge_f32_e64 s[8:9], v101, v18
	v_addc_co_u32_e64 v79, vcc, 0, v79, s[10:11]
	v_cmp_ge_f32_e64 s[10:11], v101, v19
	v_addc_co_u32_e64 v78, vcc, 0, v78, s[12:13]
	v_cmp_ge_f32_e64 s[12:13], v101, v20
	v_addc_co_u32_e64 v77, vcc, 0, v77, s[8:9]
	v_cmp_ge_f32_e64 s[8:9], v101, v21
	v_addc_co_u32_e64 v76, vcc, 0, v76, s[10:11]
	v_cmp_ge_f32_e64 s[10:11], v101, v22
	v_addc_co_u32_e64 v75, vcc, 0, v75, s[12:13]
	v_cmp_ge_f32_e64 s[12:13], v101, v23
	v_addc_co_u32_e64 v74, vcc, 0, v74, s[8:9]
	v_cmp_ge_f32_e64 s[8:9], v101, v24
	v_addc_co_u32_e64 v73, vcc, 0, v73, s[10:11]
	v_cmp_ge_f32_e64 s[10:11], v101, v25
	v_addc_co_u32_e64 v72, vcc, 0, v72, s[12:13]
	v_cmp_ge_f32_e64 s[12:13], v101, v26
	v_addc_co_u32_e64 v71, vcc, 0, v71, s[8:9]
	v_cmp_ge_f32_e64 s[8:9], v101, v27
	v_addc_co_u32_e64 v70, vcc, 0, v70, s[10:11]
	v_cmp_ge_f32_e64 s[10:11], v101, v28
	v_addc_co_u32_e64 v69, vcc, 0, v69, s[12:13]
	v_cmp_ge_f32_e64 s[12:13], v101, v29
	v_addc_co_u32_e64 v68, vcc, 0, v68, s[8:9]
	v_cmp_ge_f32_e64 s[8:9], v101, v30
	v_addc_co_u32_e64 v67, vcc, 0, v67, s[10:11]
	v_cmp_ge_f32_e64 s[10:11], v101, v31
	v_addc_co_u32_e64 v66, vcc, 0, v66, s[12:13]
	s_nop 0
	v_addc_co_u32_e64 v65, vcc, 0, v65, s[8:9]
	v_addc_co_u32_e64 v64, vcc, 0, v64, s[10:11]
	s_cmp_le_u32 s14, 34
	s_cbranch_scc1 .Lrk_done
	ds_read2_b32 v[100:101], v104 offset0:36 offset1:37
	s_waitcnt lgkmcnt(1)
	v_cmp_gt_f32_e64 s[8:9], v102, v0
	v_cmp_gt_f32_e64 s[10:11], v102, v1
	v_cmp_gt_f32_e64 s[12:13], v102, v2
	v_addc_co_u32_e64 v97, vcc, 0, v97, s[8:9]
	v_cmp_gt_f32_e64 s[8:9], v102, v3
	v_addc_co_u32_e64 v96, vcc, 0, v96, s[10:11]
	v_cmp_gt_f32_e64 s[10:11], v102, v4
	v_addc_co_u32_e64 v95, vcc, 0, v95, s[12:13]
	v_cmp_gt_f32_e64 s[12:13], v102, v5
	v_addc_co_u32_e64 v94, vcc, 0, v94, s[8:9]
	v_cmp_gt_f32_e64 s[8:9], v102, v6
	v_addc_co_u32_e64 v93, vcc, 0, v93, s[10:11]
	v_cmp_gt_f32_e64 s[10:11], v102, v7
	v_addc_co_u32_e64 v92, vcc, 0, v92, s[12:13]
	v_cmp_gt_f32_e64 s[12:13], v102, v8
	v_addc_co_u32_e64 v91, vcc, 0, v91, s[8:9]
	v_cmp_gt_f32_e64 s[8:9], v102, v9
	v_addc_co_u32_e64 v90, vcc, 0, v90, s[10:11]
	v_cmp_gt_f32_e64 s[10:11], v102, v10
	v_addc_co_u32_e64 v89, vcc, 0, v89, s[12:13]
	v_cmp_gt_f32_e64 s[12:13], v102, v11
	v_addc_co_u32_e64 v88, vcc, 0, v88, s[8:9]
	v_cmp_gt_f32_e64 s[8:9], v102, v12
	v_addc_co_u32_e64 v87, vcc, 0, v87, s[10:11]
	v_cmp_gt_f32_e64 s[10:11], v102, v13
	v_addc_co_u32_e64 v86, vcc, 0, v86, s[12:13]
	v_cmp_gt_f32_e64 s[12:13], v102, v14
	v_addc_co_u32_e64 v85, vcc, 0, v85, s[8:9]
	v_cmp_gt_f32_e64 s[8:9], v102, v15
	v_addc_co_u32_e64 v84, vcc, 0, v84, s[10:11]
	v_cmp_gt_f32_e64 s[10:11], v102, v16
	v_addc_co_u32_e64 v83, vcc, 0, v83, s[12:13]
	v_cmp_ge_f32_e64 s[12:13], v102, v17
	v_addc_co_u32_e64 v81, vcc, 0, v81, s[8:9]
	v_cmp_ge_f32_e64 s[8:9], v102, v18
	v_addc_co_u32_e64 v79, vcc, 0, v79, s[10:11]
	v_cmp_ge_f32_e64 s[10:11], v102, v19
	s_and_b64 s[12:13], s[12:13], s[6:7]
	v_addc_co_u32_e64 v78, vcc, 0, v78, s[12:13]
	v_cmp_ge_f32_e64 s[12:13], v102, v20
	v_addc_co_u32_e64 v77, vcc, 0, v77, s[8:9]
	v_cmp_ge_f32_e64 s[8:9], v102, v21
	v_addc_co_u32_e64 v76, vcc, 0, v76, s[10:11]
	v_cmp_ge_f32_e64 s[10:11], v102, v22
	v_addc_co_u32_e64 v75, vcc, 0, v75, s[12:13]
	v_cmp_ge_f32_e64 s[12:13], v102, v23
	v_addc_co_u32_e64 v74, vcc, 0, v74, s[8:9]
	v_cmp_ge_f32_e64 s[8:9], v102, v24
	v_addc_co_u32_e64 v73, vcc, 0, v73, s[10:11]
	v_cmp_ge_f32_e64 s[10:11], v102, v25
	v_addc_co_u32_e64 v72, vcc, 0, v72, s[12:13]
	v_cmp_ge_f32_e64 s[12:13], v102, v26
	v_addc_co_u32_e64 v71, vcc, 0, v71, s[8:9]
	v_cmp_ge_f32_e64 s[8:9], v102, v27
	v_addc_co_u32_e64 v70, vcc, 0, v70, s[10:11]
	v_cmp_ge_f32_e64 s[10:11], v102, v28
	v_addc_co_u32_e64 v69, vcc, 0, v69, s[12:13]
	v_cmp_ge_f32_e64 s[12:13], v102, v29
	v_addc_co_u32_e64 v68, vcc, 0, v68, s[8:9]
	v_cmp_ge_f32_e64 s[8:9], v102, v30
	v_addc_co_u32_e64 v67, vcc, 0, v67, s[10:11]
	v_cmp_ge_f32_e64 s[10:11], v102, v31
	v_addc_co_u32_e64 v66, vcc, 0, v66, s[12:13]
	s_nop 0
	v_addc_co_u32_e64 v65, vcc, 0, v65, s[8:9]
	v_addc_co_u32_e64 v64, vcc, 0, v64, s[10:11]
	s_cmp_le_u32 s14, 35
	s_cbranch_scc1 .Lrk_done
; __device__ __forceinline__ void cmp_phase(LAS unsigned char* lds, const bf16_t* __restrict__ P, const bf16_t* __restrict__ Kc, const bf16_t* __restrict__ Vc,
;                                           bf16_t* __restrict__ ocmp, unsigned long long* __restrict__ mask, int G, const int wave0) {
;     ...
; #pragma nounroll
;             for (int k = 0; k < kmax; ++k) {
;                 const float sk = sc[k];
;                 const int kk = k - hi;
; #pragma unroll
;                 for (int i = 0; i < 32; ++i) rank[i] += ((sk > s[i]) || ((sk == s[i]) && (kk < 2 * i))) ? 1 : 0;
;             }
	v_cmp_gt_f32_e64 s[8:9], v103, v0
	v_cmp_gt_f32_e64 s[10:11], v103, v1
	v_cmp_gt_f32_e64 s[12:13], v103, v2
	v_addc_co_u32_e64 v97, vcc, 0, v97, s[8:9]
	v_cmp_gt_f32_e64 s[8:9], v103, v3
	v_addc_co_u32_e64 v96, vcc, 0, v96, s[10:11]
	v_cmp_gt_f32_e64 s[10:11], v103, v4
	v_addc_co_u32_e64 v95, vcc, 0, v95, s[12:13]
	v_cmp_gt_f32_e64 s[12:13], v103, v5
	v_addc_co_u32_e64 v94, vcc, 0, v94, s[8:9]
	v_cmp_gt_f32_e64 s[8:9], v103, v6
	v_addc_co_u32_e64 v93, vcc, 0, v93, s[10:11]
	v_cmp_gt_f32_e64 s[10:11], v103, v7
	v_addc_co_u32_e64 v92, vcc, 0, v92, s[12:13]
	v_cmp_gt_f32_e64 s[12:13], v103, v8
	v_addc_co_u32_e64 v91, vcc, 0, v91, s[8:9]
	v_cmp_gt_f32_e64 s[8:9], v103, v9
	v_addc_co_u32_e64 v90, vcc, 0, v90, s[10:11]
	v_cmp_gt_f32_e64 s[10:11], v103, v10
	v_addc_co_u32_e64 v89, vcc, 0, v89, s[12:13]
	v_cmp_gt_f32_e64 s[12:13], v103, v11
	v_addc_co_u32_e64 v88, vcc, 0, v88, s[8:9]
	v_cmp_gt_f32_e64 s[8:9], v103, v12
	v_addc_co_u32_e64 v87, vcc, 0, v87, s[10:11]
	v_cmp_gt_f32_e64 s[10:11], v103, v13
	v_addc_co_u32_e64 v86, vcc, 0, v86, s[12:13]
	v_cmp_gt_f32_e64 s[12:13], v103, v14
	v_addc_co_u32_e64 v85, vcc, 0, v85, s[8:9]
	v_cmp_gt_f32_e64 s[8:9], v103, v15
	v_addc_co_u32_e64 v84, vcc, 0, v84, s[10:11]
	v_cmp_gt_f32_e64 s[10:11], v103, v16
	v_addc_co_u32_e64 v83, vcc, 0, v83, s[12:13]
	v_cmp_gt_f32_e64 s[12:13], v103, v17
	v_addc_co_u32_e64 v81, vcc, 0, v81, s[8:9]
	v_cmp_ge_f32_e64 s[8:9], v103, v18
	v_addc_co_u32_e64 v79, vcc, 0, v79, s[10:11]
	v_cmp_ge_f32_e64 s[10:11], v103, v19
	v_addc_co_u32_e64 v78, vcc, 0, v78, s[12:13]
	v_cmp_ge_f32_e64 s[12:13], v103, v20
	v_addc_co_u32_e64 v77, vcc, 0, v77, s[8:9]
	v_cmp_ge_f32_e64 s[8:9], v103, v21
	v_addc_co_u32_e64 v76, vcc, 0, v76, s[10:11]
	v_cmp_ge_f32_e64 s[10:11], v103, v22
	v_addc_co_u32_e64 v75, vcc, 0, v75, s[12:13]
	v_cmp_ge_f32_e64 s[12:13], v103, v23
	v_addc_co_u32_e64 v74, vcc, 0, v74, s[8:9]
	v_cmp_ge_f32_e64 s[8:9], v103, v24
	v_addc_co_u32_e64 v73, vcc, 0, v73, s[10:11]
	v_cmp_ge_f32_e64 s[10:11], v103, v25
	v_addc_co_u32_e64 v72, vcc, 0, v72, s[12:13]
	v_cmp_ge_f32_e64 s[12:13], v103, v26
	v_addc_co_u32_e64 v71, vcc, 0, v71, s[8:9]
	v_cmp_ge_f32_e64 s[8:9], v103, v27
	v_addc_co_u32_e64 v70, vcc, 0, v70, s[10:11]
	v_cmp_ge_f32_e64 s[10:11], v103, v28
	v_addc_co_u32_e64 v69, vcc, 0, v69, s[12:13]
	v_cmp_ge_f32_e64 s[12:13], v103, v29
	v_addc_co_u32_e64 v68, vcc, 0, v68, s[8:9]
	v_cmp_ge_f32_e64 s[8:9], v103, v30
	v_addc_co_u32_e64 v67, vcc, 0, v67, s[10:11]
	v_cmp_ge_f32_e64 s[10:11], v103, v31
	v_addc_co_u32_e64 v66, vcc, 0, v66, s[12:13]
	s_nop 0
	v_addc_co_u32_e64 v65, vcc, 0, v65, s[8:9]
	v_addc_co_u32_e64 v64, vcc, 0, v64, s[10:11]
	s_cmp_le_u32 s14, 36
	s_cbranch_scc1 .Lrk_done
	ds_read2_b32 v[102:103], v104 offset0:38 offset1:39
	s_waitcnt lgkmcnt(1)
	v_cmp_gt_f32_e64 s[8:9], v100, v0
	v_cmp_gt_f32_e64 s[10:11], v100, v1
	v_cmp_gt_f32_e64 s[12:13], v100, v2
	v_addc_co_u32_e64 v97, vcc, 0, v97, s[8:9]
	v_cmp_gt_f32_e64 s[8:9], v100, v3
	v_addc_co_u32_e64 v96, vcc, 0, v96, s[10:11]
	v_cmp_gt_f32_e64 s[10:11], v100, v4
	v_addc_co_u32_e64 v95, vcc, 0, v95, s[12:13]
	v_cmp_gt_f32_e64 s[12:13], v100, v5
	v_addc_co_u32_e64 v94, vcc, 0, v94, s[8:9]
	v_cmp_gt_f32_e64 s[8:9], v100, v6
	v_addc_co_u32_e64 v93, vcc, 0, v93, s[10:11]
	v_cmp_gt_f32_e64 s[10:11], v100, v7
	v_addc_co_u32_e64 v92, vcc, 0, v92, s[12:13]
	v_cmp_gt_f32_e64 s[12:13], v100, v8
	v_addc_co_u32_e64 v91, vcc, 0, v91, s[8:9]
	v_cmp_gt_f32_e64 s[8:9], v100, v9
	v_addc_co_u32_e64 v90, vcc, 0, v90, s[10:11]
	v_cmp_gt_f32_e64 s[10:11], v100, v10
	v_addc_co_u32_e64 v89, vcc, 0, v89, s[12:13]
	v_cmp_gt_f32_e64 s[12:13], v100, v11
	v_addc_co_u32_e64 v88, vcc, 0, v88, s[8:9]
	v_cmp_gt_f32_e64 s[8:9], v100, v12
	v_addc_co_u32_e64 v87, vcc, 0, v87, s[10:11]
	v_cmp_gt_f32_e64 s[10:11], v100, v13
	v_addc_co_u32_e64 v86, vcc, 0, v86, s[12:13]
	v_cmp_gt_f32_e64 s[12:13], v100, v14
	v_addc_co_u32_e64 v85, vcc, 0, v85, s[8:9]
	v_cmp_gt_f32_e64 s[8:9], v100, v15
	v_addc_co_u32_e64 v84, vcc, 0, v84, s[10:11]
	v_cmp_gt_f32_e64 s[10:11], v100, v16
	v_addc_co_u32_e64 v83, vcc, 0, v83, s[12:13]
	v_cmp_gt_f32_e64 s[12:13], v100, v17
	v_addc_co_u32_e64 v81, vcc, 0, v81, s[8:9]
	v_cmp_ge_f32_e64 s[8:9], v100, v18
	v_addc_co_u32_e64 v79, vcc, 0, v79, s[10:11]
	v_cmp_ge_f32_e64 s[10:11], v100, v19
	v_addc_co_u32_e64 v78, vcc, 0, v78, s[12:13]
	v_cmp_ge_f32_e64 s[12:13], v100, v20
	s_and_b64 s[8:9], s[8:9], s[6:7]
	v_addc_co_u32_e64 v77, vcc, 0, v77, s[8:9]
	v_cmp_ge_f32_e64 s[8:9], v100, v21
	v_addc_co_u32_e64 v76, vcc, 0, v76, s[10:11]
	v_cmp_ge_f32_e64 s[10:11], v100, v22
	v_addc_co_u32_e64 v75, vcc, 0, v75, s[12:13]
	v_cmp_ge_f32_e64 s[12:13], v100, v23
	v_addc_co_u32_e64 v74, vcc, 0, v74, s[8:9]
	v_cmp_ge_f32_e64 s[8:9], v100, v24
	v_addc_co_u32_e64 v73, vcc, 0, v73, s[10:11]
	v_cmp_ge_f32_e64 s[10:11], v100, v25
	v_addc_co_u32_e64 v72, vcc, 0, v72, s[12:13]
	v_cmp_ge_f32_e64 s[12:13], v100, v26
	v_addc_co_u32_e64 v71, vcc, 0, v71, s[8:9]
	v_cmp_ge_f32_e64 s[8:9], v100, v27
	v_addc_co_u32_e64 v70, vcc, 0, v70, s[10:11]
	v_cmp_ge_f32_e64 s[10:11], v100, v28
	v_addc_co_u32_e64 v69, vcc, 0, v69, s[12:13]
	v_cmp_ge_f32_e64 s[12:13], v100, v29
	v_addc_co_u32_e64 v68, vcc, 0, v68, s[8:9]
	v_cmp_ge_f32_e64 s[8:9], v100, v30
	v_addc_co_u32_e64 v67, vcc, 0, v67, s[10:11]
	v_cmp_ge_f32_e64 s[10:11], v100, v31
	v_addc_co_u32_e64 v66, vcc, 0, v66, s[12:13]
	s_nop 0
	v_addc_co_u32_e64 v65, vcc, 0, v65, s[8:9]
	v_addc_co_u32_e64 v64, vcc, 0, v64, s[10:11]
	s_cmp_le_u32 s14, 37
	s_cbranch_scc1 .Lrk_done
; __device__ __forceinline__ void cmp_phase(LAS unsigned char* lds, const bf16_t* __restrict__ P, const bf16_t* __restrict__ Kc, const bf16_t* __restrict__ Vc,
;                                           bf16_t* __restrict__ ocmp, unsigned long long* __restrict__ mask, int G, const int wave0) {
;     ...
; #pragma nounroll
;             for (int k = 0; k < kmax; ++k) {
;                 const float sk = sc[k];
;                 const int kk = k - hi;
; #pragma unroll
;                 for (int i = 0; i < 32; ++i) rank[i] += ((sk > s[i]) || ((sk == s[i]) && (kk < 2 * i))) ? 1 : 0;
;             }
	v_cmp_gt_f32_e64 s[8:9], v101, v0
	v_cmp_gt_f32_e64 s[10:11], v101, v1
	v_cmp_gt_f32_e64 s[12:13], v101, v2
	v_addc_co_u32_e64 v97, vcc, 0, v97, s[8:9]
	v_cmp_gt_f32_e64 s[8:9], v101, v3
	v_addc_co_u32_e64 v96, vcc, 0, v96, s[10:11]
	v_cmp_gt_f32_e64 s[10:11], v101, v4
	v_addc_co_u32_e64 v95, vcc, 0, v95, s[12:13]
	v_cmp_gt_f32_e64 s[12:13], v101, v5
	v_addc_co_u32_e64 v94, vcc, 0, v94, s[8:9]
	v_cmp_gt_f32_e64 s[8:9], v101, v6
	v_addc_co_u32_e64 v93, vcc, 0, v93, s[10:11]
	v_cmp_gt_f32_e64 s[10:11], v101, v7
	v_addc_co_u32_e64 v92, vcc, 0, v92, s[12:13]
	v_cmp_gt_f32_e64 s[12:13], v101, v8
	v_addc_co_u32_e64 v91, vcc, 0, v91, s[8:9]
	v_cmp_gt_f32_e64 s[8:9], v101, v9
	v_addc_co_u32_e64 v90, vcc, 0, v90, s[10:11]
	v_cmp_gt_f32_e64 s[10:11], v101, v10
	v_addc_co_u32_e64 v89, vcc, 0, v89, s[12:13]
	v_cmp_gt_f32_e64 s[12:13], v101, v11
	v_addc_co_u32_e64 v88, vcc, 0, v88, s[8:9]
	v_cmp_gt_f32_e64 s[8:9], v101, v12
	v_addc_co_u32_e64 v87, vcc, 0, v87, s[10:11]
	v_cmp_gt_f32_e64 s[10:11], v101, v13
	v_addc_co_u32_e64 v86, vcc, 0, v86, s[12:13]
	v_cmp_gt_f32_e64 s[12:13], v101, v14
	v_addc_co_u32_e64 v85, vcc, 0, v85, s[8:9]
	v_cmp_gt_f32_e64 s[8:9], v101, v15
	v_addc_co_u32_e64 v84, vcc, 0, v84, s[10:11]
	v_cmp_gt_f32_e64 s[10:11], v101, v16
	v_addc_co_u32_e64 v83, vcc, 0, v83, s[12:13]
	v_cmp_gt_f32_e64 s[12:13], v101, v17
	v_addc_co_u32_e64 v81, vcc, 0, v81, s[8:9]
	v_cmp_gt_f32_e64 s[8:9], v101, v18
	v_addc_co_u32_e64 v79, vcc, 0, v79, s[10:11]
	v_cmp_ge_f32_e64 s[10:11], v101, v19
	v_addc_co_u32_e64 v78, vcc, 0, v78, s[12:13]
	v_cmp_ge_f32_e64 s[12:13], v101, v20
	v_addc_co_u32_e64 v77, vcc, 0, v77, s[8:9]
	v_cmp_ge_f32_e64 s[8:9], v101, v21
	v_addc_co_u32_e64 v76, vcc, 0, v76, s[10:11]
	v_cmp_ge_f32_e64 s[10:11], v101, v22
	v_addc_co_u32_e64 v75, vcc, 0, v75, s[12:13]
	v_cmp_ge_f32_e64 s[12:13], v101, v23
	v_addc_co_u32_e64 v74, vcc, 0, v74, s[8:9]
	v_cmp_ge_f32_e64 s[8:9], v101, v24
	v_addc_co_u32_e64 v73, vcc, 0, v73, s[10:11]
	v_cmp_ge_f32_e64 s[10:11], v101, v25
	v_addc_co_u32_e64 v72, vcc, 0, v72, s[12:13]
	v_cmp_ge_f32_e64 s[12:13], v101, v26
	v_addc_co_u32_e64 v71, vcc, 0, v71, s[8:9]
	v_cmp_ge_f32_e64 s[8:9], v101, v27
	v_addc_co_u32_e64 v70, vcc, 0, v70, s[10:11]
	v_cmp_ge_f32_e64 s[10:11], v101, v28
	v_addc_co_u32_e64 v69, vcc, 0, v69, s[12:13]
	v_cmp_ge_f32_e64 s[12:13], v101, v29
	v_addc_co_u32_e64 v68, vcc, 0, v68, s[8:9]
	v_cmp_ge_f32_e64 s[8:9], v101, v30
	v_addc_co_u32_e64 v67, vcc, 0, v67, s[10:11]
	v_cmp_ge_f32_e64 s[10:11], v101, v31
	v_addc_co_u32_e64 v66, vcc, 0, v66, s[12:13]
	s_nop 0
	v_addc_co_u32_e64 v65, vcc, 0, v65, s[8:9]
	v_addc_co_u32_e64 v64, vcc, 0, v64, s[10:11]
	s_cmp_le_u32 s14, 38
	s_cbranch_scc1 .Lrk_done
	ds_read2_b32 v[100:101], v104 offset0:40 offset1:41
	s_waitcnt lgkmcnt(1)
	v_cmp_gt_f32_e64 s[8:9], v102, v0
	v_cmp_gt_f32_e64 s[10:11], v102, v1
	v_cmp_gt_f32_e64 s[12:13], v102, v2
	v_addc_co_u32_e64 v97, vcc, 0, v97, s[8:9]
	v_cmp_gt_f32_e64 s[8:9], v102, v3
	v_addc_co_u32_e64 v96, vcc, 0, v96, s[10:11]
	v_cmp_gt_f32_e64 s[10:11], v102, v4
	v_addc_co_u32_e64 v95, vcc, 0, v95, s[12:13]
	v_cmp_gt_f32_e64 s[12:13], v102, v5
	v_addc_co_u32_e64 v94, vcc, 0, v94, s[8:9]
	v_cmp_gt_f32_e64 s[8:9], v102, v6
	v_addc_co_u32_e64 v93, vcc, 0, v93, s[10:11]
	v_cmp_gt_f32_e64 s[10:11], v102, v7
	v_addc_co_u32_e64 v92, vcc, 0, v92, s[12:13]
	v_cmp_gt_f32_e64 s[12:13], v102, v8
	v_addc_co_u32_e64 v91, vcc, 0, v91, s[8:9]
	v_cmp_gt_f32_e64 s[8:9], v102, v9
	v_addc_co_u32_e64 v90, vcc, 0, v90, s[10:11]
	v_cmp_gt_f32_e64 s[10:11], v102, v10
	v_addc_co_u32_e64 v89, vcc, 0, v89, s[12:13]
	v_cmp_gt_f32_e64 s[12:13], v102, v11
	v_addc_co_u32_e64 v88, vcc, 0, v88, s[8:9]
	v_cmp_gt_f32_e64 s[8:9], v102, v12
	v_addc_co_u32_e64 v87, vcc, 0, v87, s[10:11]
	v_cmp_gt_f32_e64 s[10:11], v102, v13
	v_addc_co_u32_e64 v86, vcc, 0, v86, s[12:13]
	v_cmp_gt_f32_e64 s[12:13], v102, v14
	v_addc_co_u32_e64 v85, vcc, 0, v85, s[8:9]
	v_cmp_gt_f32_e64 s[8:9], v102, v15
	v_addc_co_u32_e64 v84, vcc, 0, v84, s[10:11]
	v_cmp_gt_f32_e64 s[10:11], v102, v16
	v_addc_co_u32_e64 v83, vcc, 0, v83, s[12:13]
	v_cmp_gt_f32_e64 s[12:13], v102, v17
	v_addc_co_u32_e64 v81, vcc, 0, v81, s[8:9]
	v_cmp_gt_f32_e64 s[8:9], v102, v18
	v_addc_co_u32_e64 v79, vcc, 0, v79, s[10:11]
	v_cmp_ge_f32_e64 s[10:11], v102, v19
	v_addc_co_u32_e64 v78, vcc, 0, v78, s[12:13]
	v_cmp_ge_f32_e64 s[12:13], v102, v20
	v_addc_co_u32_e64 v77, vcc, 0, v77, s[8:9]
	v_cmp_ge_f32_e64 s[8:9], v102, v21
	s_and_b64 s[10:11], s[10:11], s[6:7]
	v_addc_co_u32_e64 v76, vcc, 0, v76, s[10:11]
	v_cmp_ge_f32_e64 s[10:11], v102, v22
	v_addc_co_u32_e64 v75, vcc, 0, v75, s[12:13]
	v_cmp_ge_f32_e64 s[12:13], v102, v23
	v_addc_co_u32_e64 v74, vcc, 0, v74, s[8:9]
	v_cmp_ge_f32_e64 s[8:9], v102, v24
	v_addc_co_u32_e64 v73, vcc, 0, v73, s[10:11]
	v_cmp_ge_f32_e64 s[10:11], v102, v25
	v_addc_co_u32_e64 v72, vcc, 0, v72, s[12:13]
	v_cmp_ge_f32_e64 s[12:13], v102, v26
	v_addc_co_u32_e64 v71, vcc, 0, v71, s[8:9]
	v_cmp_ge_f32_e64 s[8:9], v102, v27
	v_addc_co_u32_e64 v70, vcc, 0, v70, s[10:11]
	v_cmp_ge_f32_e64 s[10:11], v102, v28
	v_addc_co_u32_e64 v69, vcc, 0, v69, s[12:13]
	v_cmp_ge_f32_e64 s[12:13], v102, v29
	v_addc_co_u32_e64 v68, vcc, 0, v68, s[8:9]
	v_cmp_ge_f32_e64 s[8:9], v102, v30
	v_addc_co_u32_e64 v67, vcc, 0, v67, s[10:11]
	v_cmp_ge_f32_e64 s[10:11], v102, v31
	v_addc_co_u32_e64 v66, vcc, 0, v66, s[12:13]
	s_nop 0
	v_addc_co_u32_e64 v65, vcc, 0, v65, s[8:9]
	v_addc_co_u32_e64 v64, vcc, 0, v64, s[10:11]
	s_cmp_le_u32 s14, 39
	s_cbranch_scc1 .Lrk_done
; __device__ __forceinline__ void cmp_phase(LAS unsigned char* lds, const bf16_t* __restrict__ P, const bf16_t* __restrict__ Kc, const bf16_t* __restrict__ Vc,
;                                           bf16_t* __restrict__ ocmp, unsigned long long* __restrict__ mask, int G, const int wave0) {
;     ...
; #pragma nounroll
;             for (int k = 0; k < kmax; ++k) {
;                 const float sk = sc[k];
;                 const int kk = k - hi;
; #pragma unroll
;                 for (int i = 0; i < 32; ++i) rank[i] += ((sk > s[i]) || ((sk == s[i]) && (kk < 2 * i))) ? 1 : 0;
;             }
	v_cmp_gt_f32_e64 s[8:9], v103, v0
	v_cmp_gt_f32_e64 s[10:11], v103, v1
	v_cmp_gt_f32_e64 s[12:13], v103, v2
	v_addc_co_u32_e64 v97, vcc, 0, v97, s[8:9]
	v_cmp_gt_f32_e64 s[8:9], v103, v3
	v_addc_co_u32_e64 v96, vcc, 0, v96, s[10:11]
	v_cmp_gt_f32_e64 s[10:11], v103, v4
	v_addc_co_u32_e64 v95, vcc, 0, v95, s[12:13]
	v_cmp_gt_f32_e64 s[12:13], v103, v5
	v_addc_co_u32_e64 v94, vcc, 0, v94, s[8:9]
	v_cmp_gt_f32_e64 s[8:9], v103, v6
	v_addc_co_u32_e64 v93, vcc, 0, v93, s[10:11]
	v_cmp_gt_f32_e64 s[10:11], v103, v7
	v_addc_co_u32_e64 v92, vcc, 0, v92, s[12:13]
	v_cmp_gt_f32_e64 s[12:13], v103, v8
	v_addc_co_u32_e64 v91, vcc, 0, v91, s[8:9]
	v_cmp_gt_f32_e64 s[8:9], v103, v9
	v_addc_co_u32_e64 v90, vcc, 0, v90, s[10:11]
	v_cmp_gt_f32_e64 s[10:11], v103, v10
	v_addc_co_u32_e64 v89, vcc, 0, v89, s[12:13]
	v_cmp_gt_f32_e64 s[12:13], v103, v11
	v_addc_co_u32_e64 v88, vcc, 0, v88, s[8:9]
	v_cmp_gt_f32_e64 s[8:9], v103, v12
	v_addc_co_u32_e64 v87, vcc, 0, v87, s[10:11]
	v_cmp_gt_f32_e64 s[10:11], v103, v13
	v_addc_co_u32_e64 v86, vcc, 0, v86, s[12:13]
	v_cmp_gt_f32_e64 s[12:13], v103, v14
	v_addc_co_u32_e64 v85, vcc, 0, v85, s[8:9]
	v_cmp_gt_f32_e64 s[8:9], v103, v15
	v_addc_co_u32_e64 v84, vcc, 0, v84, s[10:11]
	v_cmp_gt_f32_e64 s[10:11], v103, v16
	v_addc_co_u32_e64 v83, vcc, 0, v83, s[12:13]
	v_cmp_gt_f32_e64 s[12:13], v103, v17
	v_addc_co_u32_e64 v81, vcc, 0, v81, s[8:9]
	v_cmp_gt_f32_e64 s[8:9], v103, v18
	v_addc_co_u32_e64 v79, vcc, 0, v79, s[10:11]
	v_cmp_gt_f32_e64 s[10:11], v103, v19
	v_addc_co_u32_e64 v78, vcc, 0, v78, s[12:13]
	v_cmp_ge_f32_e64 s[12:13], v103, v20
	v_addc_co_u32_e64 v77, vcc, 0, v77, s[8:9]
	v_cmp_ge_f32_e64 s[8:9], v103, v21
	v_addc_co_u32_e64 v76, vcc, 0, v76, s[10:11]
	v_cmp_ge_f32_e64 s[10:11], v103, v22
	v_addc_co_u32_e64 v75, vcc, 0, v75, s[12:13]
	v_cmp_ge_f32_e64 s[12:13], v103, v23
	v_addc_co_u32_e64 v74, vcc, 0, v74, s[8:9]
	v_cmp_ge_f32_e64 s[8:9], v103, v24
	v_addc_co_u32_e64 v73, vcc, 0, v73, s[10:11]
	v_cmp_ge_f32_e64 s[10:11], v103, v25
	v_addc_co_u32_e64 v72, vcc, 0, v72, s[12:13]
	v_cmp_ge_f32_e64 s[12:13], v103, v26
	v_addc_co_u32_e64 v71, vcc, 0, v71, s[8:9]
	v_cmp_ge_f32_e64 s[8:9], v103, v27
	v_addc_co_u32_e64 v70, vcc, 0, v70, s[10:11]
	v_cmp_ge_f32_e64 s[10:11], v103, v28
	v_addc_co_u32_e64 v69, vcc, 0, v69, s[12:13]
	v_cmp_ge_f32_e64 s[12:13], v103, v29
	v_addc_co_u32_e64 v68, vcc, 0, v68, s[8:9]
	v_cmp_ge_f32_e64 s[8:9], v103, v30
	v_addc_co_u32_e64 v67, vcc, 0, v67, s[10:11]
	v_cmp_ge_f32_e64 s[10:11], v103, v31
	v_addc_co_u32_e64 v66, vcc, 0, v66, s[12:13]
	s_nop 0
	v_addc_co_u32_e64 v65, vcc, 0, v65, s[8:9]
	v_addc_co_u32_e64 v64, vcc, 0, v64, s[10:11]
	s_cmp_le_u32 s14, 40
	s_cbranch_scc1 .Lrk_done
	ds_read2_b32 v[102:103], v104 offset0:42 offset1:43
	s_waitcnt lgkmcnt(1)
	v_cmp_gt_f32_e64 s[8:9], v100, v0
	v_cmp_gt_f32_e64 s[10:11], v100, v1
	v_cmp_gt_f32_e64 s[12:13], v100, v2
	v_addc_co_u32_e64 v97, vcc, 0, v97, s[8:9]
	v_cmp_gt_f32_e64 s[8:9], v100, v3
	v_addc_co_u32_e64 v96, vcc, 0, v96, s[10:11]
	v_cmp_gt_f32_e64 s[10:11], v100, v4
	v_addc_co_u32_e64 v95, vcc, 0, v95, s[12:13]
	v_cmp_gt_f32_e64 s[12:13], v100, v5
	v_addc_co_u32_e64 v94, vcc, 0, v94, s[8:9]
	v_cmp_gt_f32_e64 s[8:9], v100, v6
	v_addc_co_u32_e64 v93, vcc, 0, v93, s[10:11]
	v_cmp_gt_f32_e64 s[10:11], v100, v7
	v_addc_co_u32_e64 v92, vcc, 0, v92, s[12:13]
	v_cmp_gt_f32_e64 s[12:13], v100, v8
	v_addc_co_u32_e64 v91, vcc, 0, v91, s[8:9]
	v_cmp_gt_f32_e64 s[8:9], v100, v9
	v_addc_co_u32_e64 v90, vcc, 0, v90, s[10:11]
	v_cmp_gt_f32_e64 s[10:11], v100, v10
	v_addc_co_u32_e64 v89, vcc, 0, v89, s[12:13]
	v_cmp_gt_f32_e64 s[12:13], v100, v11
	v_addc_co_u32_e64 v88, vcc, 0, v88, s[8:9]
	v_cmp_gt_f32_e64 s[8:9], v100, v12
	v_addc_co_u32_e64 v87, vcc, 0, v87, s[10:11]
	v_cmp_gt_f32_e64 s[10:11], v100, v13
	v_addc_co_u32_e64 v86, vcc, 0, v86, s[12:13]
	v_cmp_gt_f32_e64 s[12:13], v100, v14
	v_addc_co_u32_e64 v85, vcc, 0, v85, s[8:9]
	v_cmp_gt_f32_e64 s[8:9], v100, v15
	v_addc_co_u32_e64 v84, vcc, 0, v84, s[10:11]
	v_cmp_gt_f32_e64 s[10:11], v100, v16
	v_addc_co_u32_e64 v83, vcc, 0, v83, s[12:13]
	v_cmp_gt_f32_e64 s[12:13], v100, v17
	v_addc_co_u32_e64 v81, vcc, 0, v81, s[8:9]
	v_cmp_gt_f32_e64 s[8:9], v100, v18
	v_addc_co_u32_e64 v79, vcc, 0, v79, s[10:11]
	v_cmp_gt_f32_e64 s[10:11], v100, v19
	v_addc_co_u32_e64 v78, vcc, 0, v78, s[12:13]
	v_cmp_ge_f32_e64 s[12:13], v100, v20
	v_addc_co_u32_e64 v77, vcc, 0, v77, s[8:9]
	v_cmp_ge_f32_e64 s[8:9], v100, v21
	v_addc_co_u32_e64 v76, vcc, 0, v76, s[10:11]
	v_cmp_ge_f32_e64 s[10:11], v100, v22
	s_and_b64 s[12:13], s[12:13], s[6:7]
	v_addc_co_u32_e64 v75, vcc, 0, v75, s[12:13]
	v_cmp_ge_f32_e64 s[12:13], v100, v23
	v_addc_co_u32_e64 v74, vcc, 0, v74, s[8:9]
	v_cmp_ge_f32_e64 s[8:9], v100, v24
	v_addc_co_u32_e64 v73, vcc, 0, v73, s[10:11]
	v_cmp_ge_f32_e64 s[10:11], v100, v25
	v_addc_co_u32_e64 v72, vcc, 0, v72, s[12:13]
	v_cmp_ge_f32_e64 s[12:13], v100, v26
	v_addc_co_u32_e64 v71, vcc, 0, v71, s[8:9]
	v_cmp_ge_f32_e64 s[8:9], v100, v27
	v_addc_co_u32_e64 v70, vcc, 0, v70, s[10:11]
	v_cmp_ge_f32_e64 s[10:11], v100, v28
	v_addc_co_u32_e64 v69, vcc, 0, v69, s[12:13]
	v_cmp_ge_f32_e64 s[12:13], v100, v29
	v_addc_co_u32_e64 v68, vcc, 0, v68, s[8:9]
	v_cmp_ge_f32_e64 s[8:9], v100, v30
	v_addc_co_u32_e64 v67, vcc, 0, v67, s[10:11]
	v_cmp_ge_f32_e64 s[10:11], v100, v31
	v_addc_co_u32_e64 v66, vcc, 0, v66, s[12:13]
	s_nop 0
	v_addc_co_u32_e64 v65, vcc, 0, v65, s[8:9]
	v_addc_co_u32_e64 v64, vcc, 0, v64, s[10:11]
	s_cmp_le_u32 s14, 41
	s_cbranch_scc1 .Lrk_done
; __device__ __forceinline__ void cmp_phase(LAS unsigned char* lds, const bf16_t* __restrict__ P, const bf16_t* __restrict__ Kc, const bf16_t* __restrict__ Vc,
;                                           bf16_t* __restrict__ ocmp, unsigned long long* __restrict__ mask, int G, const int wave0) {
;     ...
;             const int kmax = ((tw0 + 31) >> 6) + 1;
; #pragma nounroll
;             for (int k = 0; k < kmax; ++k) {
;                 const float sk = sc[k];
;                 const int kk = k - hi;
; #pragma unroll
;                 for (int i = 0; i < 32; ++i) rank[i] += ((sk > s[i]) || ((sk == s[i]) && (kk < 2 * i))) ? 1 : 0;
;             }
	v_cmp_gt_f32_e64 s[8:9], v101, v0
	v_cmp_gt_f32_e64 s[10:11], v101, v1
	v_cmp_gt_f32_e64 s[12:13], v101, v2
	v_addc_co_u32_e64 v97, vcc, 0, v97, s[8:9]
	v_cmp_gt_f32_e64 s[8:9], v101, v3
	v_addc_co_u32_e64 v96, vcc, 0, v96, s[10:11]
	v_cmp_gt_f32_e64 s[10:11], v101, v4
	v_addc_co_u32_e64 v95, vcc, 0, v95, s[12:13]
	v_cmp_gt_f32_e64 s[12:13], v101, v5
	v_addc_co_u32_e64 v94, vcc, 0, v94, s[8:9]
	v_cmp_gt_f32_e64 s[8:9], v101, v6
	v_addc_co_u32_e64 v93, vcc, 0, v93, s[10:11]
	v_cmp_gt_f32_e64 s[10:11], v101, v7
	v_addc_co_u32_e64 v92, vcc, 0, v92, s[12:13]
	v_cmp_gt_f32_e64 s[12:13], v101, v8
	v_addc_co_u32_e64 v91, vcc, 0, v91, s[8:9]
	v_cmp_gt_f32_e64 s[8:9], v101, v9
	v_addc_co_u32_e64 v90, vcc, 0, v90, s[10:11]
	v_cmp_gt_f32_e64 s[10:11], v101, v10
	v_addc_co_u32_e64 v89, vcc, 0, v89, s[12:13]
	v_cmp_gt_f32_e64 s[12:13], v101, v11
	v_addc_co_u32_e64 v88, vcc, 0, v88, s[8:9]
	v_cmp_gt_f32_e64 s[8:9], v101, v12
	v_addc_co_u32_e64 v87, vcc, 0, v87, s[10:11]
	v_cmp_gt_f32_e64 s[10:11], v101, v13
	v_addc_co_u32_e64 v86, vcc, 0, v86, s[12:13]
	v_cmp_gt_f32_e64 s[12:13], v101, v14
	v_addc_co_u32_e64 v85, vcc, 0, v85, s[8:9]
	v_cmp_gt_f32_e64 s[8:9], v101, v15
	v_addc_co_u32_e64 v84, vcc, 0, v84, s[10:11]
	v_cmp_gt_f32_e64 s[10:11], v101, v16
	v_addc_co_u32_e64 v83, vcc, 0, v83, s[12:13]
	v_cmp_gt_f32_e64 s[12:13], v101, v17
	v_addc_co_u32_e64 v81, vcc, 0, v81, s[8:9]
	v_cmp_gt_f32_e64 s[8:9], v101, v18
	v_addc_co_u32_e64 v79, vcc, 0, v79, s[10:11]
	v_cmp_gt_f32_e64 s[10:11], v101, v19
	v_addc_co_u32_e64 v78, vcc, 0, v78, s[12:13]
	v_cmp_gt_f32_e64 s[12:13], v101, v20
	v_addc_co_u32_e64 v77, vcc, 0, v77, s[8:9]
	v_cmp_ge_f32_e64 s[8:9], v101, v21
	v_addc_co_u32_e64 v76, vcc, 0, v76, s[10:11]
	v_cmp_ge_f32_e64 s[10:11], v101, v22
	v_addc_co_u32_e64 v75, vcc, 0, v75, s[12:13]
	v_cmp_ge_f32_e64 s[12:13], v101, v23
	v_addc_co_u32_e64 v74, vcc, 0, v74, s[8:9]
	v_cmp_ge_f32_e64 s[8:9], v101, v24
	v_addc_co_u32_e64 v73, vcc, 0, v73, s[10:11]
	v_cmp_ge_f32_e64 s[10:11], v101, v25
	v_addc_co_u32_e64 v72, vcc, 0, v72, s[12:13]
	v_cmp_ge_f32_e64 s[12:13], v101, v26
	v_addc_co_u32_e64 v71, vcc, 0, v71, s[8:9]
	v_cmp_ge_f32_e64 s[8:9], v101, v27
	v_addc_co_u32_e64 v70, vcc, 0, v70, s[10:11]
	v_cmp_ge_f32_e64 s[10:11], v101, v28
	v_addc_co_u32_e64 v69, vcc, 0, v69, s[12:13]
	v_cmp_ge_f32_e64 s[12:13], v101, v29
	v_addc_co_u32_e64 v68, vcc, 0, v68, s[8:9]
	v_cmp_ge_f32_e64 s[8:9], v101, v30
	v_addc_co_u32_e64 v67, vcc, 0, v67, s[10:11]
	v_cmp_ge_f32_e64 s[10:11], v101, v31
	v_addc_co_u32_e64 v66, vcc, 0, v66, s[12:13]
	s_nop 0
	v_addc_co_u32_e64 v65, vcc, 0, v65, s[8:9]
	v_addc_co_u32_e64 v64, vcc, 0, v64, s[10:11]
	s_cmp_le_u32 s14, 42
	s_cbranch_scc1 .Lrk_done
	ds_read2_b32 v[100:101], v104 offset0:44 offset1:45
	s_waitcnt lgkmcnt(1)
	v_cmp_gt_f32_e64 s[8:9], v102, v0
	v_cmp_gt_f32_e64 s[10:11], v102, v1
	v_cmp_gt_f32_e64 s[12:13], v102, v2
	v_addc_co_u32_e64 v97, vcc, 0, v97, s[8:9]
	v_cmp_gt_f32_e64 s[8:9], v102, v3
	v_addc_co_u32_e64 v96, vcc, 0, v96, s[10:11]
	v_cmp_gt_f32_e64 s[10:11], v102, v4
	v_addc_co_u32_e64 v95, vcc, 0, v95, s[12:13]
	v_cmp_gt_f32_e64 s[12:13], v102, v5
	v_addc_co_u32_e64 v94, vcc, 0, v94, s[8:9]
	v_cmp_gt_f32_e64 s[8:9], v102, v6
	v_addc_co_u32_e64 v93, vcc, 0, v93, s[10:11]
	v_cmp_gt_f32_e64 s[10:11], v102, v7
	v_addc_co_u32_e64 v92, vcc, 0, v92, s[12:13]
	v_cmp_gt_f32_e64 s[12:13], v102, v8
	v_addc_co_u32_e64 v91, vcc, 0, v91, s[8:9]
	v_cmp_gt_f32_e64 s[8:9], v102, v9
	v_addc_co_u32_e64 v90, vcc, 0, v90, s[10:11]
	v_cmp_gt_f32_e64 s[10:11], v102, v10
	v_addc_co_u32_e64 v89, vcc, 0, v89, s[12:13]
	v_cmp_gt_f32_e64 s[12:13], v102, v11
	v_addc_co_u32_e64 v88, vcc, 0, v88, s[8:9]
	v_cmp_gt_f32_e64 s[8:9], v102, v12
	v_addc_co_u32_e64 v87, vcc, 0, v87, s[10:11]
	v_cmp_gt_f32_e64 s[10:11], v102, v13
	v_addc_co_u32_e64 v86, vcc, 0, v86, s[12:13]
	v_cmp_gt_f32_e64 s[12:13], v102, v14
	v_addc_co_u32_e64 v85, vcc, 0, v85, s[8:9]
	v_cmp_gt_f32_e64 s[8:9], v102, v15
	v_addc_co_u32_e64 v84, vcc, 0, v84, s[10:11]
	v_cmp_gt_f32_e64 s[10:11], v102, v16
	v_addc_co_u32_e64 v83, vcc, 0, v83, s[12:13]
	v_cmp_gt_f32_e64 s[12:13], v102, v17
	v_addc_co_u32_e64 v81, vcc, 0, v81, s[8:9]
	v_cmp_gt_f32_e64 s[8:9], v102, v18
	v_addc_co_u32_e64 v79, vcc, 0, v79, s[10:11]
	v_cmp_gt_f32_e64 s[10:11], v102, v19
	v_addc_co_u32_e64 v78, vcc, 0, v78, s[12:13]
	v_cmp_gt_f32_e64 s[12:13], v102, v20
	v_addc_co_u32_e64 v77, vcc, 0, v77, s[8:9]
	v_cmp_ge_f32_e64 s[8:9], v102, v21
	v_addc_co_u32_e64 v76, vcc, 0, v76, s[10:11]
	v_cmp_ge_f32_e64 s[10:11], v102, v22
	v_addc_co_u32_e64 v75, vcc, 0, v75, s[12:13]
	v_cmp_ge_f32_e64 s[12:13], v102, v23
	s_and_b64 s[8:9], s[8:9], s[6:7]
	v_addc_co_u32_e64 v74, vcc, 0, v74, s[8:9]
	v_cmp_ge_f32_e64 s[8:9], v102, v24
	v_addc_co_u32_e64 v73, vcc, 0, v73, s[10:11]
	v_cmp_ge_f32_e64 s[10:11], v102, v25
	v_addc_co_u32_e64 v72, vcc, 0, v72, s[12:13]
	v_cmp_ge_f32_e64 s[12:13], v102, v26
	v_addc_co_u32_e64 v71, vcc, 0, v71, s[8:9]
	v_cmp_ge_f32_e64 s[8:9], v102, v27
	v_addc_co_u32_e64 v70, vcc, 0, v70, s[10:11]
	v_cmp_ge_f32_e64 s[10:11], v102, v28
	v_addc_co_u32_e64 v69, vcc, 0, v69, s[12:13]
	v_cmp_ge_f32_e64 s[12:13], v102, v29
	v_addc_co_u32_e64 v68, vcc, 0, v68, s[8:9]
	v_cmp_ge_f32_e64 s[8:9], v102, v30
	v_addc_co_u32_e64 v67, vcc, 0, v67, s[10:11]
	v_cmp_ge_f32_e64 s[10:11], v102, v31
	v_addc_co_u32_e64 v66, vcc, 0, v66, s[12:13]
	s_nop 0
	v_addc_co_u32_e64 v65, vcc, 0, v65, s[8:9]
	v_addc_co_u32_e64 v64, vcc, 0, v64, s[10:11]
	s_cmp_le_u32 s14, 43
	s_cbranch_scc1 .Lrk_done
; __device__ __forceinline__ void cmp_phase(LAS unsigned char* lds, const bf16_t* __restrict__ P, const bf16_t* __restrict__ Kc, const bf16_t* __restrict__ Vc,
;                                           bf16_t* __restrict__ ocmp, unsigned long long* __restrict__ mask, int G, const int wave0) {
;     ...
;             const int kmax = ((tw0 + 31) >> 6) + 1;
; #pragma nounroll
;             for (int k = 0; k < kmax; ++k) {
;                 const float sk = sc[k];
;                 const int kk = k - hi;
; #pragma unroll
;                 for (int i = 0; i < 32; ++i) rank[i] += ((sk > s[i]) || ((sk == s[i]) && (kk < 2 * i))) ? 1 : 0;
;             }
	v_cmp_gt_f32_e64 s[8:9], v103, v0
	v_cmp_gt_f32_e64 s[10:11], v103, v1
	v_cmp_gt_f32_e64 s[12:13], v103, v2
	v_addc_co_u32_e64 v97, vcc, 0, v97, s[8:9]
	v_cmp_gt_f32_e64 s[8:9], v103, v3
	v_addc_co_u32_e64 v96, vcc, 0, v96, s[10:11]
	v_cmp_gt_f32_e64 s[10:11], v103, v4
	v_addc_co_u32_e64 v95, vcc, 0, v95, s[12:13]
	v_cmp_gt_f32_e64 s[12:13], v103, v5
	v_addc_co_u32_e64 v94, vcc, 0, v94, s[8:9]
	v_cmp_gt_f32_e64 s[8:9], v103, v6
	v_addc_co_u32_e64 v93, vcc, 0, v93, s[10:11]
	v_cmp_gt_f32_e64 s[10:11], v103, v7
	v_addc_co_u32_e64 v92, vcc, 0, v92, s[12:13]
	v_cmp_gt_f32_e64 s[12:13], v103, v8
	v_addc_co_u32_e64 v91, vcc, 0, v91, s[8:9]
	v_cmp_gt_f32_e64 s[8:9], v103, v9
	v_addc_co_u32_e64 v90, vcc, 0, v90, s[10:11]
	v_cmp_gt_f32_e64 s[10:11], v103, v10
	v_addc_co_u32_e64 v89, vcc, 0, v89, s[12:13]
	v_cmp_gt_f32_e64 s[12:13], v103, v11
	v_addc_co_u32_e64 v88, vcc, 0, v88, s[8:9]
	v_cmp_gt_f32_e64 s[8:9], v103, v12
	v_addc_co_u32_e64 v87, vcc, 0, v87, s[10:11]
	v_cmp_gt_f32_e64 s[10:11], v103, v13
	v_addc_co_u32_e64 v86, vcc, 0, v86, s[12:13]
	v_cmp_gt_f32_e64 s[12:13], v103, v14
	v_addc_co_u32_e64 v85, vcc, 0, v85, s[8:9]
	v_cmp_gt_f32_e64 s[8:9], v103, v15
	v_addc_co_u32_e64 v84, vcc, 0, v84, s[10:11]
	v_cmp_gt_f32_e64 s[10:11], v103, v16
	v_addc_co_u32_e64 v83, vcc, 0, v83, s[12:13]
	v_cmp_gt_f32_e64 s[12:13], v103, v17
	v_addc_co_u32_e64 v81, vcc, 0, v81, s[8:9]
	v_cmp_gt_f32_e64 s[8:9], v103, v18
	v_addc_co_u32_e64 v79, vcc, 0, v79, s[10:11]
	v_cmp_gt_f32_e64 s[10:11], v103, v19
	v_addc_co_u32_e64 v78, vcc, 0, v78, s[12:13]
	v_cmp_gt_f32_e64 s[12:13], v103, v20
	v_addc_co_u32_e64 v77, vcc, 0, v77, s[8:9]
	v_cmp_gt_f32_e64 s[8:9], v103, v21
	v_addc_co_u32_e64 v76, vcc, 0, v76, s[10:11]
	v_cmp_ge_f32_e64 s[10:11], v103, v22
	v_addc_co_u32_e64 v75, vcc, 0, v75, s[12:13]
	v_cmp_ge_f32_e64 s[12:13], v103, v23
	v_addc_co_u32_e64 v74, vcc, 0, v74, s[8:9]
	v_cmp_ge_f32_e64 s[8:9], v103, v24
	v_addc_co_u32_e64 v73, vcc, 0, v73, s[10:11]
	v_cmp_ge_f32_e64 s[10:11], v103, v25
	v_addc_co_u32_e64 v72, vcc, 0, v72, s[12:13]
	v_cmp_ge_f32_e64 s[12:13], v103, v26
	v_addc_co_u32_e64 v71, vcc, 0, v71, s[8:9]
	v_cmp_ge_f32_e64 s[8:9], v103, v27
	v_addc_co_u32_e64 v70, vcc, 0, v70, s[10:11]
	v_cmp_ge_f32_e64 s[10:11], v103, v28
	v_addc_co_u32_e64 v69, vcc, 0, v69, s[12:13]
	v_cmp_ge_f32_e64 s[12:13], v103, v29
	v_addc_co_u32_e64 v68, vcc, 0, v68, s[8:9]
	v_cmp_ge_f32_e64 s[8:9], v103, v30
	v_addc_co_u32_e64 v67, vcc, 0, v67, s[10:11]
	v_cmp_ge_f32_e64 s[10:11], v103, v31
	v_addc_co_u32_e64 v66, vcc, 0, v66, s[12:13]
	s_nop 0
	v_addc_co_u32_e64 v65, vcc, 0, v65, s[8:9]
	v_addc_co_u32_e64 v64, vcc, 0, v64, s[10:11]
	s_cmp_le_u32 s14, 44
	s_cbranch_scc1 .Lrk_done
	ds_read2_b32 v[102:103], v104 offset0:46 offset1:47
	s_waitcnt lgkmcnt(1)
	v_cmp_gt_f32_e64 s[8:9], v100, v0
	v_cmp_gt_f32_e64 s[10:11], v100, v1
	v_cmp_gt_f32_e64 s[12:13], v100, v2
	v_addc_co_u32_e64 v97, vcc, 0, v97, s[8:9]
	v_cmp_gt_f32_e64 s[8:9], v100, v3
	v_addc_co_u32_e64 v96, vcc, 0, v96, s[10:11]
	v_cmp_gt_f32_e64 s[10:11], v100, v4
	v_addc_co_u32_e64 v95, vcc, 0, v95, s[12:13]
	v_cmp_gt_f32_e64 s[12:13], v100, v5
	v_addc_co_u32_e64 v94, vcc, 0, v94, s[8:9]
	v_cmp_gt_f32_e64 s[8:9], v100, v6
	v_addc_co_u32_e64 v93, vcc, 0, v93, s[10:11]
	v_cmp_gt_f32_e64 s[10:11], v100, v7
	v_addc_co_u32_e64 v92, vcc, 0, v92, s[12:13]
	v_cmp_gt_f32_e64 s[12:13], v100, v8
	v_addc_co_u32_e64 v91, vcc, 0, v91, s[8:9]
	v_cmp_gt_f32_e64 s[8:9], v100, v9
	v_addc_co_u32_e64 v90, vcc, 0, v90, s[10:11]
	v_cmp_gt_f32_e64 s[10:11], v100, v10
	v_addc_co_u32_e64 v89, vcc, 0, v89, s[12:13]
	v_cmp_gt_f32_e64 s[12:13], v100, v11
	v_addc_co_u32_e64 v88, vcc, 0, v88, s[8:9]
	v_cmp_gt_f32_e64 s[8:9], v100, v12
	v_addc_co_u32_e64 v87, vcc, 0, v87, s[10:11]
	v_cmp_gt_f32_e64 s[10:11], v100, v13
	v_addc_co_u32_e64 v86, vcc, 0, v86, s[12:13]
	v_cmp_gt_f32_e64 s[12:13], v100, v14
	v_addc_co_u32_e64 v85, vcc, 0, v85, s[8:9]
	v_cmp_gt_f32_e64 s[8:9], v100, v15
	v_addc_co_u32_e64 v84, vcc, 0, v84, s[10:11]
	v_cmp_gt_f32_e64 s[10:11], v100, v16
	v_addc_co_u32_e64 v83, vcc, 0, v83, s[12:13]
	v_cmp_gt_f32_e64 s[12:13], v100, v17
	v_addc_co_u32_e64 v81, vcc, 0, v81, s[8:9]
	v_cmp_gt_f32_e64 s[8:9], v100, v18
	v_addc_co_u32_e64 v79, vcc, 0, v79, s[10:11]
	v_cmp_gt_f32_e64 s[10:11], v100, v19
	v_addc_co_u32_e64 v78, vcc, 0, v78, s[12:13]
	v_cmp_gt_f32_e64 s[12:13], v100, v20
	v_addc_co_u32_e64 v77, vcc, 0, v77, s[8:9]
	v_cmp_gt_f32_e64 s[8:9], v100, v21
	v_addc_co_u32_e64 v76, vcc, 0, v76, s[10:11]
	v_cmp_ge_f32_e64 s[10:11], v100, v22
	v_addc_co_u32_e64 v75, vcc, 0, v75, s[12:13]
	v_cmp_ge_f32_e64 s[12:13], v100, v23
	v_addc_co_u32_e64 v74, vcc, 0, v74, s[8:9]
	v_cmp_ge_f32_e64 s[8:9], v100, v24
	s_and_b64 s[10:11], s[10:11], s[6:7]
	v_addc_co_u32_e64 v73, vcc, 0, v73, s[10:11]
	v_cmp_ge_f32_e64 s[10:11], v100, v25
	v_addc_co_u32_e64 v72, vcc, 0, v72, s[12:13]
	v_cmp_ge_f32_e64 s[12:13], v100, v26
	v_addc_co_u32_e64 v71, vcc, 0, v71, s[8:9]
	v_cmp_ge_f32_e64 s[8:9], v100, v27
	v_addc_co_u32_e64 v70, vcc, 0, v70, s[10:11]
	v_cmp_ge_f32_e64 s[10:11], v100, v28
	v_addc_co_u32_e64 v69, vcc, 0, v69, s[12:13]
	v_cmp_ge_f32_e64 s[12:13], v100, v29
	v_addc_co_u32_e64 v68, vcc, 0, v68, s[8:9]
	v_cmp_ge_f32_e64 s[8:9], v100, v30
	v_addc_co_u32_e64 v67, vcc, 0, v67, s[10:11]
	v_cmp_ge_f32_e64 s[10:11], v100, v31
	v_addc_co_u32_e64 v66, vcc, 0, v66, s[12:13]
	s_nop 0
	v_addc_co_u32_e64 v65, vcc, 0, v65, s[8:9]
	v_addc_co_u32_e64 v64, vcc, 0, v64, s[10:11]
	s_cmp_le_u32 s14, 45
	s_cbranch_scc1 .Lrk_done
; __device__ __forceinline__ void cmp_phase(LAS unsigned char* lds, const bf16_t* __restrict__ P, const bf16_t* __restrict__ Kc, const bf16_t* __restrict__ Vc,
;                                           bf16_t* __restrict__ ocmp, unsigned long long* __restrict__ mask, int G, const int wave0) {
;     ...
;             const int kmax = ((tw0 + 31) >> 6) + 1;
; #pragma nounroll
;             for (int k = 0; k < kmax; ++k) {
;                 const float sk = sc[k];
;                 const int kk = k - hi;
; #pragma unroll
;                 for (int i = 0; i < 32; ++i) rank[i] += ((sk > s[i]) || ((sk == s[i]) && (kk < 2 * i))) ? 1 : 0;
;             }
	v_cmp_gt_f32_e64 s[8:9], v101, v0
	v_cmp_gt_f32_e64 s[10:11], v101, v1
	v_cmp_gt_f32_e64 s[12:13], v101, v2
	v_addc_co_u32_e64 v97, vcc, 0, v97, s[8:9]
	v_cmp_gt_f32_e64 s[8:9], v101, v3
	v_addc_co_u32_e64 v96, vcc, 0, v96, s[10:11]
	v_cmp_gt_f32_e64 s[10:11], v101, v4
	v_addc_co_u32_e64 v95, vcc, 0, v95, s[12:13]
	v_cmp_gt_f32_e64 s[12:13], v101, v5
	v_addc_co_u32_e64 v94, vcc, 0, v94, s[8:9]
	v_cmp_gt_f32_e64 s[8:9], v101, v6
	v_addc_co_u32_e64 v93, vcc, 0, v93, s[10:11]
	v_cmp_gt_f32_e64 s[10:11], v101, v7
	v_addc_co_u32_e64 v92, vcc, 0, v92, s[12:13]
	v_cmp_gt_f32_e64 s[12:13], v101, v8
	v_addc_co_u32_e64 v91, vcc, 0, v91, s[8:9]
	v_cmp_gt_f32_e64 s[8:9], v101, v9
	v_addc_co_u32_e64 v90, vcc, 0, v90, s[10:11]
	v_cmp_gt_f32_e64 s[10:11], v101, v10
	v_addc_co_u32_e64 v89, vcc, 0, v89, s[12:13]
	v_cmp_gt_f32_e64 s[12:13], v101, v11
	v_addc_co_u32_e64 v88, vcc, 0, v88, s[8:9]
	v_cmp_gt_f32_e64 s[8:9], v101, v12
	v_addc_co_u32_e64 v87, vcc, 0, v87, s[10:11]
	v_cmp_gt_f32_e64 s[10:11], v101, v13
	v_addc_co_u32_e64 v86, vcc, 0, v86, s[12:13]
	v_cmp_gt_f32_e64 s[12:13], v101, v14
	v_addc_co_u32_e64 v85, vcc, 0, v85, s[8:9]
	v_cmp_gt_f32_e64 s[8:9], v101, v15
	v_addc_co_u32_e64 v84, vcc, 0, v84, s[10:11]
	v_cmp_gt_f32_e64 s[10:11], v101, v16
	v_addc_co_u32_e64 v83, vcc, 0, v83, s[12:13]
	v_cmp_gt_f32_e64 s[12:13], v101, v17
	v_addc_co_u32_e64 v81, vcc, 0, v81, s[8:9]
	v_cmp_gt_f32_e64 s[8:9], v101, v18
	v_addc_co_u32_e64 v79, vcc, 0, v79, s[10:11]
	v_cmp_gt_f32_e64 s[10:11], v101, v19
	v_addc_co_u32_e64 v78, vcc, 0, v78, s[12:13]
	v_cmp_gt_f32_e64 s[12:13], v101, v20
	v_addc_co_u32_e64 v77, vcc, 0, v77, s[8:9]
	v_cmp_gt_f32_e64 s[8:9], v101, v21
	v_addc_co_u32_e64 v76, vcc, 0, v76, s[10:11]
	v_cmp_gt_f32_e64 s[10:11], v101, v22
	v_addc_co_u32_e64 v75, vcc, 0, v75, s[12:13]
	v_cmp_ge_f32_e64 s[12:13], v101, v23
	v_addc_co_u32_e64 v74, vcc, 0, v74, s[8:9]
	v_cmp_ge_f32_e64 s[8:9], v101, v24
	v_addc_co_u32_e64 v73, vcc, 0, v73, s[10:11]
	v_cmp_ge_f32_e64 s[10:11], v101, v25
	v_addc_co_u32_e64 v72, vcc, 0, v72, s[12:13]
	v_cmp_ge_f32_e64 s[12:13], v101, v26
	v_addc_co_u32_e64 v71, vcc, 0, v71, s[8:9]
	v_cmp_ge_f32_e64 s[8:9], v101, v27
	v_addc_co_u32_e64 v70, vcc, 0, v70, s[10:11]
	v_cmp_ge_f32_e64 s[10:11], v101, v28
	v_addc_co_u32_e64 v69, vcc, 0, v69, s[12:13]
	v_cmp_ge_f32_e64 s[12:13], v101, v29
	v_addc_co_u32_e64 v68, vcc, 0, v68, s[8:9]
	v_cmp_ge_f32_e64 s[8:9], v101, v30
	v_addc_co_u32_e64 v67, vcc, 0, v67, s[10:11]
	v_cmp_ge_f32_e64 s[10:11], v101, v31
	v_addc_co_u32_e64 v66, vcc, 0, v66, s[12:13]
	s_nop 0
	v_addc_co_u32_e64 v65, vcc, 0, v65, s[8:9]
	v_addc_co_u32_e64 v64, vcc, 0, v64, s[10:11]
	s_cmp_le_u32 s14, 46
	s_cbranch_scc1 .Lrk_done
	ds_read2_b32 v[100:101], v104 offset0:48 offset1:49
	s_waitcnt lgkmcnt(1)
	v_cmp_gt_f32_e64 s[8:9], v102, v0
	v_cmp_gt_f32_e64 s[10:11], v102, v1
	v_cmp_gt_f32_e64 s[12:13], v102, v2
	v_addc_co_u32_e64 v97, vcc, 0, v97, s[8:9]
	v_cmp_gt_f32_e64 s[8:9], v102, v3
	v_addc_co_u32_e64 v96, vcc, 0, v96, s[10:11]
	v_cmp_gt_f32_e64 s[10:11], v102, v4
	v_addc_co_u32_e64 v95, vcc, 0, v95, s[12:13]
	v_cmp_gt_f32_e64 s[12:13], v102, v5
	v_addc_co_u32_e64 v94, vcc, 0, v94, s[8:9]
	v_cmp_gt_f32_e64 s[8:9], v102, v6
	v_addc_co_u32_e64 v93, vcc, 0, v93, s[10:11]
	v_cmp_gt_f32_e64 s[10:11], v102, v7
	v_addc_co_u32_e64 v92, vcc, 0, v92, s[12:13]
	v_cmp_gt_f32_e64 s[12:13], v102, v8
	v_addc_co_u32_e64 v91, vcc, 0, v91, s[8:9]
	v_cmp_gt_f32_e64 s[8:9], v102, v9
	v_addc_co_u32_e64 v90, vcc, 0, v90, s[10:11]
	v_cmp_gt_f32_e64 s[10:11], v102, v10
	v_addc_co_u32_e64 v89, vcc, 0, v89, s[12:13]
	v_cmp_gt_f32_e64 s[12:13], v102, v11
	v_addc_co_u32_e64 v88, vcc, 0, v88, s[8:9]
	v_cmp_gt_f32_e64 s[8:9], v102, v12
	v_addc_co_u32_e64 v87, vcc, 0, v87, s[10:11]
	v_cmp_gt_f32_e64 s[10:11], v102, v13
	v_addc_co_u32_e64 v86, vcc, 0, v86, s[12:13]
	v_cmp_gt_f32_e64 s[12:13], v102, v14
	v_addc_co_u32_e64 v85, vcc, 0, v85, s[8:9]
	v_cmp_gt_f32_e64 s[8:9], v102, v15
	v_addc_co_u32_e64 v84, vcc, 0, v84, s[10:11]
	v_cmp_gt_f32_e64 s[10:11], v102, v16
	v_addc_co_u32_e64 v83, vcc, 0, v83, s[12:13]
	v_cmp_gt_f32_e64 s[12:13], v102, v17
	v_addc_co_u32_e64 v81, vcc, 0, v81, s[8:9]
	v_cmp_gt_f32_e64 s[8:9], v102, v18
	v_addc_co_u32_e64 v79, vcc, 0, v79, s[10:11]
	v_cmp_gt_f32_e64 s[10:11], v102, v19
	v_addc_co_u32_e64 v78, vcc, 0, v78, s[12:13]
	v_cmp_gt_f32_e64 s[12:13], v102, v20
	v_addc_co_u32_e64 v77, vcc, 0, v77, s[8:9]
	v_cmp_gt_f32_e64 s[8:9], v102, v21
	v_addc_co_u32_e64 v76, vcc, 0, v76, s[10:11]
	v_cmp_gt_f32_e64 s[10:11], v102, v22
	v_addc_co_u32_e64 v75, vcc, 0, v75, s[12:13]
	v_cmp_ge_f32_e64 s[12:13], v102, v23
	v_addc_co_u32_e64 v74, vcc, 0, v74, s[8:9]
	v_cmp_ge_f32_e64 s[8:9], v102, v24
	v_addc_co_u32_e64 v73, vcc, 0, v73, s[10:11]
	v_cmp_ge_f32_e64 s[10:11], v102, v25
	s_and_b64 s[12:13], s[12:13], s[6:7]
	v_addc_co_u32_e64 v72, vcc, 0, v72, s[12:13]
	v_cmp_ge_f32_e64 s[12:13], v102, v26
	v_addc_co_u32_e64 v71, vcc, 0, v71, s[8:9]
	v_cmp_ge_f32_e64 s[8:9], v102, v27
	v_addc_co_u32_e64 v70, vcc, 0, v70, s[10:11]
	v_cmp_ge_f32_e64 s[10:11], v102, v28
	v_addc_co_u32_e64 v69, vcc, 0, v69, s[12:13]
	v_cmp_ge_f32_e64 s[12:13], v102, v29
	v_addc_co_u32_e64 v68, vcc, 0, v68, s[8:9]
	v_cmp_ge_f32_e64 s[8:9], v102, v30
	v_addc_co_u32_e64 v67, vcc, 0, v67, s[10:11]
	v_cmp_ge_f32_e64 s[10:11], v102, v31
	v_addc_co_u32_e64 v66, vcc, 0, v66, s[12:13]
	s_nop 0
	v_addc_co_u32_e64 v65, vcc, 0, v65, s[8:9]
	v_addc_co_u32_e64 v64, vcc, 0, v64, s[10:11]
	s_cmp_le_u32 s14, 47
	s_cbranch_scc1 .Lrk_done
; __device__ __forceinline__ void cmp_phase(LAS unsigned char* lds, const bf16_t* __restrict__ P, const bf16_t* __restrict__ Kc, const bf16_t* __restrict__ Vc,
;                                           bf16_t* __restrict__ ocmp, unsigned long long* __restrict__ mask, int G, const int wave0) {
;     ...
;             const int kmax = ((tw0 + 31) >> 6) + 1;
; #pragma nounroll
;             for (int k = 0; k < kmax; ++k) {
;                 const float sk = sc[k];
;                 const int kk = k - hi;
; #pragma unroll
;                 for (int i = 0; i < 32; ++i) rank[i] += ((sk > s[i]) || ((sk == s[i]) && (kk < 2 * i))) ? 1 : 0;
;             }
	v_cmp_gt_f32_e64 s[8:9], v103, v0
	v_cmp_gt_f32_e64 s[10:11], v103, v1
	v_cmp_gt_f32_e64 s[12:13], v103, v2
	v_addc_co_u32_e64 v97, vcc, 0, v97, s[8:9]
	v_cmp_gt_f32_e64 s[8:9], v103, v3
	v_addc_co_u32_e64 v96, vcc, 0, v96, s[10:11]
	v_cmp_gt_f32_e64 s[10:11], v103, v4
	v_addc_co_u32_e64 v95, vcc, 0, v95, s[12:13]
	v_cmp_gt_f32_e64 s[12:13], v103, v5
	v_addc_co_u32_e64 v94, vcc, 0, v94, s[8:9]
	v_cmp_gt_f32_e64 s[8:9], v103, v6
	v_addc_co_u32_e64 v93, vcc, 0, v93, s[10:11]
	v_cmp_gt_f32_e64 s[10:11], v103, v7
	v_addc_co_u32_e64 v92, vcc, 0, v92, s[12:13]
	v_cmp_gt_f32_e64 s[12:13], v103, v8
	v_addc_co_u32_e64 v91, vcc, 0, v91, s[8:9]
	v_cmp_gt_f32_e64 s[8:9], v103, v9
	v_addc_co_u32_e64 v90, vcc, 0, v90, s[10:11]
	v_cmp_gt_f32_e64 s[10:11], v103, v10
	v_addc_co_u32_e64 v89, vcc, 0, v89, s[12:13]
	v_cmp_gt_f32_e64 s[12:13], v103, v11
	v_addc_co_u32_e64 v88, vcc, 0, v88, s[8:9]
	v_cmp_gt_f32_e64 s[8:9], v103, v12
	v_addc_co_u32_e64 v87, vcc, 0, v87, s[10:11]
	v_cmp_gt_f32_e64 s[10:11], v103, v13
	v_addc_co_u32_e64 v86, vcc, 0, v86, s[12:13]
	v_cmp_gt_f32_e64 s[12:13], v103, v14
	v_addc_co_u32_e64 v85, vcc, 0, v85, s[8:9]
	v_cmp_gt_f32_e64 s[8:9], v103, v15
	v_addc_co_u32_e64 v84, vcc, 0, v84, s[10:11]
	v_cmp_gt_f32_e64 s[10:11], v103, v16
	v_addc_co_u32_e64 v83, vcc, 0, v83, s[12:13]
	v_cmp_gt_f32_e64 s[12:13], v103, v17
	v_addc_co_u32_e64 v81, vcc, 0, v81, s[8:9]
	v_cmp_gt_f32_e64 s[8:9], v103, v18
	v_addc_co_u32_e64 v79, vcc, 0, v79, s[10:11]
	v_cmp_gt_f32_e64 s[10:11], v103, v19
	v_addc_co_u32_e64 v78, vcc, 0, v78, s[12:13]
	v_cmp_gt_f32_e64 s[12:13], v103, v20
	v_addc_co_u32_e64 v77, vcc, 0, v77, s[8:9]
	v_cmp_gt_f32_e64 s[8:9], v103, v21
	v_addc_co_u32_e64 v76, vcc, 0, v76, s[10:11]
	v_cmp_gt_f32_e64 s[10:11], v103, v22
	v_addc_co_u32_e64 v75, vcc, 0, v75, s[12:13]
	v_cmp_gt_f32_e64 s[12:13], v103, v23
	v_addc_co_u32_e64 v74, vcc, 0, v74, s[8:9]
	v_cmp_ge_f32_e64 s[8:9], v103, v24
	v_addc_co_u32_e64 v73, vcc, 0, v73, s[10:11]
	v_cmp_ge_f32_e64 s[10:11], v103, v25
	v_addc_co_u32_e64 v72, vcc, 0, v72, s[12:13]
	v_cmp_ge_f32_e64 s[12:13], v103, v26
	v_addc_co_u32_e64 v71, vcc, 0, v71, s[8:9]
	v_cmp_ge_f32_e64 s[8:9], v103, v27
	v_addc_co_u32_e64 v70, vcc, 0, v70, s[10:11]
	v_cmp_ge_f32_e64 s[10:11], v103, v28
	v_addc_co_u32_e64 v69, vcc, 0, v69, s[12:13]
	v_cmp_ge_f32_e64 s[12:13], v103, v29
	v_addc_co_u32_e64 v68, vcc, 0, v68, s[8:9]
	v_cmp_ge_f32_e64 s[8:9], v103, v30
	v_addc_co_u32_e64 v67, vcc, 0, v67, s[10:11]
	v_cmp_ge_f32_e64 s[10:11], v103, v31
	v_addc_co_u32_e64 v66, vcc, 0, v66, s[12:13]
	s_nop 0
	v_addc_co_u32_e64 v65, vcc, 0, v65, s[8:9]
	v_addc_co_u32_e64 v64, vcc, 0, v64, s[10:11]
	s_cmp_le_u32 s14, 48
	s_cbranch_scc1 .Lrk_done
	ds_read2_b32 v[102:103], v104 offset0:50 offset1:51
	s_waitcnt lgkmcnt(1)
	v_cmp_gt_f32_e64 s[8:9], v100, v0
	v_cmp_gt_f32_e64 s[10:11], v100, v1
	v_cmp_gt_f32_e64 s[12:13], v100, v2
	v_addc_co_u32_e64 v97, vcc, 0, v97, s[8:9]
	v_cmp_gt_f32_e64 s[8:9], v100, v3
	v_addc_co_u32_e64 v96, vcc, 0, v96, s[10:11]
	v_cmp_gt_f32_e64 s[10:11], v100, v4
	v_addc_co_u32_e64 v95, vcc, 0, v95, s[12:13]
	v_cmp_gt_f32_e64 s[12:13], v100, v5
	v_addc_co_u32_e64 v94, vcc, 0, v94, s[8:9]
	v_cmp_gt_f32_e64 s[8:9], v100, v6
	v_addc_co_u32_e64 v93, vcc, 0, v93, s[10:11]
	v_cmp_gt_f32_e64 s[10:11], v100, v7
	v_addc_co_u32_e64 v92, vcc, 0, v92, s[12:13]
	v_cmp_gt_f32_e64 s[12:13], v100, v8
	v_addc_co_u32_e64 v91, vcc, 0, v91, s[8:9]
	v_cmp_gt_f32_e64 s[8:9], v100, v9
	v_addc_co_u32_e64 v90, vcc, 0, v90, s[10:11]
	v_cmp_gt_f32_e64 s[10:11], v100, v10
	v_addc_co_u32_e64 v89, vcc, 0, v89, s[12:13]
	v_cmp_gt_f32_e64 s[12:13], v100, v11
	v_addc_co_u32_e64 v88, vcc, 0, v88, s[8:9]
	v_cmp_gt_f32_e64 s[8:9], v100, v12
	v_addc_co_u32_e64 v87, vcc, 0, v87, s[10:11]
	v_cmp_gt_f32_e64 s[10:11], v100, v13
	v_addc_co_u32_e64 v86, vcc, 0, v86, s[12:13]
	v_cmp_gt_f32_e64 s[12:13], v100, v14
	v_addc_co_u32_e64 v85, vcc, 0, v85, s[8:9]
	v_cmp_gt_f32_e64 s[8:9], v100, v15
	v_addc_co_u32_e64 v84, vcc, 0, v84, s[10:11]
	v_cmp_gt_f32_e64 s[10:11], v100, v16
	v_addc_co_u32_e64 v83, vcc, 0, v83, s[12:13]
	v_cmp_gt_f32_e64 s[12:13], v100, v17
	v_addc_co_u32_e64 v81, vcc, 0, v81, s[8:9]
	v_cmp_gt_f32_e64 s[8:9], v100, v18
	v_addc_co_u32_e64 v79, vcc, 0, v79, s[10:11]
	v_cmp_gt_f32_e64 s[10:11], v100, v19
	v_addc_co_u32_e64 v78, vcc, 0, v78, s[12:13]
	v_cmp_gt_f32_e64 s[12:13], v100, v20
	v_addc_co_u32_e64 v77, vcc, 0, v77, s[8:9]
	v_cmp_gt_f32_e64 s[8:9], v100, v21
	v_addc_co_u32_e64 v76, vcc, 0, v76, s[10:11]
	v_cmp_gt_f32_e64 s[10:11], v100, v22
	v_addc_co_u32_e64 v75, vcc, 0, v75, s[12:13]
	v_cmp_gt_f32_e64 s[12:13], v100, v23
	v_addc_co_u32_e64 v74, vcc, 0, v74, s[8:9]
	v_cmp_ge_f32_e64 s[8:9], v100, v24
	v_addc_co_u32_e64 v73, vcc, 0, v73, s[10:11]
	v_cmp_ge_f32_e64 s[10:11], v100, v25
	v_addc_co_u32_e64 v72, vcc, 0, v72, s[12:13]
	v_cmp_ge_f32_e64 s[12:13], v100, v26
	s_and_b64 s[8:9], s[8:9], s[6:7]
	v_addc_co_u32_e64 v71, vcc, 0, v71, s[8:9]
	v_cmp_ge_f32_e64 s[8:9], v100, v27
	v_addc_co_u32_e64 v70, vcc, 0, v70, s[10:11]
	v_cmp_ge_f32_e64 s[10:11], v100, v28
	v_addc_co_u32_e64 v69, vcc, 0, v69, s[12:13]
	v_cmp_ge_f32_e64 s[12:13], v100, v29
	v_addc_co_u32_e64 v68, vcc, 0, v68, s[8:9]
	v_cmp_ge_f32_e64 s[8:9], v100, v30
	v_addc_co_u32_e64 v67, vcc, 0, v67, s[10:11]
	v_cmp_ge_f32_e64 s[10:11], v100, v31
	v_addc_co_u32_e64 v66, vcc, 0, v66, s[12:13]
	s_nop 0
	v_addc_co_u32_e64 v65, vcc, 0, v65, s[8:9]
	v_addc_co_u32_e64 v64, vcc, 0, v64, s[10:11]
	s_cmp_le_u32 s14, 49
	s_cbranch_scc1 .Lrk_done
; __device__ __forceinline__ void cmp_phase(LAS unsigned char* lds, const bf16_t* __restrict__ P, const bf16_t* __restrict__ Kc, const bf16_t* __restrict__ Vc,
;                                           bf16_t* __restrict__ ocmp, unsigned long long* __restrict__ mask, int G, const int wave0) {
;     ...
;             const int kmax = ((tw0 + 31) >> 6) + 1;
; #pragma nounroll
;             for (int k = 0; k < kmax; ++k) {
;                 const float sk = sc[k];
;                 const int kk = k - hi;
; #pragma unroll
;                 for (int i = 0; i < 32; ++i) rank[i] += ((sk > s[i]) || ((sk == s[i]) && (kk < 2 * i))) ? 1 : 0;
;             }
	v_cmp_gt_f32_e64 s[8:9], v101, v0
	v_cmp_gt_f32_e64 s[10:11], v101, v1
	v_cmp_gt_f32_e64 s[12:13], v101, v2
	v_addc_co_u32_e64 v97, vcc, 0, v97, s[8:9]
	v_cmp_gt_f32_e64 s[8:9], v101, v3
	v_addc_co_u32_e64 v96, vcc, 0, v96, s[10:11]
	v_cmp_gt_f32_e64 s[10:11], v101, v4
	v_addc_co_u32_e64 v95, vcc, 0, v95, s[12:13]
	v_cmp_gt_f32_e64 s[12:13], v101, v5
	v_addc_co_u32_e64 v94, vcc, 0, v94, s[8:9]
	v_cmp_gt_f32_e64 s[8:9], v101, v6
	v_addc_co_u32_e64 v93, vcc, 0, v93, s[10:11]
	v_cmp_gt_f32_e64 s[10:11], v101, v7
	v_addc_co_u32_e64 v92, vcc, 0, v92, s[12:13]
	v_cmp_gt_f32_e64 s[12:13], v101, v8
	v_addc_co_u32_e64 v91, vcc, 0, v91, s[8:9]
	v_cmp_gt_f32_e64 s[8:9], v101, v9
	v_addc_co_u32_e64 v90, vcc, 0, v90, s[10:11]
	v_cmp_gt_f32_e64 s[10:11], v101, v10
	v_addc_co_u32_e64 v89, vcc, 0, v89, s[12:13]
	v_cmp_gt_f32_e64 s[12:13], v101, v11
	v_addc_co_u32_e64 v88, vcc, 0, v88, s[8:9]
	v_cmp_gt_f32_e64 s[8:9], v101, v12
	v_addc_co_u32_e64 v87, vcc, 0, v87, s[10:11]
	v_cmp_gt_f32_e64 s[10:11], v101, v13
	v_addc_co_u32_e64 v86, vcc, 0, v86, s[12:13]
	v_cmp_gt_f32_e64 s[12:13], v101, v14
	v_addc_co_u32_e64 v85, vcc, 0, v85, s[8:9]
	v_cmp_gt_f32_e64 s[8:9], v101, v15
	v_addc_co_u32_e64 v84, vcc, 0, v84, s[10:11]
	v_cmp_gt_f32_e64 s[10:11], v101, v16
	v_addc_co_u32_e64 v83, vcc, 0, v83, s[12:13]
	v_cmp_gt_f32_e64 s[12:13], v101, v17
	v_addc_co_u32_e64 v81, vcc, 0, v81, s[8:9]
	v_cmp_gt_f32_e64 s[8:9], v101, v18
	v_addc_co_u32_e64 v79, vcc, 0, v79, s[10:11]
	v_cmp_gt_f32_e64 s[10:11], v101, v19
	v_addc_co_u32_e64 v78, vcc, 0, v78, s[12:13]
	v_cmp_gt_f32_e64 s[12:13], v101, v20
	v_addc_co_u32_e64 v77, vcc, 0, v77, s[8:9]
	v_cmp_gt_f32_e64 s[8:9], v101, v21
	v_addc_co_u32_e64 v76, vcc, 0, v76, s[10:11]
	v_cmp_gt_f32_e64 s[10:11], v101, v22
	v_addc_co_u32_e64 v75, vcc, 0, v75, s[12:13]
	v_cmp_gt_f32_e64 s[12:13], v101, v23
	v_addc_co_u32_e64 v74, vcc, 0, v74, s[8:9]
	v_cmp_gt_f32_e64 s[8:9], v101, v24
	v_addc_co_u32_e64 v73, vcc, 0, v73, s[10:11]
	v_cmp_ge_f32_e64 s[10:11], v101, v25
	v_addc_co_u32_e64 v72, vcc, 0, v72, s[12:13]
	v_cmp_ge_f32_e64 s[12:13], v101, v26
	v_addc_co_u32_e64 v71, vcc, 0, v71, s[8:9]
	v_cmp_ge_f32_e64 s[8:9], v101, v27
	v_addc_co_u32_e64 v70, vcc, 0, v70, s[10:11]
	v_cmp_ge_f32_e64 s[10:11], v101, v28
	v_addc_co_u32_e64 v69, vcc, 0, v69, s[12:13]
	v_cmp_ge_f32_e64 s[12:13], v101, v29
	v_addc_co_u32_e64 v68, vcc, 0, v68, s[8:9]
	v_cmp_ge_f32_e64 s[8:9], v101, v30
	v_addc_co_u32_e64 v67, vcc, 0, v67, s[10:11]
	v_cmp_ge_f32_e64 s[10:11], v101, v31
	v_addc_co_u32_e64 v66, vcc, 0, v66, s[12:13]
	s_nop 0
	v_addc_co_u32_e64 v65, vcc, 0, v65, s[8:9]
	v_addc_co_u32_e64 v64, vcc, 0, v64, s[10:11]
	s_cmp_le_u32 s14, 50
	s_cbranch_scc1 .Lrk_done
	ds_read2_b32 v[100:101], v104 offset0:52 offset1:53
	s_waitcnt lgkmcnt(1)
	v_cmp_gt_f32_e64 s[8:9], v102, v0
	v_cmp_gt_f32_e64 s[10:11], v102, v1
	v_cmp_gt_f32_e64 s[12:13], v102, v2
	v_addc_co_u32_e64 v97, vcc, 0, v97, s[8:9]
	v_cmp_gt_f32_e64 s[8:9], v102, v3
	v_addc_co_u32_e64 v96, vcc, 0, v96, s[10:11]
	v_cmp_gt_f32_e64 s[10:11], v102, v4
	v_addc_co_u32_e64 v95, vcc, 0, v95, s[12:13]
	v_cmp_gt_f32_e64 s[12:13], v102, v5
	v_addc_co_u32_e64 v94, vcc, 0, v94, s[8:9]
	v_cmp_gt_f32_e64 s[8:9], v102, v6
	v_addc_co_u32_e64 v93, vcc, 0, v93, s[10:11]
	v_cmp_gt_f32_e64 s[10:11], v102, v7
	v_addc_co_u32_e64 v92, vcc, 0, v92, s[12:13]
	v_cmp_gt_f32_e64 s[12:13], v102, v8
	v_addc_co_u32_e64 v91, vcc, 0, v91, s[8:9]
	v_cmp_gt_f32_e64 s[8:9], v102, v9
	v_addc_co_u32_e64 v90, vcc, 0, v90, s[10:11]
	v_cmp_gt_f32_e64 s[10:11], v102, v10
	v_addc_co_u32_e64 v89, vcc, 0, v89, s[12:13]
	v_cmp_gt_f32_e64 s[12:13], v102, v11
	v_addc_co_u32_e64 v88, vcc, 0, v88, s[8:9]
	v_cmp_gt_f32_e64 s[8:9], v102, v12
	v_addc_co_u32_e64 v87, vcc, 0, v87, s[10:11]
	v_cmp_gt_f32_e64 s[10:11], v102, v13
	v_addc_co_u32_e64 v86, vcc, 0, v86, s[12:13]
	v_cmp_gt_f32_e64 s[12:13], v102, v14
	v_addc_co_u32_e64 v85, vcc, 0, v85, s[8:9]
	v_cmp_gt_f32_e64 s[8:9], v102, v15
	v_addc_co_u32_e64 v84, vcc, 0, v84, s[10:11]
	v_cmp_gt_f32_e64 s[10:11], v102, v16
	v_addc_co_u32_e64 v83, vcc, 0, v83, s[12:13]
	v_cmp_gt_f32_e64 s[12:13], v102, v17
	v_addc_co_u32_e64 v81, vcc, 0, v81, s[8:9]
	v_cmp_gt_f32_e64 s[8:9], v102, v18
	v_addc_co_u32_e64 v79, vcc, 0, v79, s[10:11]
	v_cmp_gt_f32_e64 s[10:11], v102, v19
	v_addc_co_u32_e64 v78, vcc, 0, v78, s[12:13]
	v_cmp_gt_f32_e64 s[12:13], v102, v20
	v_addc_co_u32_e64 v77, vcc, 0, v77, s[8:9]
	v_cmp_gt_f32_e64 s[8:9], v102, v21
	v_addc_co_u32_e64 v76, vcc, 0, v76, s[10:11]
	v_cmp_gt_f32_e64 s[10:11], v102, v22
	v_addc_co_u32_e64 v75, vcc, 0, v75, s[12:13]
	v_cmp_gt_f32_e64 s[12:13], v102, v23
	v_addc_co_u32_e64 v74, vcc, 0, v74, s[8:9]
	v_cmp_gt_f32_e64 s[8:9], v102, v24
	v_addc_co_u32_e64 v73, vcc, 0, v73, s[10:11]
	v_cmp_ge_f32_e64 s[10:11], v102, v25
	v_addc_co_u32_e64 v72, vcc, 0, v72, s[12:13]
	v_cmp_ge_f32_e64 s[12:13], v102, v26
	v_addc_co_u32_e64 v71, vcc, 0, v71, s[8:9]
	v_cmp_ge_f32_e64 s[8:9], v102, v27
	s_and_b64 s[10:11], s[10:11], s[6:7]
	v_addc_co_u32_e64 v70, vcc, 0, v70, s[10:11]
	v_cmp_ge_f32_e64 s[10:11], v102, v28
	v_addc_co_u32_e64 v69, vcc, 0, v69, s[12:13]
	v_cmp_ge_f32_e64 s[12:13], v102, v29
	v_addc_co_u32_e64 v68, vcc, 0, v68, s[8:9]
	v_cmp_ge_f32_e64 s[8:9], v102, v30
	v_addc_co_u32_e64 v67, vcc, 0, v67, s[10:11]
	v_cmp_ge_f32_e64 s[10:11], v102, v31
	v_addc_co_u32_e64 v66, vcc, 0, v66, s[12:13]
	s_nop 0
	v_addc_co_u32_e64 v65, vcc, 0, v65, s[8:9]
	v_addc_co_u32_e64 v64, vcc, 0, v64, s[10:11]
	s_cmp_le_u32 s14, 51
	s_cbranch_scc1 .Lrk_done
; __device__ __forceinline__ void cmp_phase(LAS unsigned char* lds, const bf16_t* __restrict__ P, const bf16_t* __restrict__ Kc, const bf16_t* __restrict__ Vc,
;                                           bf16_t* __restrict__ ocmp, unsigned long long* __restrict__ mask, int G, const int wave0) {
;     ...
;             const int kmax = ((tw0 + 31) >> 6) + 1;
; #pragma nounroll
;             for (int k = 0; k < kmax; ++k) {
;                 const float sk = sc[k];
;                 const int kk = k - hi;
; #pragma unroll
;                 for (int i = 0; i < 32; ++i) rank[i] += ((sk > s[i]) || ((sk == s[i]) && (kk < 2 * i))) ? 1 : 0;
;             }
	v_cmp_gt_f32_e64 s[8:9], v103, v0
	v_cmp_gt_f32_e64 s[10:11], v103, v1
	v_cmp_gt_f32_e64 s[12:13], v103, v2
	v_addc_co_u32_e64 v97, vcc, 0, v97, s[8:9]
	v_cmp_gt_f32_e64 s[8:9], v103, v3
	v_addc_co_u32_e64 v96, vcc, 0, v96, s[10:11]
	v_cmp_gt_f32_e64 s[10:11], v103, v4
	v_addc_co_u32_e64 v95, vcc, 0, v95, s[12:13]
	v_cmp_gt_f32_e64 s[12:13], v103, v5
	v_addc_co_u32_e64 v94, vcc, 0, v94, s[8:9]
	v_cmp_gt_f32_e64 s[8:9], v103, v6
	v_addc_co_u32_e64 v93, vcc, 0, v93, s[10:11]
	v_cmp_gt_f32_e64 s[10:11], v103, v7
	v_addc_co_u32_e64 v92, vcc, 0, v92, s[12:13]
	v_cmp_gt_f32_e64 s[12:13], v103, v8
	v_addc_co_u32_e64 v91, vcc, 0, v91, s[8:9]
	v_cmp_gt_f32_e64 s[8:9], v103, v9
	v_addc_co_u32_e64 v90, vcc, 0, v90, s[10:11]
	v_cmp_gt_f32_e64 s[10:11], v103, v10
	v_addc_co_u32_e64 v89, vcc, 0, v89, s[12:13]
	v_cmp_gt_f32_e64 s[12:13], v103, v11
	v_addc_co_u32_e64 v88, vcc, 0, v88, s[8:9]
	v_cmp_gt_f32_e64 s[8:9], v103, v12
	v_addc_co_u32_e64 v87, vcc, 0, v87, s[10:11]
	v_cmp_gt_f32_e64 s[10:11], v103, v13
	v_addc_co_u32_e64 v86, vcc, 0, v86, s[12:13]
	v_cmp_gt_f32_e64 s[12:13], v103, v14
	v_addc_co_u32_e64 v85, vcc, 0, v85, s[8:9]
	v_cmp_gt_f32_e64 s[8:9], v103, v15
	v_addc_co_u32_e64 v84, vcc, 0, v84, s[10:11]
	v_cmp_gt_f32_e64 s[10:11], v103, v16
	v_addc_co_u32_e64 v83, vcc, 0, v83, s[12:13]
	v_cmp_gt_f32_e64 s[12:13], v103, v17
	v_addc_co_u32_e64 v81, vcc, 0, v81, s[8:9]
	v_cmp_gt_f32_e64 s[8:9], v103, v18
	v_addc_co_u32_e64 v79, vcc, 0, v79, s[10:11]
	v_cmp_gt_f32_e64 s[10:11], v103, v19
	v_addc_co_u32_e64 v78, vcc, 0, v78, s[12:13]
	v_cmp_gt_f32_e64 s[12:13], v103, v20
	v_addc_co_u32_e64 v77, vcc, 0, v77, s[8:9]
	v_cmp_gt_f32_e64 s[8:9], v103, v21
	v_addc_co_u32_e64 v76, vcc, 0, v76, s[10:11]
	v_cmp_gt_f32_e64 s[10:11], v103, v22
	v_addc_co_u32_e64 v75, vcc, 0, v75, s[12:13]
	v_cmp_gt_f32_e64 s[12:13], v103, v23
	v_addc_co_u32_e64 v74, vcc, 0, v74, s[8:9]
	v_cmp_gt_f32_e64 s[8:9], v103, v24
	v_addc_co_u32_e64 v73, vcc, 0, v73, s[10:11]
	v_cmp_gt_f32_e64 s[10:11], v103, v25
	v_addc_co_u32_e64 v72, vcc, 0, v72, s[12:13]
	v_cmp_ge_f32_e64 s[12:13], v103, v26
	v_addc_co_u32_e64 v71, vcc, 0, v71, s[8:9]
	v_cmp_ge_f32_e64 s[8:9], v103, v27
	v_addc_co_u32_e64 v70, vcc, 0, v70, s[10:11]
	v_cmp_ge_f32_e64 s[10:11], v103, v28
	v_addc_co_u32_e64 v69, vcc, 0, v69, s[12:13]
	v_cmp_ge_f32_e64 s[12:13], v103, v29
	v_addc_co_u32_e64 v68, vcc, 0, v68, s[8:9]
	v_cmp_ge_f32_e64 s[8:9], v103, v30
	v_addc_co_u32_e64 v67, vcc, 0, v67, s[10:11]
	v_cmp_ge_f32_e64 s[10:11], v103, v31
	v_addc_co_u32_e64 v66, vcc, 0, v66, s[12:13]
	s_nop 0
	v_addc_co_u32_e64 v65, vcc, 0, v65, s[8:9]
	v_addc_co_u32_e64 v64, vcc, 0, v64, s[10:11]
	s_cmp_le_u32 s14, 52
	s_cbranch_scc1 .Lrk_done
	ds_read2_b32 v[102:103], v104 offset0:54 offset1:55
	s_waitcnt lgkmcnt(1)
	v_cmp_gt_f32_e64 s[8:9], v100, v0
	v_cmp_gt_f32_e64 s[10:11], v100, v1
	v_cmp_gt_f32_e64 s[12:13], v100, v2
	v_addc_co_u32_e64 v97, vcc, 0, v97, s[8:9]
	v_cmp_gt_f32_e64 s[8:9], v100, v3
	v_addc_co_u32_e64 v96, vcc, 0, v96, s[10:11]
	v_cmp_gt_f32_e64 s[10:11], v100, v4
	v_addc_co_u32_e64 v95, vcc, 0, v95, s[12:13]
	v_cmp_gt_f32_e64 s[12:13], v100, v5
	v_addc_co_u32_e64 v94, vcc, 0, v94, s[8:9]
	v_cmp_gt_f32_e64 s[8:9], v100, v6
	v_addc_co_u32_e64 v93, vcc, 0, v93, s[10:11]
	v_cmp_gt_f32_e64 s[10:11], v100, v7
	v_addc_co_u32_e64 v92, vcc, 0, v92, s[12:13]
	v_cmp_gt_f32_e64 s[12:13], v100, v8
	v_addc_co_u32_e64 v91, vcc, 0, v91, s[8:9]
	v_cmp_gt_f32_e64 s[8:9], v100, v9
	v_addc_co_u32_e64 v90, vcc, 0, v90, s[10:11]
	v_cmp_gt_f32_e64 s[10:11], v100, v10
	v_addc_co_u32_e64 v89, vcc, 0, v89, s[12:13]
	v_cmp_gt_f32_e64 s[12:13], v100, v11
	v_addc_co_u32_e64 v88, vcc, 0, v88, s[8:9]
	v_cmp_gt_f32_e64 s[8:9], v100, v12
	v_addc_co_u32_e64 v87, vcc, 0, v87, s[10:11]
	v_cmp_gt_f32_e64 s[10:11], v100, v13
	v_addc_co_u32_e64 v86, vcc, 0, v86, s[12:13]
	v_cmp_gt_f32_e64 s[12:13], v100, v14
	v_addc_co_u32_e64 v85, vcc, 0, v85, s[8:9]
	v_cmp_gt_f32_e64 s[8:9], v100, v15
	v_addc_co_u32_e64 v84, vcc, 0, v84, s[10:11]
	v_cmp_gt_f32_e64 s[10:11], v100, v16
	v_addc_co_u32_e64 v83, vcc, 0, v83, s[12:13]
	v_cmp_gt_f32_e64 s[12:13], v100, v17
	v_addc_co_u32_e64 v81, vcc, 0, v81, s[8:9]
	v_cmp_gt_f32_e64 s[8:9], v100, v18
	v_addc_co_u32_e64 v79, vcc, 0, v79, s[10:11]
	v_cmp_gt_f32_e64 s[10:11], v100, v19
	v_addc_co_u32_e64 v78, vcc, 0, v78, s[12:13]
	v_cmp_gt_f32_e64 s[12:13], v100, v20
	v_addc_co_u32_e64 v77, vcc, 0, v77, s[8:9]
	v_cmp_gt_f32_e64 s[8:9], v100, v21
	v_addc_co_u32_e64 v76, vcc, 0, v76, s[10:11]
	v_cmp_gt_f32_e64 s[10:11], v100, v22
	v_addc_co_u32_e64 v75, vcc, 0, v75, s[12:13]
	v_cmp_gt_f32_e64 s[12:13], v100, v23
	v_addc_co_u32_e64 v74, vcc, 0, v74, s[8:9]
	v_cmp_gt_f32_e64 s[8:9], v100, v24
	v_addc_co_u32_e64 v73, vcc, 0, v73, s[10:11]
	v_cmp_gt_f32_e64 s[10:11], v100, v25
	v_addc_co_u32_e64 v72, vcc, 0, v72, s[12:13]
	v_cmp_ge_f32_e64 s[12:13], v100, v26
	v_addc_co_u32_e64 v71, vcc, 0, v71, s[8:9]
	v_cmp_ge_f32_e64 s[8:9], v100, v27
	v_addc_co_u32_e64 v70, vcc, 0, v70, s[10:11]
	v_cmp_ge_f32_e64 s[10:11], v100, v28
	s_and_b64 s[12:13], s[12:13], s[6:7]
	v_addc_co_u32_e64 v69, vcc, 0, v69, s[12:13]
	v_cmp_ge_f32_e64 s[12:13], v100, v29
	v_addc_co_u32_e64 v68, vcc, 0, v68, s[8:9]
	v_cmp_ge_f32_e64 s[8:9], v100, v30
	v_addc_co_u32_e64 v67, vcc, 0, v67, s[10:11]
	v_cmp_ge_f32_e64 s[10:11], v100, v31
	v_addc_co_u32_e64 v66, vcc, 0, v66, s[12:13]
	s_nop 0
	v_addc_co_u32_e64 v65, vcc, 0, v65, s[8:9]
	v_addc_co_u32_e64 v64, vcc, 0, v64, s[10:11]
	s_cmp_le_u32 s14, 53
	s_cbranch_scc1 .Lrk_done
; __device__ __forceinline__ void cmp_phase(LAS unsigned char* lds, const bf16_t* __restrict__ P, const bf16_t* __restrict__ Kc, const bf16_t* __restrict__ Vc,
;                                           bf16_t* __restrict__ ocmp, unsigned long long* __restrict__ mask, int G, const int wave0) {
;     ...
;             const int kmax = ((tw0 + 31) >> 6) + 1;
; #pragma nounroll
;             for (int k = 0; k < kmax; ++k) {
;                 const float sk = sc[k];
;                 const int kk = k - hi;
; #pragma unroll
;                 for (int i = 0; i < 32; ++i) rank[i] += ((sk > s[i]) || ((sk == s[i]) && (kk < 2 * i))) ? 1 : 0;
;             }
	v_cmp_gt_f32_e64 s[8:9], v101, v0
	v_cmp_gt_f32_e64 s[10:11], v101, v1
	v_cmp_gt_f32_e64 s[12:13], v101, v2
	v_addc_co_u32_e64 v97, vcc, 0, v97, s[8:9]
	v_cmp_gt_f32_e64 s[8:9], v101, v3
	v_addc_co_u32_e64 v96, vcc, 0, v96, s[10:11]
	v_cmp_gt_f32_e64 s[10:11], v101, v4
	v_addc_co_u32_e64 v95, vcc, 0, v95, s[12:13]
	v_cmp_gt_f32_e64 s[12:13], v101, v5
	v_addc_co_u32_e64 v94, vcc, 0, v94, s[8:9]
	v_cmp_gt_f32_e64 s[8:9], v101, v6
	v_addc_co_u32_e64 v93, vcc, 0, v93, s[10:11]
	v_cmp_gt_f32_e64 s[10:11], v101, v7
	v_addc_co_u32_e64 v92, vcc, 0, v92, s[12:13]
	v_cmp_gt_f32_e64 s[12:13], v101, v8
	v_addc_co_u32_e64 v91, vcc, 0, v91, s[8:9]
	v_cmp_gt_f32_e64 s[8:9], v101, v9
	v_addc_co_u32_e64 v90, vcc, 0, v90, s[10:11]
	v_cmp_gt_f32_e64 s[10:11], v101, v10
	v_addc_co_u32_e64 v89, vcc, 0, v89, s[12:13]
	v_cmp_gt_f32_e64 s[12:13], v101, v11
	v_addc_co_u32_e64 v88, vcc, 0, v88, s[8:9]
	v_cmp_gt_f32_e64 s[8:9], v101, v12
	v_addc_co_u32_e64 v87, vcc, 0, v87, s[10:11]
	v_cmp_gt_f32_e64 s[10:11], v101, v13
	v_addc_co_u32_e64 v86, vcc, 0, v86, s[12:13]
	v_cmp_gt_f32_e64 s[12:13], v101, v14
	v_addc_co_u32_e64 v85, vcc, 0, v85, s[8:9]
	v_cmp_gt_f32_e64 s[8:9], v101, v15
	v_addc_co_u32_e64 v84, vcc, 0, v84, s[10:11]
	v_cmp_gt_f32_e64 s[10:11], v101, v16
	v_addc_co_u32_e64 v83, vcc, 0, v83, s[12:13]
	v_cmp_gt_f32_e64 s[12:13], v101, v17
	v_addc_co_u32_e64 v81, vcc, 0, v81, s[8:9]
	v_cmp_gt_f32_e64 s[8:9], v101, v18
	v_addc_co_u32_e64 v79, vcc, 0, v79, s[10:11]
	v_cmp_gt_f32_e64 s[10:11], v101, v19
	v_addc_co_u32_e64 v78, vcc, 0, v78, s[12:13]
	v_cmp_gt_f32_e64 s[12:13], v101, v20
	v_addc_co_u32_e64 v77, vcc, 0, v77, s[8:9]
	v_cmp_gt_f32_e64 s[8:9], v101, v21
	v_addc_co_u32_e64 v76, vcc, 0, v76, s[10:11]
	v_cmp_gt_f32_e64 s[10:11], v101, v22
	v_addc_co_u32_e64 v75, vcc, 0, v75, s[12:13]
	v_cmp_gt_f32_e64 s[12:13], v101, v23
	v_addc_co_u32_e64 v74, vcc, 0, v74, s[8:9]
	v_cmp_gt_f32_e64 s[8:9], v101, v24
	v_addc_co_u32_e64 v73, vcc, 0, v73, s[10:11]
	v_cmp_gt_f32_e64 s[10:11], v101, v25
	v_addc_co_u32_e64 v72, vcc, 0, v72, s[12:13]
	v_cmp_gt_f32_e64 s[12:13], v101, v26
	v_addc_co_u32_e64 v71, vcc, 0, v71, s[8:9]
	v_cmp_ge_f32_e64 s[8:9], v101, v27
	v_addc_co_u32_e64 v70, vcc, 0, v70, s[10:11]
	v_cmp_ge_f32_e64 s[10:11], v101, v28
	v_addc_co_u32_e64 v69, vcc, 0, v69, s[12:13]
	v_cmp_ge_f32_e64 s[12:13], v101, v29
	v_addc_co_u32_e64 v68, vcc, 0, v68, s[8:9]
	v_cmp_ge_f32_e64 s[8:9], v101, v30
	v_addc_co_u32_e64 v67, vcc, 0, v67, s[10:11]
	v_cmp_ge_f32_e64 s[10:11], v101, v31
	v_addc_co_u32_e64 v66, vcc, 0, v66, s[12:13]
	s_nop 0
	v_addc_co_u32_e64 v65, vcc, 0, v65, s[8:9]
	v_addc_co_u32_e64 v64, vcc, 0, v64, s[10:11]
	s_cmp_le_u32 s14, 54
	s_cbranch_scc1 .Lrk_done
	ds_read2_b32 v[100:101], v104 offset0:56 offset1:57
	s_waitcnt lgkmcnt(1)
	v_cmp_gt_f32_e64 s[8:9], v102, v0
	v_cmp_gt_f32_e64 s[10:11], v102, v1
	v_cmp_gt_f32_e64 s[12:13], v102, v2
	v_addc_co_u32_e64 v97, vcc, 0, v97, s[8:9]
	v_cmp_gt_f32_e64 s[8:9], v102, v3
	v_addc_co_u32_e64 v96, vcc, 0, v96, s[10:11]
	v_cmp_gt_f32_e64 s[10:11], v102, v4
	v_addc_co_u32_e64 v95, vcc, 0, v95, s[12:13]
	v_cmp_gt_f32_e64 s[12:13], v102, v5
	v_addc_co_u32_e64 v94, vcc, 0, v94, s[8:9]
	v_cmp_gt_f32_e64 s[8:9], v102, v6
	v_addc_co_u32_e64 v93, vcc, 0, v93, s[10:11]
	v_cmp_gt_f32_e64 s[10:11], v102, v7
	v_addc_co_u32_e64 v92, vcc, 0, v92, s[12:13]
	v_cmp_gt_f32_e64 s[12:13], v102, v8
	v_addc_co_u32_e64 v91, vcc, 0, v91, s[8:9]
	v_cmp_gt_f32_e64 s[8:9], v102, v9
	v_addc_co_u32_e64 v90, vcc, 0, v90, s[10:11]
	v_cmp_gt_f32_e64 s[10:11], v102, v10
	v_addc_co_u32_e64 v89, vcc, 0, v89, s[12:13]
	v_cmp_gt_f32_e64 s[12:13], v102, v11
	v_addc_co_u32_e64 v88, vcc, 0, v88, s[8:9]
	v_cmp_gt_f32_e64 s[8:9], v102, v12
	v_addc_co_u32_e64 v87, vcc, 0, v87, s[10:11]
	v_cmp_gt_f32_e64 s[10:11], v102, v13
	v_addc_co_u32_e64 v86, vcc, 0, v86, s[12:13]
	v_cmp_gt_f32_e64 s[12:13], v102, v14
	v_addc_co_u32_e64 v85, vcc, 0, v85, s[8:9]
	v_cmp_gt_f32_e64 s[8:9], v102, v15
	v_addc_co_u32_e64 v84, vcc, 0, v84, s[10:11]
	v_cmp_gt_f32_e64 s[10:11], v102, v16
	v_addc_co_u32_e64 v83, vcc, 0, v83, s[12:13]
	v_cmp_gt_f32_e64 s[12:13], v102, v17
	v_addc_co_u32_e64 v81, vcc, 0, v81, s[8:9]
	v_cmp_gt_f32_e64 s[8:9], v102, v18
	v_addc_co_u32_e64 v79, vcc, 0, v79, s[10:11]
	v_cmp_gt_f32_e64 s[10:11], v102, v19
	v_addc_co_u32_e64 v78, vcc, 0, v78, s[12:13]
	v_cmp_gt_f32_e64 s[12:13], v102, v20
	v_addc_co_u32_e64 v77, vcc, 0, v77, s[8:9]
	v_cmp_gt_f32_e64 s[8:9], v102, v21
	v_addc_co_u32_e64 v76, vcc, 0, v76, s[10:11]
	v_cmp_gt_f32_e64 s[10:11], v102, v22
	v_addc_co_u32_e64 v75, vcc, 0, v75, s[12:13]
	v_cmp_gt_f32_e64 s[12:13], v102, v23
	v_addc_co_u32_e64 v74, vcc, 0, v74, s[8:9]
	v_cmp_gt_f32_e64 s[8:9], v102, v24
	v_addc_co_u32_e64 v73, vcc, 0, v73, s[10:11]
	v_cmp_gt_f32_e64 s[10:11], v102, v25
	v_addc_co_u32_e64 v72, vcc, 0, v72, s[12:13]
	v_cmp_gt_f32_e64 s[12:13], v102, v26
	v_addc_co_u32_e64 v71, vcc, 0, v71, s[8:9]
	v_cmp_ge_f32_e64 s[8:9], v102, v27
	v_addc_co_u32_e64 v70, vcc, 0, v70, s[10:11]
	v_cmp_ge_f32_e64 s[10:11], v102, v28
	v_addc_co_u32_e64 v69, vcc, 0, v69, s[12:13]
	v_cmp_ge_f32_e64 s[12:13], v102, v29
	s_and_b64 s[8:9], s[8:9], s[6:7]
	v_addc_co_u32_e64 v68, vcc, 0, v68, s[8:9]
	v_cmp_ge_f32_e64 s[8:9], v102, v30
	v_addc_co_u32_e64 v67, vcc, 0, v67, s[10:11]
	v_cmp_ge_f32_e64 s[10:11], v102, v31
	v_addc_co_u32_e64 v66, vcc, 0, v66, s[12:13]
	s_nop 0
	v_addc_co_u32_e64 v65, vcc, 0, v65, s[8:9]
	v_addc_co_u32_e64 v64, vcc, 0, v64, s[10:11]
	s_cmp_le_u32 s14, 55
	s_cbranch_scc1 .Lrk_done
; __device__ __forceinline__ void cmp_phase(LAS unsigned char* lds, const bf16_t* __restrict__ P, const bf16_t* __restrict__ Kc, const bf16_t* __restrict__ Vc,
;                                           bf16_t* __restrict__ ocmp, unsigned long long* __restrict__ mask, int G, const int wave0) {
;     ...
;             const int kmax = ((tw0 + 31) >> 6) + 1;
; #pragma nounroll
;             for (int k = 0; k < kmax; ++k) {
;                 const float sk = sc[k];
;                 const int kk = k - hi;
; #pragma unroll
;                 for (int i = 0; i < 32; ++i) rank[i] += ((sk > s[i]) || ((sk == s[i]) && (kk < 2 * i))) ? 1 : 0;
;             }
	v_cmp_gt_f32_e64 s[8:9], v103, v0
	v_cmp_gt_f32_e64 s[10:11], v103, v1
	v_cmp_gt_f32_e64 s[12:13], v103, v2
	v_addc_co_u32_e64 v97, vcc, 0, v97, s[8:9]
	v_cmp_gt_f32_e64 s[8:9], v103, v3
	v_addc_co_u32_e64 v96, vcc, 0, v96, s[10:11]
	v_cmp_gt_f32_e64 s[10:11], v103, v4
	v_addc_co_u32_e64 v95, vcc, 0, v95, s[12:13]
	v_cmp_gt_f32_e64 s[12:13], v103, v5
	v_addc_co_u32_e64 v94, vcc, 0, v94, s[8:9]
	v_cmp_gt_f32_e64 s[8:9], v103, v6
	v_addc_co_u32_e64 v93, vcc, 0, v93, s[10:11]
	v_cmp_gt_f32_e64 s[10:11], v103, v7
	v_addc_co_u32_e64 v92, vcc, 0, v92, s[12:13]
	v_cmp_gt_f32_e64 s[12:13], v103, v8
	v_addc_co_u32_e64 v91, vcc, 0, v91, s[8:9]
	v_cmp_gt_f32_e64 s[8:9], v103, v9
	v_addc_co_u32_e64 v90, vcc, 0, v90, s[10:11]
	v_cmp_gt_f32_e64 s[10:11], v103, v10
	v_addc_co_u32_e64 v89, vcc, 0, v89, s[12:13]
	v_cmp_gt_f32_e64 s[12:13], v103, v11
	v_addc_co_u32_e64 v88, vcc, 0, v88, s[8:9]
	v_cmp_gt_f32_e64 s[8:9], v103, v12
	v_addc_co_u32_e64 v87, vcc, 0, v87, s[10:11]
	v_cmp_gt_f32_e64 s[10:11], v103, v13
	v_addc_co_u32_e64 v86, vcc, 0, v86, s[12:13]
	v_cmp_gt_f32_e64 s[12:13], v103, v14
	v_addc_co_u32_e64 v85, vcc, 0, v85, s[8:9]
	v_cmp_gt_f32_e64 s[8:9], v103, v15
	v_addc_co_u32_e64 v84, vcc, 0, v84, s[10:11]
	v_cmp_gt_f32_e64 s[10:11], v103, v16
	v_addc_co_u32_e64 v83, vcc, 0, v83, s[12:13]
	v_cmp_gt_f32_e64 s[12:13], v103, v17
	v_addc_co_u32_e64 v81, vcc, 0, v81, s[8:9]
	v_cmp_gt_f32_e64 s[8:9], v103, v18
	v_addc_co_u32_e64 v79, vcc, 0, v79, s[10:11]
	v_cmp_gt_f32_e64 s[10:11], v103, v19
	v_addc_co_u32_e64 v78, vcc, 0, v78, s[12:13]
	v_cmp_gt_f32_e64 s[12:13], v103, v20
	v_addc_co_u32_e64 v77, vcc, 0, v77, s[8:9]
	v_cmp_gt_f32_e64 s[8:9], v103, v21
	v_addc_co_u32_e64 v76, vcc, 0, v76, s[10:11]
	v_cmp_gt_f32_e64 s[10:11], v103, v22
	v_addc_co_u32_e64 v75, vcc, 0, v75, s[12:13]
	v_cmp_gt_f32_e64 s[12:13], v103, v23
	v_addc_co_u32_e64 v74, vcc, 0, v74, s[8:9]
	v_cmp_gt_f32_e64 s[8:9], v103, v24
	v_addc_co_u32_e64 v73, vcc, 0, v73, s[10:11]
	v_cmp_gt_f32_e64 s[10:11], v103, v25
	v_addc_co_u32_e64 v72, vcc, 0, v72, s[12:13]
	v_cmp_gt_f32_e64 s[12:13], v103, v26
	v_addc_co_u32_e64 v71, vcc, 0, v71, s[8:9]
	v_cmp_gt_f32_e64 s[8:9], v103, v27
	v_addc_co_u32_e64 v70, vcc, 0, v70, s[10:11]
	v_cmp_ge_f32_e64 s[10:11], v103, v28
	v_addc_co_u32_e64 v69, vcc, 0, v69, s[12:13]
	v_cmp_ge_f32_e64 s[12:13], v103, v29
	v_addc_co_u32_e64 v68, vcc, 0, v68, s[8:9]
	v_cmp_ge_f32_e64 s[8:9], v103, v30
	v_addc_co_u32_e64 v67, vcc, 0, v67, s[10:11]
	v_cmp_ge_f32_e64 s[10:11], v103, v31
	v_addc_co_u32_e64 v66, vcc, 0, v66, s[12:13]
	s_nop 0
	v_addc_co_u32_e64 v65, vcc, 0, v65, s[8:9]
	v_addc_co_u32_e64 v64, vcc, 0, v64, s[10:11]
	s_cmp_le_u32 s14, 56
	s_cbranch_scc1 .Lrk_done
	ds_read2_b32 v[102:103], v104 offset0:58 offset1:59
	s_waitcnt lgkmcnt(1)
	v_cmp_gt_f32_e64 s[8:9], v100, v0
	v_cmp_gt_f32_e64 s[10:11], v100, v1
	v_cmp_gt_f32_e64 s[12:13], v100, v2
	v_addc_co_u32_e64 v97, vcc, 0, v97, s[8:9]
	v_cmp_gt_f32_e64 s[8:9], v100, v3
	v_addc_co_u32_e64 v96, vcc, 0, v96, s[10:11]
	v_cmp_gt_f32_e64 s[10:11], v100, v4
	v_addc_co_u32_e64 v95, vcc, 0, v95, s[12:13]
	v_cmp_gt_f32_e64 s[12:13], v100, v5
	v_addc_co_u32_e64 v94, vcc, 0, v94, s[8:9]
	v_cmp_gt_f32_e64 s[8:9], v100, v6
	v_addc_co_u32_e64 v93, vcc, 0, v93, s[10:11]
	v_cmp_gt_f32_e64 s[10:11], v100, v7
	v_addc_co_u32_e64 v92, vcc, 0, v92, s[12:13]
	v_cmp_gt_f32_e64 s[12:13], v100, v8
	v_addc_co_u32_e64 v91, vcc, 0, v91, s[8:9]
	v_cmp_gt_f32_e64 s[8:9], v100, v9
	v_addc_co_u32_e64 v90, vcc, 0, v90, s[10:11]
	v_cmp_gt_f32_e64 s[10:11], v100, v10
	v_addc_co_u32_e64 v89, vcc, 0, v89, s[12:13]
	v_cmp_gt_f32_e64 s[12:13], v100, v11
	v_addc_co_u32_e64 v88, vcc, 0, v88, s[8:9]
	v_cmp_gt_f32_e64 s[8:9], v100, v12
	v_addc_co_u32_e64 v87, vcc, 0, v87, s[10:11]
	v_cmp_gt_f32_e64 s[10:11], v100, v13
	v_addc_co_u32_e64 v86, vcc, 0, v86, s[12:13]
	v_cmp_gt_f32_e64 s[12:13], v100, v14
	v_addc_co_u32_e64 v85, vcc, 0, v85, s[8:9]
	v_cmp_gt_f32_e64 s[8:9], v100, v15
	v_addc_co_u32_e64 v84, vcc, 0, v84, s[10:11]
	v_cmp_gt_f32_e64 s[10:11], v100, v16
	v_addc_co_u32_e64 v83, vcc, 0, v83, s[12:13]
	v_cmp_gt_f32_e64 s[12:13], v100, v17
	v_addc_co_u32_e64 v81, vcc, 0, v81, s[8:9]
	v_cmp_gt_f32_e64 s[8:9], v100, v18
	v_addc_co_u32_e64 v79, vcc, 0, v79, s[10:11]
	v_cmp_gt_f32_e64 s[10:11], v100, v19
	v_addc_co_u32_e64 v78, vcc, 0, v78, s[12:13]
	v_cmp_gt_f32_e64 s[12:13], v100, v20
	v_addc_co_u32_e64 v77, vcc, 0, v77, s[8:9]
	v_cmp_gt_f32_e64 s[8:9], v100, v21
	v_addc_co_u32_e64 v76, vcc, 0, v76, s[10:11]
	v_cmp_gt_f32_e64 s[10:11], v100, v22
	v_addc_co_u32_e64 v75, vcc, 0, v75, s[12:13]
	v_cmp_gt_f32_e64 s[12:13], v100, v23
	v_addc_co_u32_e64 v74, vcc, 0, v74, s[8:9]
	v_cmp_gt_f32_e64 s[8:9], v100, v24
	v_addc_co_u32_e64 v73, vcc, 0, v73, s[10:11]
	v_cmp_gt_f32_e64 s[10:11], v100, v25
	v_addc_co_u32_e64 v72, vcc, 0, v72, s[12:13]
	v_cmp_gt_f32_e64 s[12:13], v100, v26
	v_addc_co_u32_e64 v71, vcc, 0, v71, s[8:9]
	v_cmp_gt_f32_e64 s[8:9], v100, v27
	v_addc_co_u32_e64 v70, vcc, 0, v70, s[10:11]
	v_cmp_ge_f32_e64 s[10:11], v100, v28
	v_addc_co_u32_e64 v69, vcc, 0, v69, s[12:13]
	v_cmp_ge_f32_e64 s[12:13], v100, v29
	v_addc_co_u32_e64 v68, vcc, 0, v68, s[8:9]
	v_cmp_ge_f32_e64 s[8:9], v100, v30
	s_and_b64 s[10:11], s[10:11], s[6:7]
	v_addc_co_u32_e64 v67, vcc, 0, v67, s[10:11]
	v_cmp_ge_f32_e64 s[10:11], v100, v31
	v_addc_co_u32_e64 v66, vcc, 0, v66, s[12:13]
	s_nop 0
	v_addc_co_u32_e64 v65, vcc, 0, v65, s[8:9]
	v_addc_co_u32_e64 v64, vcc, 0, v64, s[10:11]
	s_cmp_le_u32 s14, 57
	s_cbranch_scc1 .Lrk_done
; __device__ __forceinline__ void cmp_phase(LAS unsigned char* lds, const bf16_t* __restrict__ P, const bf16_t* __restrict__ Kc, const bf16_t* __restrict__ Vc,
;                                           bf16_t* __restrict__ ocmp, unsigned long long* __restrict__ mask, int G, const int wave0) {
;     ...
;             const int kmax = ((tw0 + 31) >> 6) + 1;
; #pragma nounroll
;             for (int k = 0; k < kmax; ++k) {
;                 const float sk = sc[k];
;                 const int kk = k - hi;
; #pragma unroll
;                 for (int i = 0; i < 32; ++i) rank[i] += ((sk > s[i]) || ((sk == s[i]) && (kk < 2 * i))) ? 1 : 0;
;             }
	v_cmp_gt_f32_e64 s[8:9], v101, v0
	v_cmp_gt_f32_e64 s[10:11], v101, v1
	v_cmp_gt_f32_e64 s[12:13], v101, v2
	v_addc_co_u32_e64 v97, vcc, 0, v97, s[8:9]
	v_cmp_gt_f32_e64 s[8:9], v101, v3
	v_addc_co_u32_e64 v96, vcc, 0, v96, s[10:11]
	v_cmp_gt_f32_e64 s[10:11], v101, v4
	v_addc_co_u32_e64 v95, vcc, 0, v95, s[12:13]
	v_cmp_gt_f32_e64 s[12:13], v101, v5
	v_addc_co_u32_e64 v94, vcc, 0, v94, s[8:9]
	v_cmp_gt_f32_e64 s[8:9], v101, v6
	v_addc_co_u32_e64 v93, vcc, 0, v93, s[10:11]
	v_cmp_gt_f32_e64 s[10:11], v101, v7
	v_addc_co_u32_e64 v92, vcc, 0, v92, s[12:13]
	v_cmp_gt_f32_e64 s[12:13], v101, v8
	v_addc_co_u32_e64 v91, vcc, 0, v91, s[8:9]
	v_cmp_gt_f32_e64 s[8:9], v101, v9
	v_addc_co_u32_e64 v90, vcc, 0, v90, s[10:11]
	v_cmp_gt_f32_e64 s[10:11], v101, v10
	v_addc_co_u32_e64 v89, vcc, 0, v89, s[12:13]
	v_cmp_gt_f32_e64 s[12:13], v101, v11
	v_addc_co_u32_e64 v88, vcc, 0, v88, s[8:9]
	v_cmp_gt_f32_e64 s[8:9], v101, v12
	v_addc_co_u32_e64 v87, vcc, 0, v87, s[10:11]
	v_cmp_gt_f32_e64 s[10:11], v101, v13
	v_addc_co_u32_e64 v86, vcc, 0, v86, s[12:13]
	v_cmp_gt_f32_e64 s[12:13], v101, v14
	v_addc_co_u32_e64 v85, vcc, 0, v85, s[8:9]
	v_cmp_gt_f32_e64 s[8:9], v101, v15
	v_addc_co_u32_e64 v84, vcc, 0, v84, s[10:11]
	v_cmp_gt_f32_e64 s[10:11], v101, v16
	v_addc_co_u32_e64 v83, vcc, 0, v83, s[12:13]
	v_cmp_gt_f32_e64 s[12:13], v101, v17
	v_addc_co_u32_e64 v81, vcc, 0, v81, s[8:9]
	v_cmp_gt_f32_e64 s[8:9], v101, v18
	v_addc_co_u32_e64 v79, vcc, 0, v79, s[10:11]
	v_cmp_gt_f32_e64 s[10:11], v101, v19
	v_addc_co_u32_e64 v78, vcc, 0, v78, s[12:13]
	v_cmp_gt_f32_e64 s[12:13], v101, v20
	v_addc_co_u32_e64 v77, vcc, 0, v77, s[8:9]
	v_cmp_gt_f32_e64 s[8:9], v101, v21
	v_addc_co_u32_e64 v76, vcc, 0, v76, s[10:11]
	v_cmp_gt_f32_e64 s[10:11], v101, v22
	v_addc_co_u32_e64 v75, vcc, 0, v75, s[12:13]
	v_cmp_gt_f32_e64 s[12:13], v101, v23
	v_addc_co_u32_e64 v74, vcc, 0, v74, s[8:9]
	v_cmp_gt_f32_e64 s[8:9], v101, v24
	v_addc_co_u32_e64 v73, vcc, 0, v73, s[10:11]
	v_cmp_gt_f32_e64 s[10:11], v101, v25
	v_addc_co_u32_e64 v72, vcc, 0, v72, s[12:13]
	v_cmp_gt_f32_e64 s[12:13], v101, v26
	v_addc_co_u32_e64 v71, vcc, 0, v71, s[8:9]
	v_cmp_gt_f32_e64 s[8:9], v101, v27
	v_addc_co_u32_e64 v70, vcc, 0, v70, s[10:11]
	v_cmp_gt_f32_e64 s[10:11], v101, v28
	v_addc_co_u32_e64 v69, vcc, 0, v69, s[12:13]
	v_cmp_ge_f32_e64 s[12:13], v101, v29
	v_addc_co_u32_e64 v68, vcc, 0, v68, s[8:9]
	v_cmp_ge_f32_e64 s[8:9], v101, v30
	v_addc_co_u32_e64 v67, vcc, 0, v67, s[10:11]
	v_cmp_ge_f32_e64 s[10:11], v101, v31
	v_addc_co_u32_e64 v66, vcc, 0, v66, s[12:13]
	s_nop 0
	v_addc_co_u32_e64 v65, vcc, 0, v65, s[8:9]
	v_addc_co_u32_e64 v64, vcc, 0, v64, s[10:11]
	s_cmp_le_u32 s14, 58
	s_cbranch_scc1 .Lrk_done
	ds_read2_b32 v[100:101], v104 offset0:60 offset1:61
	s_waitcnt lgkmcnt(1)
	v_cmp_gt_f32_e64 s[8:9], v102, v0
	v_cmp_gt_f32_e64 s[10:11], v102, v1
	v_cmp_gt_f32_e64 s[12:13], v102, v2
	v_addc_co_u32_e64 v97, vcc, 0, v97, s[8:9]
	v_cmp_gt_f32_e64 s[8:9], v102, v3
	v_addc_co_u32_e64 v96, vcc, 0, v96, s[10:11]
	v_cmp_gt_f32_e64 s[10:11], v102, v4
	v_addc_co_u32_e64 v95, vcc, 0, v95, s[12:13]
	v_cmp_gt_f32_e64 s[12:13], v102, v5
	v_addc_co_u32_e64 v94, vcc, 0, v94, s[8:9]
	v_cmp_gt_f32_e64 s[8:9], v102, v6
	v_addc_co_u32_e64 v93, vcc, 0, v93, s[10:11]
	v_cmp_gt_f32_e64 s[10:11], v102, v7
	v_addc_co_u32_e64 v92, vcc, 0, v92, s[12:13]
	v_cmp_gt_f32_e64 s[12:13], v102, v8
	v_addc_co_u32_e64 v91, vcc, 0, v91, s[8:9]
	v_cmp_gt_f32_e64 s[8:9], v102, v9
	v_addc_co_u32_e64 v90, vcc, 0, v90, s[10:11]
	v_cmp_gt_f32_e64 s[10:11], v102, v10
	v_addc_co_u32_e64 v89, vcc, 0, v89, s[12:13]
	v_cmp_gt_f32_e64 s[12:13], v102, v11
	v_addc_co_u32_e64 v88, vcc, 0, v88, s[8:9]
	v_cmp_gt_f32_e64 s[8:9], v102, v12
	v_addc_co_u32_e64 v87, vcc, 0, v87, s[10:11]
	v_cmp_gt_f32_e64 s[10:11], v102, v13
	v_addc_co_u32_e64 v86, vcc, 0, v86, s[12:13]
	v_cmp_gt_f32_e64 s[12:13], v102, v14
	v_addc_co_u32_e64 v85, vcc, 0, v85, s[8:9]
	v_cmp_gt_f32_e64 s[8:9], v102, v15
	v_addc_co_u32_e64 v84, vcc, 0, v84, s[10:11]
	v_cmp_gt_f32_e64 s[10:11], v102, v16
	v_addc_co_u32_e64 v83, vcc, 0, v83, s[12:13]
	v_cmp_gt_f32_e64 s[12:13], v102, v17
	v_addc_co_u32_e64 v81, vcc, 0, v81, s[8:9]
	v_cmp_gt_f32_e64 s[8:9], v102, v18
	v_addc_co_u32_e64 v79, vcc, 0, v79, s[10:11]
	v_cmp_gt_f32_e64 s[10:11], v102, v19
	v_addc_co_u32_e64 v78, vcc, 0, v78, s[12:13]
	v_cmp_gt_f32_e64 s[12:13], v102, v20
	v_addc_co_u32_e64 v77, vcc, 0, v77, s[8:9]
	v_cmp_gt_f32_e64 s[8:9], v102, v21
	v_addc_co_u32_e64 v76, vcc, 0, v76, s[10:11]
	v_cmp_gt_f32_e64 s[10:11], v102, v22
	v_addc_co_u32_e64 v75, vcc, 0, v75, s[12:13]
	v_cmp_gt_f32_e64 s[12:13], v102, v23
	v_addc_co_u32_e64 v74, vcc, 0, v74, s[8:9]
	v_cmp_gt_f32_e64 s[8:9], v102, v24
	v_addc_co_u32_e64 v73, vcc, 0, v73, s[10:11]
	v_cmp_gt_f32_e64 s[10:11], v102, v25
	v_addc_co_u32_e64 v72, vcc, 0, v72, s[12:13]
	v_cmp_gt_f32_e64 s[12:13], v102, v26
	v_addc_co_u32_e64 v71, vcc, 0, v71, s[8:9]
	v_cmp_gt_f32_e64 s[8:9], v102, v27
	v_addc_co_u32_e64 v70, vcc, 0, v70, s[10:11]
	v_cmp_gt_f32_e64 s[10:11], v102, v28
	v_addc_co_u32_e64 v69, vcc, 0, v69, s[12:13]
	v_cmp_ge_f32_e64 s[12:13], v102, v29
	v_addc_co_u32_e64 v68, vcc, 0, v68, s[8:9]
	v_cmp_ge_f32_e64 s[8:9], v102, v30
	v_addc_co_u32_e64 v67, vcc, 0, v67, s[10:11]
	v_cmp_ge_f32_e64 s[10:11], v102, v31
	s_and_b64 s[12:13], s[12:13], s[6:7]
	v_addc_co_u32_e64 v66, vcc, 0, v66, s[12:13]
	s_nop 0
	v_addc_co_u32_e64 v65, vcc, 0, v65, s[8:9]
	v_addc_co_u32_e64 v64, vcc, 0, v64, s[10:11]
	s_cmp_le_u32 s14, 59
	s_cbranch_scc1 .Lrk_done
; __device__ __forceinline__ void cmp_phase(LAS unsigned char* lds, const bf16_t* __restrict__ P, const bf16_t* __restrict__ Kc, const bf16_t* __restrict__ Vc,
;                                           bf16_t* __restrict__ ocmp, unsigned long long* __restrict__ mask, int G, const int wave0) {
;     ...
;             const int kmax = ((tw0 + 31) >> 6) + 1;
; #pragma nounroll
;             for (int k = 0; k < kmax; ++k) {
;                 const float sk = sc[k];
;                 const int kk = k - hi;
; #pragma unroll
;                 for (int i = 0; i < 32; ++i) rank[i] += ((sk > s[i]) || ((sk == s[i]) && (kk < 2 * i))) ? 1 : 0;
;             }
	v_cmp_gt_f32_e64 s[8:9], v103, v0
	v_cmp_gt_f32_e64 s[10:11], v103, v1
	v_cmp_gt_f32_e64 s[12:13], v103, v2
	v_addc_co_u32_e64 v97, vcc, 0, v97, s[8:9]
	v_cmp_gt_f32_e64 s[8:9], v103, v3
	v_addc_co_u32_e64 v96, vcc, 0, v96, s[10:11]
	v_cmp_gt_f32_e64 s[10:11], v103, v4
	v_addc_co_u32_e64 v95, vcc, 0, v95, s[12:13]
	v_cmp_gt_f32_e64 s[12:13], v103, v5
	v_addc_co_u32_e64 v94, vcc, 0, v94, s[8:9]
	v_cmp_gt_f32_e64 s[8:9], v103, v6
	v_addc_co_u32_e64 v93, vcc, 0, v93, s[10:11]
	v_cmp_gt_f32_e64 s[10:11], v103, v7
	v_addc_co_u32_e64 v92, vcc, 0, v92, s[12:13]
	v_cmp_gt_f32_e64 s[12:13], v103, v8
	v_addc_co_u32_e64 v91, vcc, 0, v91, s[8:9]
	v_cmp_gt_f32_e64 s[8:9], v103, v9
	v_addc_co_u32_e64 v90, vcc, 0, v90, s[10:11]
	v_cmp_gt_f32_e64 s[10:11], v103, v10
	v_addc_co_u32_e64 v89, vcc, 0, v89, s[12:13]
	v_cmp_gt_f32_e64 s[12:13], v103, v11
	v_addc_co_u32_e64 v88, vcc, 0, v88, s[8:9]
	v_cmp_gt_f32_e64 s[8:9], v103, v12
	v_addc_co_u32_e64 v87, vcc, 0, v87, s[10:11]
	v_cmp_gt_f32_e64 s[10:11], v103, v13
	v_addc_co_u32_e64 v86, vcc, 0, v86, s[12:13]
	v_cmp_gt_f32_e64 s[12:13], v103, v14
	v_addc_co_u32_e64 v85, vcc, 0, v85, s[8:9]
	v_cmp_gt_f32_e64 s[8:9], v103, v15
	v_addc_co_u32_e64 v84, vcc, 0, v84, s[10:11]
	v_cmp_gt_f32_e64 s[10:11], v103, v16
	v_addc_co_u32_e64 v83, vcc, 0, v83, s[12:13]
	v_cmp_gt_f32_e64 s[12:13], v103, v17
	v_addc_co_u32_e64 v81, vcc, 0, v81, s[8:9]
	v_cmp_gt_f32_e64 s[8:9], v103, v18
	v_addc_co_u32_e64 v79, vcc, 0, v79, s[10:11]
	v_cmp_gt_f32_e64 s[10:11], v103, v19
	v_addc_co_u32_e64 v78, vcc, 0, v78, s[12:13]
	v_cmp_gt_f32_e64 s[12:13], v103, v20
	v_addc_co_u32_e64 v77, vcc, 0, v77, s[8:9]
	v_cmp_gt_f32_e64 s[8:9], v103, v21
	v_addc_co_u32_e64 v76, vcc, 0, v76, s[10:11]
	v_cmp_gt_f32_e64 s[10:11], v103, v22
	v_addc_co_u32_e64 v75, vcc, 0, v75, s[12:13]
	v_cmp_gt_f32_e64 s[12:13], v103, v23
	v_addc_co_u32_e64 v74, vcc, 0, v74, s[8:9]
	v_cmp_gt_f32_e64 s[8:9], v103, v24
	v_addc_co_u32_e64 v73, vcc, 0, v73, s[10:11]
	v_cmp_gt_f32_e64 s[10:11], v103, v25
	v_addc_co_u32_e64 v72, vcc, 0, v72, s[12:13]
	v_cmp_gt_f32_e64 s[12:13], v103, v26
	v_addc_co_u32_e64 v71, vcc, 0, v71, s[8:9]
	v_cmp_gt_f32_e64 s[8:9], v103, v27
	v_addc_co_u32_e64 v70, vcc, 0, v70, s[10:11]
	v_cmp_gt_f32_e64 s[10:11], v103, v28
	v_addc_co_u32_e64 v69, vcc, 0, v69, s[12:13]
	v_cmp_gt_f32_e64 s[12:13], v103, v29
	v_addc_co_u32_e64 v68, vcc, 0, v68, s[8:9]
	v_cmp_ge_f32_e64 s[8:9], v103, v30
	v_addc_co_u32_e64 v67, vcc, 0, v67, s[10:11]
	v_cmp_ge_f32_e64 s[10:11], v103, v31
	v_addc_co_u32_e64 v66, vcc, 0, v66, s[12:13]
	s_nop 0
	v_addc_co_u32_e64 v65, vcc, 0, v65, s[8:9]
	v_addc_co_u32_e64 v64, vcc, 0, v64, s[10:11]
	s_cmp_le_u32 s14, 60
	s_cbranch_scc1 .Lrk_done
	ds_read2_b32 v[102:103], v104 offset0:62 offset1:63
	s_waitcnt lgkmcnt(1)
	v_cmp_gt_f32_e64 s[8:9], v100, v0
	v_cmp_gt_f32_e64 s[10:11], v100, v1
	v_cmp_gt_f32_e64 s[12:13], v100, v2
	v_addc_co_u32_e64 v97, vcc, 0, v97, s[8:9]
	v_cmp_gt_f32_e64 s[8:9], v100, v3
	v_addc_co_u32_e64 v96, vcc, 0, v96, s[10:11]
	v_cmp_gt_f32_e64 s[10:11], v100, v4
	v_addc_co_u32_e64 v95, vcc, 0, v95, s[12:13]
	v_cmp_gt_f32_e64 s[12:13], v100, v5
	v_addc_co_u32_e64 v94, vcc, 0, v94, s[8:9]
	v_cmp_gt_f32_e64 s[8:9], v100, v6
	v_addc_co_u32_e64 v93, vcc, 0, v93, s[10:11]
	v_cmp_gt_f32_e64 s[10:11], v100, v7
	v_addc_co_u32_e64 v92, vcc, 0, v92, s[12:13]
	v_cmp_gt_f32_e64 s[12:13], v100, v8
	v_addc_co_u32_e64 v91, vcc, 0, v91, s[8:9]
	v_cmp_gt_f32_e64 s[8:9], v100, v9
	v_addc_co_u32_e64 v90, vcc, 0, v90, s[10:11]
	v_cmp_gt_f32_e64 s[10:11], v100, v10
	v_addc_co_u32_e64 v89, vcc, 0, v89, s[12:13]
	v_cmp_gt_f32_e64 s[12:13], v100, v11
	v_addc_co_u32_e64 v88, vcc, 0, v88, s[8:9]
	v_cmp_gt_f32_e64 s[8:9], v100, v12
	v_addc_co_u32_e64 v87, vcc, 0, v87, s[10:11]
	v_cmp_gt_f32_e64 s[10:11], v100, v13
	v_addc_co_u32_e64 v86, vcc, 0, v86, s[12:13]
	v_cmp_gt_f32_e64 s[12:13], v100, v14
	v_addc_co_u32_e64 v85, vcc, 0, v85, s[8:9]
	v_cmp_gt_f32_e64 s[8:9], v100, v15
	v_addc_co_u32_e64 v84, vcc, 0, v84, s[10:11]
	v_cmp_gt_f32_e64 s[10:11], v100, v16
	v_addc_co_u32_e64 v83, vcc, 0, v83, s[12:13]
	v_cmp_gt_f32_e64 s[12:13], v100, v17
	v_addc_co_u32_e64 v81, vcc, 0, v81, s[8:9]
	v_cmp_gt_f32_e64 s[8:9], v100, v18
	v_addc_co_u32_e64 v79, vcc, 0, v79, s[10:11]
	v_cmp_gt_f32_e64 s[10:11], v100, v19
	v_addc_co_u32_e64 v78, vcc, 0, v78, s[12:13]
	v_cmp_gt_f32_e64 s[12:13], v100, v20
	v_addc_co_u32_e64 v77, vcc, 0, v77, s[8:9]
	v_cmp_gt_f32_e64 s[8:9], v100, v21
	v_addc_co_u32_e64 v76, vcc, 0, v76, s[10:11]
	v_cmp_gt_f32_e64 s[10:11], v100, v22
	v_addc_co_u32_e64 v75, vcc, 0, v75, s[12:13]
	v_cmp_gt_f32_e64 s[12:13], v100, v23
	v_addc_co_u32_e64 v74, vcc, 0, v74, s[8:9]
	v_cmp_gt_f32_e64 s[8:9], v100, v24
	v_addc_co_u32_e64 v73, vcc, 0, v73, s[10:11]
	v_cmp_gt_f32_e64 s[10:11], v100, v25
	v_addc_co_u32_e64 v72, vcc, 0, v72, s[12:13]
	v_cmp_gt_f32_e64 s[12:13], v100, v26
	v_addc_co_u32_e64 v71, vcc, 0, v71, s[8:9]
	v_cmp_gt_f32_e64 s[8:9], v100, v27
	v_addc_co_u32_e64 v70, vcc, 0, v70, s[10:11]
	v_cmp_gt_f32_e64 s[10:11], v100, v28
	v_addc_co_u32_e64 v69, vcc, 0, v69, s[12:13]
	v_cmp_gt_f32_e64 s[12:13], v100, v29
	v_addc_co_u32_e64 v68, vcc, 0, v68, s[8:9]
	v_cmp_ge_f32_e64 s[8:9], v100, v30
	v_addc_co_u32_e64 v67, vcc, 0, v67, s[10:11]
	v_cmp_ge_f32_e64 s[10:11], v100, v31
	v_addc_co_u32_e64 v66, vcc, 0, v66, s[12:13]
	s_nop 0
	s_and_b64 s[8:9], s[8:9], s[6:7]
	v_addc_co_u32_e64 v65, vcc, 0, v65, s[8:9]
	v_addc_co_u32_e64 v64, vcc, 0, v64, s[10:11]
	s_cmp_le_u32 s14, 61
	s_cbranch_scc1 .Lrk_done
; __device__ __forceinline__ void cmp_phase(LAS unsigned char* lds, const bf16_t* __restrict__ P, const bf16_t* __restrict__ Kc, const bf16_t* __restrict__ Vc,
;                                           bf16_t* __restrict__ ocmp, unsigned long long* __restrict__ mask, int G, const int wave0) {
;     ...
;             const int kmax = ((tw0 + 31) >> 6) + 1;
; #pragma nounroll
;             for (int k = 0; k < kmax; ++k) {
;                 const float sk = sc[k];
;                 const int kk = k - hi;
; #pragma unroll
;                 for (int i = 0; i < 32; ++i) rank[i] += ((sk > s[i]) || ((sk == s[i]) && (kk < 2 * i))) ? 1 : 0;
;             }
	v_cmp_gt_f32_e64 s[8:9], v101, v0
	v_cmp_gt_f32_e64 s[10:11], v101, v1
	v_cmp_gt_f32_e64 s[12:13], v101, v2
	v_addc_co_u32_e64 v97, vcc, 0, v97, s[8:9]
	v_cmp_gt_f32_e64 s[8:9], v101, v3
	v_addc_co_u32_e64 v96, vcc, 0, v96, s[10:11]
	v_cmp_gt_f32_e64 s[10:11], v101, v4
	v_addc_co_u32_e64 v95, vcc, 0, v95, s[12:13]
	v_cmp_gt_f32_e64 s[12:13], v101, v5
	v_addc_co_u32_e64 v94, vcc, 0, v94, s[8:9]
	v_cmp_gt_f32_e64 s[8:9], v101, v6
	v_addc_co_u32_e64 v93, vcc, 0, v93, s[10:11]
	v_cmp_gt_f32_e64 s[10:11], v101, v7
	v_addc_co_u32_e64 v92, vcc, 0, v92, s[12:13]
	v_cmp_gt_f32_e64 s[12:13], v101, v8
	v_addc_co_u32_e64 v91, vcc, 0, v91, s[8:9]
	v_cmp_gt_f32_e64 s[8:9], v101, v9
	v_addc_co_u32_e64 v90, vcc, 0, v90, s[10:11]
	v_cmp_gt_f32_e64 s[10:11], v101, v10
	v_addc_co_u32_e64 v89, vcc, 0, v89, s[12:13]
	v_cmp_gt_f32_e64 s[12:13], v101, v11
	v_addc_co_u32_e64 v88, vcc, 0, v88, s[8:9]
	v_cmp_gt_f32_e64 s[8:9], v101, v12
	v_addc_co_u32_e64 v87, vcc, 0, v87, s[10:11]
	v_cmp_gt_f32_e64 s[10:11], v101, v13
	v_addc_co_u32_e64 v86, vcc, 0, v86, s[12:13]
	v_cmp_gt_f32_e64 s[12:13], v101, v14
	v_addc_co_u32_e64 v85, vcc, 0, v85, s[8:9]
	v_cmp_gt_f32_e64 s[8:9], v101, v15
	v_addc_co_u32_e64 v84, vcc, 0, v84, s[10:11]
	v_cmp_gt_f32_e64 s[10:11], v101, v16
	v_addc_co_u32_e64 v83, vcc, 0, v83, s[12:13]
	v_cmp_gt_f32_e64 s[12:13], v101, v17
	v_addc_co_u32_e64 v81, vcc, 0, v81, s[8:9]
	v_cmp_gt_f32_e64 s[8:9], v101, v18
	v_addc_co_u32_e64 v79, vcc, 0, v79, s[10:11]
	v_cmp_gt_f32_e64 s[10:11], v101, v19
	v_addc_co_u32_e64 v78, vcc, 0, v78, s[12:13]
	v_cmp_gt_f32_e64 s[12:13], v101, v20
	v_addc_co_u32_e64 v77, vcc, 0, v77, s[8:9]
	v_cmp_gt_f32_e64 s[8:9], v101, v21
	v_addc_co_u32_e64 v76, vcc, 0, v76, s[10:11]
	v_cmp_gt_f32_e64 s[10:11], v101, v22
	v_addc_co_u32_e64 v75, vcc, 0, v75, s[12:13]
	v_cmp_gt_f32_e64 s[12:13], v101, v23
	v_addc_co_u32_e64 v74, vcc, 0, v74, s[8:9]
	v_cmp_gt_f32_e64 s[8:9], v101, v24
	v_addc_co_u32_e64 v73, vcc, 0, v73, s[10:11]
	v_cmp_gt_f32_e64 s[10:11], v101, v25
	v_addc_co_u32_e64 v72, vcc, 0, v72, s[12:13]
	v_cmp_gt_f32_e64 s[12:13], v101, v26
	v_addc_co_u32_e64 v71, vcc, 0, v71, s[8:9]
	v_cmp_gt_f32_e64 s[8:9], v101, v27
	v_addc_co_u32_e64 v70, vcc, 0, v70, s[10:11]
	v_cmp_gt_f32_e64 s[10:11], v101, v28
	v_addc_co_u32_e64 v69, vcc, 0, v69, s[12:13]
	v_cmp_gt_f32_e64 s[12:13], v101, v29
	v_addc_co_u32_e64 v68, vcc, 0, v68, s[8:9]
	v_cmp_gt_f32_e64 s[8:9], v101, v30
	v_addc_co_u32_e64 v67, vcc, 0, v67, s[10:11]
	v_cmp_ge_f32_e64 s[10:11], v101, v31
	v_addc_co_u32_e64 v66, vcc, 0, v66, s[12:13]
	s_nop 0
	v_addc_co_u32_e64 v65, vcc, 0, v65, s[8:9]
	v_addc_co_u32_e64 v64, vcc, 0, v64, s[10:11]
	s_cmp_le_u32 s14, 62
	s_cbranch_scc1 .Lrk_done
	s_waitcnt lgkmcnt(0)
	v_cmp_gt_f32_e64 s[8:9], v102, v0
	v_cmp_gt_f32_e64 s[10:11], v102, v1
	v_cmp_gt_f32_e64 s[12:13], v102, v2
	v_addc_co_u32_e64 v97, vcc, 0, v97, s[8:9]
	v_cmp_gt_f32_e64 s[8:9], v102, v3
	v_addc_co_u32_e64 v96, vcc, 0, v96, s[10:11]
	v_cmp_gt_f32_e64 s[10:11], v102, v4
	v_addc_co_u32_e64 v95, vcc, 0, v95, s[12:13]
	v_cmp_gt_f32_e64 s[12:13], v102, v5
	v_addc_co_u32_e64 v94, vcc, 0, v94, s[8:9]
	v_cmp_gt_f32_e64 s[8:9], v102, v6
	v_addc_co_u32_e64 v93, vcc, 0, v93, s[10:11]
	v_cmp_gt_f32_e64 s[10:11], v102, v7
	v_addc_co_u32_e64 v92, vcc, 0, v92, s[12:13]
	v_cmp_gt_f32_e64 s[12:13], v102, v8
	v_addc_co_u32_e64 v91, vcc, 0, v91, s[8:9]
	v_cmp_gt_f32_e64 s[8:9], v102, v9
	v_addc_co_u32_e64 v90, vcc, 0, v90, s[10:11]
	v_cmp_gt_f32_e64 s[10:11], v102, v10
	v_addc_co_u32_e64 v89, vcc, 0, v89, s[12:13]
	v_cmp_gt_f32_e64 s[12:13], v102, v11
	v_addc_co_u32_e64 v88, vcc, 0, v88, s[8:9]
	v_cmp_gt_f32_e64 s[8:9], v102, v12
	v_addc_co_u32_e64 v87, vcc, 0, v87, s[10:11]
	v_cmp_gt_f32_e64 s[10:11], v102, v13
	v_addc_co_u32_e64 v86, vcc, 0, v86, s[12:13]
	v_cmp_gt_f32_e64 s[12:13], v102, v14
	v_addc_co_u32_e64 v85, vcc, 0, v85, s[8:9]
	v_cmp_gt_f32_e64 s[8:9], v102, v15
	v_addc_co_u32_e64 v84, vcc, 0, v84, s[10:11]
	v_cmp_gt_f32_e64 s[10:11], v102, v16
	v_addc_co_u32_e64 v83, vcc, 0, v83, s[12:13]
	v_cmp_gt_f32_e64 s[12:13], v102, v17
	v_addc_co_u32_e64 v81, vcc, 0, v81, s[8:9]
	v_cmp_gt_f32_e64 s[8:9], v102, v18
	v_addc_co_u32_e64 v79, vcc, 0, v79, s[10:11]
	v_cmp_gt_f32_e64 s[10:11], v102, v19
	v_addc_co_u32_e64 v78, vcc, 0, v78, s[12:13]
	v_cmp_gt_f32_e64 s[12:13], v102, v20
	v_addc_co_u32_e64 v77, vcc, 0, v77, s[8:9]
	v_cmp_gt_f32_e64 s[8:9], v102, v21
	v_addc_co_u32_e64 v76, vcc, 0, v76, s[10:11]
	v_cmp_gt_f32_e64 s[10:11], v102, v22
	v_addc_co_u32_e64 v75, vcc, 0, v75, s[12:13]
	v_cmp_gt_f32_e64 s[12:13], v102, v23
	v_addc_co_u32_e64 v74, vcc, 0, v74, s[8:9]
	v_cmp_gt_f32_e64 s[8:9], v102, v24
	v_addc_co_u32_e64 v73, vcc, 0, v73, s[10:11]
	v_cmp_gt_f32_e64 s[10:11], v102, v25
	v_addc_co_u32_e64 v72, vcc, 0, v72, s[12:13]
	v_cmp_gt_f32_e64 s[12:13], v102, v26
	v_addc_co_u32_e64 v71, vcc, 0, v71, s[8:9]
	v_cmp_gt_f32_e64 s[8:9], v102, v27
	v_addc_co_u32_e64 v70, vcc, 0, v70, s[10:11]
	v_cmp_gt_f32_e64 s[10:11], v102, v28
	v_addc_co_u32_e64 v69, vcc, 0, v69, s[12:13]
	v_cmp_gt_f32_e64 s[12:13], v102, v29
	v_addc_co_u32_e64 v68, vcc, 0, v68, s[8:9]
	v_cmp_gt_f32_e64 s[8:9], v102, v30
	v_addc_co_u32_e64 v67, vcc, 0, v67, s[10:11]
	v_cmp_ge_f32_e64 s[10:11], v102, v31
	v_addc_co_u32_e64 v66, vcc, 0, v66, s[12:13]
	s_nop 0
	v_addc_co_u32_e64 v65, vcc, 0, v65, s[8:9]
	s_and_b64 s[10:11], s[10:11], s[6:7]
	v_addc_co_u32_e64 v64, vcc, 0, v64, s[10:11]
	s_cmp_le_u32 s14, 63
	s_cbranch_scc1 .Lrk_done
; __device__ __forceinline__ void cmp_phase(LAS unsigned char* lds, const bf16_t* __restrict__ P, const bf16_t* __restrict__ Kc, const bf16_t* __restrict__ Vc,
;                                           bf16_t* __restrict__ ocmp, unsigned long long* __restrict__ mask, int G, const int wave0) {
;     ...
;             const int kmax = ((tw0 + 31) >> 6) + 1;
; #pragma nounroll
;             for (int k = 0; k < kmax; ++k) {
;                 const float sk = sc[k];
;                 const int kk = k - hi;
; #pragma unroll
;                 for (int i = 0; i < 32; ++i) rank[i] += ((sk > s[i]) || ((sk == s[i]) && (kk < 2 * i))) ? 1 : 0;
;             }
	v_cmp_gt_f32_e64 s[8:9], v103, v0
	v_cmp_gt_f32_e64 s[10:11], v103, v1
	v_cmp_gt_f32_e64 s[12:13], v103, v2
	v_addc_co_u32_e64 v97, vcc, 0, v97, s[8:9]
	v_cmp_gt_f32_e64 s[8:9], v103, v3
	v_addc_co_u32_e64 v96, vcc, 0, v96, s[10:11]
	v_cmp_gt_f32_e64 s[10:11], v103, v4
	v_addc_co_u32_e64 v95, vcc, 0, v95, s[12:13]
	v_cmp_gt_f32_e64 s[12:13], v103, v5
	v_addc_co_u32_e64 v94, vcc, 0, v94, s[8:9]
	v_cmp_gt_f32_e64 s[8:9], v103, v6
	v_addc_co_u32_e64 v93, vcc, 0, v93, s[10:11]
	v_cmp_gt_f32_e64 s[10:11], v103, v7
	v_addc_co_u32_e64 v92, vcc, 0, v92, s[12:13]
	v_cmp_gt_f32_e64 s[12:13], v103, v8
	v_addc_co_u32_e64 v91, vcc, 0, v91, s[8:9]
	v_cmp_gt_f32_e64 s[8:9], v103, v9
	v_addc_co_u32_e64 v90, vcc, 0, v90, s[10:11]
	v_cmp_gt_f32_e64 s[10:11], v103, v10
	v_addc_co_u32_e64 v89, vcc, 0, v89, s[12:13]
	v_cmp_gt_f32_e64 s[12:13], v103, v11
	v_addc_co_u32_e64 v88, vcc, 0, v88, s[8:9]
	v_cmp_gt_f32_e64 s[8:9], v103, v12
	v_addc_co_u32_e64 v87, vcc, 0, v87, s[10:11]
	v_cmp_gt_f32_e64 s[10:11], v103, v13
	v_addc_co_u32_e64 v86, vcc, 0, v86, s[12:13]
	v_cmp_gt_f32_e64 s[12:13], v103, v14
	v_addc_co_u32_e64 v85, vcc, 0, v85, s[8:9]
	v_cmp_gt_f32_e64 s[8:9], v103, v15
	v_addc_co_u32_e64 v84, vcc, 0, v84, s[10:11]
	v_cmp_gt_f32_e64 s[10:11], v103, v16
	v_addc_co_u32_e64 v83, vcc, 0, v83, s[12:13]
	v_cmp_gt_f32_e64 s[12:13], v103, v17
	v_addc_co_u32_e64 v81, vcc, 0, v81, s[8:9]
	v_cmp_gt_f32_e64 s[8:9], v103, v18
	v_addc_co_u32_e64 v79, vcc, 0, v79, s[10:11]
	v_cmp_gt_f32_e64 s[10:11], v103, v19
	v_addc_co_u32_e64 v78, vcc, 0, v78, s[12:13]
	v_cmp_gt_f32_e64 s[12:13], v103, v20
	v_addc_co_u32_e64 v77, vcc, 0, v77, s[8:9]
	v_cmp_gt_f32_e64 s[8:9], v103, v21
	v_addc_co_u32_e64 v76, vcc, 0, v76, s[10:11]
	v_cmp_gt_f32_e64 s[10:11], v103, v22
	v_addc_co_u32_e64 v75, vcc, 0, v75, s[12:13]
	v_cmp_gt_f32_e64 s[12:13], v103, v23
	v_addc_co_u32_e64 v74, vcc, 0, v74, s[8:9]
	v_cmp_gt_f32_e64 s[8:9], v103, v24
	v_addc_co_u32_e64 v73, vcc, 0, v73, s[10:11]
	v_cmp_gt_f32_e64 s[10:11], v103, v25
	v_addc_co_u32_e64 v72, vcc, 0, v72, s[12:13]
	v_cmp_gt_f32_e64 s[12:13], v103, v26
	v_addc_co_u32_e64 v71, vcc, 0, v71, s[8:9]
	v_cmp_gt_f32_e64 s[8:9], v103, v27
	v_addc_co_u32_e64 v70, vcc, 0, v70, s[10:11]
	v_cmp_gt_f32_e64 s[10:11], v103, v28
	v_addc_co_u32_e64 v69, vcc, 0, v69, s[12:13]
	v_cmp_gt_f32_e64 s[12:13], v103, v29
	v_addc_co_u32_e64 v68, vcc, 0, v68, s[8:9]
	v_cmp_gt_f32_e64 s[8:9], v103, v30
	v_addc_co_u32_e64 v67, vcc, 0, v67, s[10:11]
	v_cmp_gt_f32_e64 s[10:11], v103, v31
	v_addc_co_u32_e64 v66, vcc, 0, v66, s[12:13]
	s_nop 0
	v_addc_co_u32_e64 v65, vcc, 0, v65, s[8:9]
	v_addc_co_u32_e64 v64, vcc, 0, v64, s[10:11]
.Lrk_done:
	s_waitcnt lgkmcnt(0)
	s_branch .LBB0_921
